# GEMM mainloop: static s_setprio 1 for the wave in hardware slot 1 of each SIMD (co-resident block), reset after the mainloop
# speedup vs baseline: 1.0152x; 1.0047x over previous
.LBB0_150:
	s_ashr_i32 s4, s35, 31
	s_lshr_b32 s4, s4, 26
	s_add_i32 s4, s35, s4
	s_ashr_i32 s6, s4, 6
	s_and_b32 s4, s4, 0x3ffffc0
	s_sub_i32 s4, s35, s4
	s_mulk_i32 s4, 0xc0
	v_add_u32_e32 v2, s4, v1
	s_lshr_b32 s7, s4, 6
	s_lshl_b32 s5, s6, 7
	v_ashrrev_i32_e32 v3, 31, v2
	s_add_i32 s7, s7, s6
	v_lshlrev_b64 v[2:3], 11, v[2:3]
	v_or_b32_e32 v4, s5, v1
	s_lshl_b32 s6, s7, 6
	s_lshl_b32 s7, s7, 7
	v_ashrrev_i32_e32 v5, 31, v4
	v_lshl_add_u64 v[104:105], v[100:101], 0, v[2:3]
	s_and_b32 s14, s7, 0x780
	v_readfirstlane_b32 s7, v112
	v_lshlrev_b64 v[4:5], 11, v[4:5]
	v_lshl_add_u64 v[2:3], v[104:105], 0, s[14:15]
	s_mov_b32 m0, s7
	v_readfirstlane_b32 s7, v124
	v_lshl_add_u64 v[106:107], v[102:103], 0, v[4:5]
	s_getreg_b32 s83, hwreg(HW_REG_HW_ID, 0, 4)
	s_bitcmp1_b32 s83, 0
	s_cbranch_scc0 .Lgm_ph2_noprio
	s_setprio 1
.Lgm_ph2_noprio:
	s_waitcnt vmcnt(0)
	s_barrier
	s_load_dwordx2 s[66:67], s[0:1], 0x90
	s_load_dwordx2 s[68:69], s[0:1], 0xc0
	v_and_b32_e32 v201, 0x3ff, v0
	v_readfirstlane_b32 s80, v0
	v_and_b32_e32 v200, 31, v201
	v_bfe_u32 v214, v201, 1, 3
	v_bfe_u32 v213, v201, 5, 1
	v_xor_b32_e32 v214, v214, v213
	v_lshlrev_b32_e32 v214, 4, v214
	s_and_b32 s80, s80, 0x3ff
	s_lshr_b32 s83, s80, 6
	s_lshl_b32 s80, s80, 4
	s_lshr_b32 s84, s83, 1
	s_and_b32 s83, s83, 1
	s_mul_i32 s84, s84, 0x3000
	s_lshl_b32 s83, s83, 13
	s_add_u32 s83, s83, 0xc000
	v_lshlrev_b32_e32 v200, 7, v200
	v_or_b32_e32 v200, v200, v214
	v_add_u32_e32 v215, s84, v200
	v_add_u32_e32 v211, s83, v200
	v_xor_b32_e32 v214, 0x20, v215
	v_xor_b32_e32 v210, 0x20, v211
	v_xor_b32_e32 v213, 0x40, v215
	v_xor_b32_e32 v209, 0x40, v211
	v_xor_b32_e32 v212, 0x60, v215
	v_xor_b32_e32 v208, 0x60, v211
	v_bfe_u32 v200, v201, 4, 3
	v_and_b32_e32 v206, 7, v201
	v_xor_b32_e32 v200, v200, v206
	v_lshlrev_b32_e32 v200, 4, v200
	v_lshrrev_b32_e32 v206, 3, v201
	v_lshl_or_b32 v207, v206, 11, v200
	v_add_u32_e32 v206, 0x10000, v207
	v_add_u32_e32 v205, 0x20000, v207
	v_add_u32_e32 v204, 0x30000, v207
	v_add_u32_e32 v203, 0x40000, v207
	v_add_u32_e32 v202, 0x50000, v207
	s_lshr_b32 s83, s35, 6
	s_and_b32 s84, s35, 63
	s_mov_b32 s79, 0
	s_mul_i32 s84, s84, 0x60000
	s_lshl_b32 s83, s83, 18
	s_waitcnt lgkmcnt(0)
	s_add_u32 s66, s66, s84
	s_addc_u32 s67, s67, 0
	s_add_u32 s68, s68, s83
	s_addc_u32 s69, s69, 0
	s_add_u32 s83, s79, 0
	s_and_b32 s83, s83, 15
	s_lshl_b32 s83, s83, 7
	s_add_u32 s70, s66, s83
	s_addc_u32 s71, s67, 0
	s_add_u32 s72, s68, s83
	s_addc_u32 s73, s69, 0
	s_add_u32 s81, s80, 0x0
	s_add_u32 s82, s80, 0xc000
	s_add_u32 m0, s81, 0x0
	s_nop 0
	global_load_lds_dwordx4 v207, s[70:71]
	s_add_u32 m0, s81, 0x1000
	s_nop 0
	global_load_lds_dwordx4 v206, s[70:71]
	s_add_u32 m0, s81, 0x2000
	s_nop 0
	global_load_lds_dwordx4 v205, s[70:71]
	s_add_u32 m0, s81, 0x3000
	s_nop 0
	global_load_lds_dwordx4 v204, s[70:71]
	s_add_u32 m0, s81, 0x4000
	s_nop 0
	global_load_lds_dwordx4 v203, s[70:71]
	s_add_u32 m0, s81, 0x5000
	s_nop 0
	global_load_lds_dwordx4 v202, s[70:71]
	s_add_u32 m0, s82, 0x0
	s_nop 0
	global_load_lds_dwordx4 v207, s[72:73]
	s_add_u32 m0, s82, 0x1000
	s_nop 0
	global_load_lds_dwordx4 v206, s[72:73]
	s_add_u32 m0, s82, 0x2000
	s_nop 0
	global_load_lds_dwordx4 v205, s[72:73]
	s_add_u32 m0, s82, 0x3000
	s_nop 0
	global_load_lds_dwordx4 v204, s[72:73]
	s_add_u32 s83, s79, 1
	s_and_b32 s83, s83, 15
	s_lshl_b32 s83, s83, 7
	s_add_u32 s70, s66, s83
	s_addc_u32 s71, s67, 0
	s_add_u32 s72, s68, s83
	s_addc_u32 s73, s69, 0
	s_add_u32 s81, s80, 0x6000
	s_add_u32 s82, s80, 0x10000
	s_add_u32 m0, s81, 0x0
	s_nop 0
	global_load_lds_dwordx4 v207, s[70:71]
	s_add_u32 m0, s81, 0x1000
	s_nop 0
	global_load_lds_dwordx4 v206, s[70:71]
	s_add_u32 m0, s81, 0x2000
	s_nop 0
	global_load_lds_dwordx4 v205, s[70:71]
	s_add_u32 m0, s81, 0x3000
	s_nop 0
	global_load_lds_dwordx4 v204, s[70:71]
	s_add_u32 m0, s81, 0x4000
	s_nop 0
	global_load_lds_dwordx4 v203, s[70:71]
	v_mov_b32_e32 v2, 0
	v_mov_b32_e32 v3, 0
	v_mov_b32_e32 v4, 0
	v_mov_b32_e32 v5, 0
	v_mov_b32_e32 v6, 0
	v_mov_b32_e32 v7, 0
	v_mov_b32_e32 v8, 0
	v_mov_b32_e32 v9, 0
	v_mov_b32_e32 v10, 0
	v_mov_b32_e32 v11, 0
	v_mov_b32_e32 v12, 0
	v_mov_b32_e32 v13, 0
	v_mov_b32_e32 v14, 0
	v_mov_b32_e32 v15, 0
	v_mov_b32_e32 v16, 0
	v_mov_b32_e32 v17, 0
	v_mov_b32_e32 v18, 0
	v_mov_b32_e32 v19, 0
	v_mov_b32_e32 v20, 0
	v_mov_b32_e32 v21, 0
	v_mov_b32_e32 v22, 0
	v_mov_b32_e32 v23, 0
	v_mov_b32_e32 v24, 0
	v_mov_b32_e32 v25, 0
	v_mov_b32_e32 v26, 0
	v_mov_b32_e32 v27, 0
	v_mov_b32_e32 v28, 0
	v_mov_b32_e32 v29, 0
	v_mov_b32_e32 v30, 0
	v_mov_b32_e32 v31, 0
	v_mov_b32_e32 v32, 0
	v_mov_b32_e32 v33, 0
	v_mov_b32_e32 v34, 0
	v_mov_b32_e32 v35, 0
	v_mov_b32_e32 v36, 0
	v_mov_b32_e32 v37, 0
	v_mov_b32_e32 v38, 0
	v_mov_b32_e32 v39, 0
	v_mov_b32_e32 v40, 0
	v_mov_b32_e32 v41, 0
	v_mov_b32_e32 v42, 0
	v_mov_b32_e32 v43, 0
	v_mov_b32_e32 v44, 0
	v_mov_b32_e32 v45, 0
	v_mov_b32_e32 v46, 0
	v_mov_b32_e32 v47, 0
	v_mov_b32_e32 v48, 0
	v_mov_b32_e32 v49, 0
	v_mov_b32_e32 v50, 0
	v_mov_b32_e32 v51, 0
	v_mov_b32_e32 v52, 0
	v_mov_b32_e32 v53, 0
	v_mov_b32_e32 v54, 0
	v_mov_b32_e32 v55, 0
	v_mov_b32_e32 v56, 0
	v_mov_b32_e32 v57, 0
	v_mov_b32_e32 v58, 0
	v_mov_b32_e32 v59, 0
	v_mov_b32_e32 v60, 0
	v_mov_b32_e32 v61, 0
	v_mov_b32_e32 v62, 0
	v_mov_b32_e32 v63, 0
	v_mov_b32_e32 v64, 0
	v_mov_b32_e32 v65, 0
	v_mov_b32_e32 v66, 0
	v_mov_b32_e32 v67, 0
	v_mov_b32_e32 v68, 0
	v_mov_b32_e32 v69, 0
	v_mov_b32_e32 v70, 0
	v_mov_b32_e32 v71, 0
	v_mov_b32_e32 v72, 0
	v_mov_b32_e32 v73, 0
	v_mov_b32_e32 v74, 0
	v_mov_b32_e32 v75, 0
	v_mov_b32_e32 v76, 0
	v_mov_b32_e32 v77, 0
	v_mov_b32_e32 v78, 0
	v_mov_b32_e32 v79, 0
	v_mov_b32_e32 v80, 0
	v_mov_b32_e32 v81, 0
	v_mov_b32_e32 v82, 0
	v_mov_b32_e32 v83, 0
	v_mov_b32_e32 v84, 0
	v_mov_b32_e32 v85, 0
	v_mov_b32_e32 v86, 0
	v_mov_b32_e32 v87, 0
	v_mov_b32_e32 v88, 0
	v_mov_b32_e32 v89, 0
	v_mov_b32_e32 v90, 0
	v_mov_b32_e32 v91, 0
	v_mov_b32_e32 v92, 0
	v_mov_b32_e32 v93, 0
	v_mov_b32_e32 v94, 0
	v_mov_b32_e32 v95, 0
	v_mov_b32_e32 v96, 0
	v_mov_b32_e32 v97, 0
	s_waitcnt vmcnt(5)
	s_barrier
	ds_read_b128 v[240:243], v211 offset:0
	ds_read_b128 v[252:255], v215 offset:0
	ds_read_b128 v[236:239], v211 offset:4096
	ds_read_b128 v[248:251], v215 offset:4096
	ds_read_b128 v[244:247], v215 offset:8192
	s_mov_b32 s78, 0
.Lgm_ph2_loop:
	s_waitcnt lgkmcnt(1)
	v_mfma_f32_32x32x16_bf16 v[82:97], v[240:243], v[252:255], v[82:97]
	ds_read_b128 v[220:223], v210 offset:0
	s_add_u32 m0, s81, 0x5000
	s_nop 0
	global_load_lds_dwordx4 v202, s[70:71]
	v_mfma_f32_32x32x16_bf16 v[66:81], v[236:239], v[252:255], v[66:81]
	ds_read_b128 v[232:235], v214 offset:0
	s_add_u32 m0, s82, 0x0
	s_nop 0
	global_load_lds_dwordx4 v207, s[72:73]
	v_mfma_f32_32x32x16_bf16 v[50:65], v[240:243], v[248:251], v[50:65]
	ds_read_b128 v[216:219], v210 offset:4096
	s_add_u32 m0, s82, 0x1000
	s_nop 0
	global_load_lds_dwordx4 v206, s[72:73]
	v_mfma_f32_32x32x16_bf16 v[34:49], v[236:239], v[248:251], v[34:49]
	ds_read_b128 v[228:231], v214 offset:4096
	s_add_u32 m0, s82, 0x2000
	s_nop 0
	global_load_lds_dwordx4 v205, s[72:73]
	s_waitcnt lgkmcnt(4)
	v_mfma_f32_32x32x16_bf16 v[18:33], v[240:243], v[244:247], v[18:33]
	ds_read_b128 v[224:227], v214 offset:8192
	v_mfma_f32_32x32x16_bf16 v[2:17], v[236:239], v[244:247], v[2:17]
	s_add_u32 m0, s82, 0x3000
	s_nop 0
	global_load_lds_dwordx4 v204, s[72:73]
	s_waitcnt lgkmcnt(1)
	v_mfma_f32_32x32x16_bf16 v[82:97], v[220:223], v[232:235], v[82:97]
	ds_read_b128 v[240:243], v209 offset:0
	v_mfma_f32_32x32x16_bf16 v[66:81], v[216:219], v[232:235], v[66:81]
	ds_read_b128 v[252:255], v213 offset:0
	v_mfma_f32_32x32x16_bf16 v[50:65], v[220:223], v[228:231], v[50:65]
	ds_read_b128 v[236:239], v209 offset:4096
	v_mfma_f32_32x32x16_bf16 v[34:49], v[216:219], v[228:231], v[34:49]
	ds_read_b128 v[248:251], v213 offset:4096
	s_waitcnt lgkmcnt(4)
	v_mfma_f32_32x32x16_bf16 v[18:33], v[220:223], v[224:227], v[18:33]
	ds_read_b128 v[244:247], v213 offset:8192
	v_mfma_f32_32x32x16_bf16 v[2:17], v[216:219], v[224:227], v[2:17]
	s_waitcnt lgkmcnt(1)
	v_mfma_f32_32x32x16_bf16 v[82:97], v[240:243], v[252:255], v[82:97]
	ds_read_b128 v[220:223], v208 offset:0
	s_add_u32 s83, s79, s78
	s_add_u32 s83, s83, 2
	s_and_b32 s83, s83, 15
	v_mfma_f32_32x32x16_bf16 v[66:81], v[236:239], v[252:255], v[66:81]
	ds_read_b128 v[232:235], v212 offset:0
	s_lshl_b32 s83, s83, 7
	s_add_u32 s70, s66, s83
	v_mfma_f32_32x32x16_bf16 v[50:65], v[240:243], v[248:251], v[50:65]
	ds_read_b128 v[216:219], v208 offset:4096
	s_addc_u32 s71, s67, 0
	s_add_u32 s72, s68, s83
	v_mfma_f32_32x32x16_bf16 v[34:49], v[236:239], v[248:251], v[34:49]
	ds_read_b128 v[228:231], v212 offset:4096
	s_addc_u32 s73, s69, 0
	s_add_u32 s81, s80, 0x0
	s_add_u32 s82, s80, 0xc000
	s_waitcnt lgkmcnt(4)
	v_mfma_f32_32x32x16_bf16 v[18:33], v[240:243], v[244:247], v[18:33]
	ds_read_b128 v[224:227], v212 offset:8192
	v_mfma_f32_32x32x16_bf16 v[2:17], v[236:239], v[244:247], v[2:17]
	s_waitcnt vmcnt(0) lgkmcnt(0)
	s_barrier
	v_mfma_f32_32x32x16_bf16 v[82:97], v[220:223], v[232:235], v[82:97]
	s_add_u32 m0, s81, 0x0
	ds_read_b128 v[240:243], v211 offset:16384
	global_load_lds_dwordx4 v207, s[70:71]
	v_mfma_f32_32x32x16_bf16 v[66:81], v[216:219], v[232:235], v[66:81]
	s_add_u32 m0, s81, 0x1000
	ds_read_b128 v[252:255], v215 offset:24576
	global_load_lds_dwordx4 v206, s[70:71]
	v_mfma_f32_32x32x16_bf16 v[50:65], v[220:223], v[228:231], v[50:65]
	s_add_u32 m0, s81, 0x2000
	ds_read_b128 v[236:239], v211 offset:20480
	global_load_lds_dwordx4 v205, s[70:71]
	v_mfma_f32_32x32x16_bf16 v[34:49], v[216:219], v[228:231], v[34:49]
	s_add_u32 m0, s81, 0x3000
	ds_read_b128 v[248:251], v215 offset:28672
	global_load_lds_dwordx4 v204, s[70:71]
	v_mfma_f32_32x32x16_bf16 v[18:33], v[220:223], v[224:227], v[18:33]
	s_add_u32 m0, s81, 0x4000
	ds_read_b128 v[244:247], v215 offset:32768
	global_load_lds_dwordx4 v203, s[70:71]
	v_mfma_f32_32x32x16_bf16 v[2:17], v[216:219], v[224:227], v[2:17]
	s_waitcnt lgkmcnt(1)
	v_mfma_f32_32x32x16_bf16 v[82:97], v[240:243], v[252:255], v[82:97]
	ds_read_b128 v[220:223], v210 offset:16384
	s_add_u32 m0, s81, 0x5000
	s_nop 0
	global_load_lds_dwordx4 v202, s[70:71]
	v_mfma_f32_32x32x16_bf16 v[66:81], v[236:239], v[252:255], v[66:81]
	ds_read_b128 v[232:235], v214 offset:24576
	s_add_u32 m0, s82, 0x0
	s_nop 0
	global_load_lds_dwordx4 v207, s[72:73]
	v_mfma_f32_32x32x16_bf16 v[50:65], v[240:243], v[248:251], v[50:65]
	ds_read_b128 v[216:219], v210 offset:20480
	s_add_u32 m0, s82, 0x1000
	s_nop 0
	global_load_lds_dwordx4 v206, s[72:73]
	v_mfma_f32_32x32x16_bf16 v[34:49], v[236:239], v[248:251], v[34:49]
	ds_read_b128 v[228:231], v214 offset:28672
	s_add_u32 m0, s82, 0x2000
	s_nop 0
	global_load_lds_dwordx4 v205, s[72:73]
	s_waitcnt lgkmcnt(4)
	v_mfma_f32_32x32x16_bf16 v[18:33], v[240:243], v[244:247], v[18:33]
	ds_read_b128 v[224:227], v214 offset:32768
	v_mfma_f32_32x32x16_bf16 v[2:17], v[236:239], v[244:247], v[2:17]
	s_add_u32 m0, s82, 0x3000
	s_nop 0
	global_load_lds_dwordx4 v204, s[72:73]
	s_waitcnt lgkmcnt(1)
	v_mfma_f32_32x32x16_bf16 v[82:97], v[220:223], v[232:235], v[82:97]
	ds_read_b128 v[240:243], v209 offset:16384
	v_mfma_f32_32x32x16_bf16 v[66:81], v[216:219], v[232:235], v[66:81]
	ds_read_b128 v[252:255], v213 offset:24576
	v_mfma_f32_32x32x16_bf16 v[50:65], v[220:223], v[228:231], v[50:65]
	ds_read_b128 v[236:239], v209 offset:20480
	v_mfma_f32_32x32x16_bf16 v[34:49], v[216:219], v[228:231], v[34:49]
	ds_read_b128 v[248:251], v213 offset:28672
	s_waitcnt lgkmcnt(4)
	v_mfma_f32_32x32x16_bf16 v[18:33], v[220:223], v[224:227], v[18:33]
	ds_read_b128 v[244:247], v213 offset:32768
	v_mfma_f32_32x32x16_bf16 v[2:17], v[216:219], v[224:227], v[2:17]
	s_waitcnt lgkmcnt(1)
	v_mfma_f32_32x32x16_bf16 v[82:97], v[240:243], v[252:255], v[82:97]
	ds_read_b128 v[220:223], v208 offset:16384
	s_add_u32 s83, s79, s78
	s_add_u32 s83, s83, 3
	s_and_b32 s83, s83, 15
	v_mfma_f32_32x32x16_bf16 v[66:81], v[236:239], v[252:255], v[66:81]
	ds_read_b128 v[232:235], v212 offset:24576
	s_lshl_b32 s83, s83, 7
	s_add_u32 s70, s66, s83
	v_mfma_f32_32x32x16_bf16 v[50:65], v[240:243], v[248:251], v[50:65]
	ds_read_b128 v[216:219], v208 offset:20480
	s_addc_u32 s71, s67, 0
	s_add_u32 s72, s68, s83
	v_mfma_f32_32x32x16_bf16 v[34:49], v[236:239], v[248:251], v[34:49]
	ds_read_b128 v[228:231], v212 offset:28672
	s_addc_u32 s73, s69, 0
	s_add_u32 s81, s80, 0x6000
	s_add_u32 s82, s80, 0x10000
	s_waitcnt lgkmcnt(4)
	v_mfma_f32_32x32x16_bf16 v[18:33], v[240:243], v[244:247], v[18:33]
	ds_read_b128 v[224:227], v212 offset:32768
	v_mfma_f32_32x32x16_bf16 v[2:17], v[236:239], v[244:247], v[2:17]
	s_waitcnt vmcnt(0) lgkmcnt(0)
	s_barrier
	v_mfma_f32_32x32x16_bf16 v[82:97], v[220:223], v[232:235], v[82:97]
	s_add_u32 m0, s81, 0x0
	ds_read_b128 v[240:243], v211 offset:0
	global_load_lds_dwordx4 v207, s[70:71]
	v_mfma_f32_32x32x16_bf16 v[66:81], v[216:219], v[232:235], v[66:81]
	s_add_u32 m0, s81, 0x1000
	ds_read_b128 v[252:255], v215 offset:0
	global_load_lds_dwordx4 v206, s[70:71]
	v_mfma_f32_32x32x16_bf16 v[50:65], v[220:223], v[228:231], v[50:65]
	s_add_u32 m0, s81, 0x2000
	ds_read_b128 v[236:239], v211 offset:4096
	global_load_lds_dwordx4 v205, s[70:71]
	v_mfma_f32_32x32x16_bf16 v[34:49], v[216:219], v[228:231], v[34:49]
	s_add_u32 m0, s81, 0x3000
	ds_read_b128 v[248:251], v215 offset:4096
	global_load_lds_dwordx4 v204, s[70:71]
	v_mfma_f32_32x32x16_bf16 v[18:33], v[220:223], v[224:227], v[18:33]
	s_add_u32 m0, s81, 0x4000
	ds_read_b128 v[244:247], v215 offset:8192
	global_load_lds_dwordx4 v203, s[70:71]
	v_mfma_f32_32x32x16_bf16 v[2:17], v[216:219], v[224:227], v[2:17]
	s_add_u32 s78, s78, 2
	s_cmp_lt_u32 s78, 14
	s_cbranch_scc1 .Lgm_ph2_loop
	s_waitcnt lgkmcnt(1)
	v_mfma_f32_32x32x16_bf16 v[82:97], v[240:243], v[252:255], v[82:97]
	ds_read_b128 v[220:223], v210 offset:0
	s_add_u32 m0, s81, 0x5000
	s_nop 0
	global_load_lds_dwordx4 v202, s[70:71]
	v_mfma_f32_32x32x16_bf16 v[66:81], v[236:239], v[252:255], v[66:81]
	ds_read_b128 v[232:235], v214 offset:0
	s_add_u32 m0, s82, 0x0
	s_nop 0
	global_load_lds_dwordx4 v207, s[72:73]
	v_mfma_f32_32x32x16_bf16 v[50:65], v[240:243], v[248:251], v[50:65]
	ds_read_b128 v[216:219], v210 offset:4096
	s_add_u32 m0, s82, 0x1000
	s_nop 0
	global_load_lds_dwordx4 v206, s[72:73]
	v_mfma_f32_32x32x16_bf16 v[34:49], v[236:239], v[248:251], v[34:49]
	ds_read_b128 v[228:231], v214 offset:4096
	s_add_u32 m0, s82, 0x2000
	s_nop 0
	global_load_lds_dwordx4 v205, s[72:73]
	s_waitcnt lgkmcnt(4)
	v_mfma_f32_32x32x16_bf16 v[18:33], v[240:243], v[244:247], v[18:33]
	ds_read_b128 v[224:227], v214 offset:8192
	v_mfma_f32_32x32x16_bf16 v[2:17], v[236:239], v[244:247], v[2:17]
	s_add_u32 m0, s82, 0x3000
	s_nop 0
	global_load_lds_dwordx4 v204, s[72:73]
	s_waitcnt lgkmcnt(1)
	v_mfma_f32_32x32x16_bf16 v[82:97], v[220:223], v[232:235], v[82:97]
	ds_read_b128 v[240:243], v209 offset:0
	v_mfma_f32_32x32x16_bf16 v[66:81], v[216:219], v[232:235], v[66:81]
	ds_read_b128 v[252:255], v213 offset:0
	v_mfma_f32_32x32x16_bf16 v[50:65], v[220:223], v[228:231], v[50:65]
	ds_read_b128 v[236:239], v209 offset:4096
	v_mfma_f32_32x32x16_bf16 v[34:49], v[216:219], v[228:231], v[34:49]
	ds_read_b128 v[248:251], v213 offset:4096
	s_waitcnt lgkmcnt(4)
	v_mfma_f32_32x32x16_bf16 v[18:33], v[220:223], v[224:227], v[18:33]
	ds_read_b128 v[244:247], v213 offset:8192
	v_mfma_f32_32x32x16_bf16 v[2:17], v[216:219], v[224:227], v[2:17]
	s_waitcnt lgkmcnt(1)
	v_mfma_f32_32x32x16_bf16 v[82:97], v[240:243], v[252:255], v[82:97]
	ds_read_b128 v[220:223], v208 offset:0
	v_mfma_f32_32x32x16_bf16 v[66:81], v[236:239], v[252:255], v[66:81]
	ds_read_b128 v[232:235], v212 offset:0
	v_mfma_f32_32x32x16_bf16 v[50:65], v[240:243], v[248:251], v[50:65]
	ds_read_b128 v[216:219], v208 offset:4096
	v_mfma_f32_32x32x16_bf16 v[34:49], v[236:239], v[248:251], v[34:49]
	ds_read_b128 v[228:231], v212 offset:4096
	s_waitcnt lgkmcnt(4)
	v_mfma_f32_32x32x16_bf16 v[18:33], v[240:243], v[244:247], v[18:33]
	ds_read_b128 v[224:227], v212 offset:8192
	v_mfma_f32_32x32x16_bf16 v[2:17], v[236:239], v[244:247], v[2:17]
	s_waitcnt vmcnt(0) lgkmcnt(0)
	s_barrier
	v_mfma_f32_32x32x16_bf16 v[82:97], v[220:223], v[232:235], v[82:97]
	ds_read_b128 v[240:243], v211 offset:16384
	v_mfma_f32_32x32x16_bf16 v[66:81], v[216:219], v[232:235], v[66:81]
	ds_read_b128 v[252:255], v215 offset:24576
	v_mfma_f32_32x32x16_bf16 v[50:65], v[220:223], v[228:231], v[50:65]
	ds_read_b128 v[236:239], v211 offset:20480
	v_mfma_f32_32x32x16_bf16 v[34:49], v[216:219], v[228:231], v[34:49]
	ds_read_b128 v[248:251], v215 offset:28672
	v_mfma_f32_32x32x16_bf16 v[18:33], v[220:223], v[224:227], v[18:33]
	ds_read_b128 v[244:247], v215 offset:32768
	v_mfma_f32_32x32x16_bf16 v[2:17], v[216:219], v[224:227], v[2:17]
	s_waitcnt lgkmcnt(1)
	v_mfma_f32_32x32x16_bf16 v[82:97], v[240:243], v[252:255], v[82:97]
	ds_read_b128 v[220:223], v210 offset:16384
	v_mfma_f32_32x32x16_bf16 v[66:81], v[236:239], v[252:255], v[66:81]
	ds_read_b128 v[232:235], v214 offset:24576
	v_mfma_f32_32x32x16_bf16 v[50:65], v[240:243], v[248:251], v[50:65]
	ds_read_b128 v[216:219], v210 offset:20480
	v_mfma_f32_32x32x16_bf16 v[34:49], v[236:239], v[248:251], v[34:49]
	ds_read_b128 v[228:231], v214 offset:28672
	s_waitcnt lgkmcnt(4)
	v_mfma_f32_32x32x16_bf16 v[18:33], v[240:243], v[244:247], v[18:33]
	ds_read_b128 v[224:227], v214 offset:32768
	v_mfma_f32_32x32x16_bf16 v[2:17], v[236:239], v[244:247], v[2:17]
	s_waitcnt lgkmcnt(1)
	v_mfma_f32_32x32x16_bf16 v[82:97], v[220:223], v[232:235], v[82:97]
	ds_read_b128 v[240:243], v209 offset:16384
	v_mfma_f32_32x32x16_bf16 v[66:81], v[216:219], v[232:235], v[66:81]
	ds_read_b128 v[252:255], v213 offset:24576
	v_mfma_f32_32x32x16_bf16 v[50:65], v[220:223], v[228:231], v[50:65]
	ds_read_b128 v[236:239], v209 offset:20480
	v_mfma_f32_32x32x16_bf16 v[34:49], v[216:219], v[228:231], v[34:49]
	ds_read_b128 v[248:251], v213 offset:28672
	s_waitcnt lgkmcnt(4)
	v_mfma_f32_32x32x16_bf16 v[18:33], v[220:223], v[224:227], v[18:33]
	ds_read_b128 v[244:247], v213 offset:32768
	v_mfma_f32_32x32x16_bf16 v[2:17], v[216:219], v[224:227], v[2:17]
	s_waitcnt lgkmcnt(1)
	v_mfma_f32_32x32x16_bf16 v[82:97], v[240:243], v[252:255], v[82:97]
	ds_read_b128 v[220:223], v208 offset:16384
	v_mfma_f32_32x32x16_bf16 v[66:81], v[236:239], v[252:255], v[66:81]
	ds_read_b128 v[232:235], v212 offset:24576
	v_mfma_f32_32x32x16_bf16 v[50:65], v[240:243], v[248:251], v[50:65]
	ds_read_b128 v[216:219], v208 offset:20480
	v_mfma_f32_32x32x16_bf16 v[34:49], v[236:239], v[248:251], v[34:49]
	ds_read_b128 v[228:231], v212 offset:28672
	s_waitcnt lgkmcnt(4)
	v_mfma_f32_32x32x16_bf16 v[18:33], v[240:243], v[244:247], v[18:33]
	ds_read_b128 v[224:227], v212 offset:32768
	v_mfma_f32_32x32x16_bf16 v[2:17], v[236:239], v[244:247], v[2:17]
	s_waitcnt vmcnt(0) lgkmcnt(0)
	s_barrier
	v_mfma_f32_32x32x16_bf16 v[82:97], v[220:223], v[232:235], v[82:97]
	v_mfma_f32_32x32x16_bf16 v[66:81], v[216:219], v[232:235], v[66:81]
	v_mfma_f32_32x32x16_bf16 v[50:65], v[220:223], v[228:231], v[50:65]
	v_mfma_f32_32x32x16_bf16 v[34:49], v[216:219], v[228:231], v[34:49]
	v_mfma_f32_32x32x16_bf16 v[18:33], v[220:223], v[224:227], v[18:33]
	v_mfma_f32_32x32x16_bf16 v[2:17], v[216:219], v[224:227], v[2:17]
	s_nop 7
	s_nop 7
	s_setprio 0
	v_add_u32_e32 v147, v115, v118
	s_nop 4
	v_add_u32_e32 v98, v117, v121
	s_nop 4
	s_waitcnt lgkmcnt(0)
	v_or_b32_e32 v142, s5, v122
	v_cmp_lt_i32_e64 s[6:7], s3, v142
	v_add_u32_e32 v106, s4, v114
	v_ashrrev_i32_e32 v107, 31, v106
	v_lshlrev_b64 v[110:111], 11, v[106:107]
	v_or_b32_e32 v104, v142, v123
	v_lshl_add_u64 v[108:109], s[10:11], 0, v[110:111]
	s_and_saveexec_b64 s[4:5], s[6:7]
	s_xor_b64 s[4:5], exec, s[4:5]
	s_cbranch_execz .LBB0_154
	v_mul_f32_e32 v98, 0xbfb8aa3b, v82
	v_exp_f32_e32 v144, v98
	v_mul_f32_e32 v98, 0xbfb8aa3b, v83
	v_exp_f32_e32 v145, v98
	s_nop 0
	v_pk_add_f32 v[144:145], v[144:145], 1.0 op_sel_hi:[1,0]
	s_nop 0
	v_div_scale_f32 v98, s[30:31], v145, v145, v83
	v_rcp_f32_e32 v105, v98
	v_div_scale_f32 v107, vcc, v83, v145, v83
	v_fma_f32 v143, -v98, v105, 1.0
	v_fmac_f32_e32 v105, v143, v105
	v_mul_f32_e32 v143, v107, v105
	v_fma_f32 v147, -v98, v143, v107
	v_fmac_f32_e32 v143, v147, v105
	v_fma_f32 v98, -v98, v143, v107
	v_div_scale_f32 v107, s[30:31], v144, v144, v82
	v_rcp_f32_e32 v147, v107
	v_div_fmas_f32 v98, v98, v105, v143
	v_div_fixup_f32 v98, v98, v145, v83
	v_mul_f32_e32 v145, 0xbfb8aa3b, v84
	v_exp_f32_e32 v150, v145
	v_mul_f32_e32 v145, 0xbfb8aa3b, v85
	v_fma_f32 v105, -v107, v147, 1.0
	v_exp_f32_e32 v151, v145
	v_fmac_f32_e32 v147, v105, v147
	v_div_scale_f32 v105, vcc, v82, v144, v82
	v_mul_f32_e32 v143, v105, v147
	v_fma_f32 v145, -v107, v143, v105
	v_fmac_f32_e32 v143, v145, v147
	v_pk_add_f32 v[150:151], v[150:151], 1.0 op_sel_hi:[1,0]
	v_fma_f32 v105, -v107, v143, v105
	v_div_scale_f32 v107, s[30:31], v151, v151, v85
	v_rcp_f32_e32 v145, v107
	v_div_fmas_f32 v105, v105, v147, v143
	v_div_fixup_f32 v105, v105, v144, v82
	v_cvt_pk_bf16_f32 v144, v105, v98
	v_fma_f32 v98, -v107, v145, 1.0
	v_fmac_f32_e32 v145, v98, v145
	v_div_scale_f32 v98, vcc, v85, v151, v85
	v_mul_f32_e32 v105, v98, v145
	v_fma_f32 v143, -v107, v105, v98
	v_fmac_f32_e32 v105, v143, v145
	v_fma_f32 v98, -v107, v105, v98
	v_div_scale_f32 v107, s[30:31], v150, v150, v84
	v_rcp_f32_e32 v143, v107
	v_div_fmas_f32 v98, v98, v145, v105
	v_div_fixup_f32 v98, v98, v151, v85
	v_fma_f32 v105, -v107, v143, 1.0
	v_fmac_f32_e32 v143, v105, v143
	v_div_scale_f32 v105, vcc, v84, v150, v84
	v_mul_f32_e32 v145, v105, v143
	v_fma_f32 v147, -v107, v145, v105
	v_fmac_f32_e32 v145, v147, v143
	v_fma_f32 v105, -v107, v145, v105
	v_div_fmas_f32 v105, v105, v143, v145
	v_div_fixup_f32 v105, v105, v150, v84
	v_cvt_pk_bf16_f32 v145, v105, v98
	v_mov_b32_e32 v105, v99
	v_lshl_add_u64 v[150:151], v[104:105], 1, v[108:109]
	global_store_dwordx2 v[150:151], v[144:145], off offset:-2048

.LBB0_489:
	s_ashr_i32 s10, s28, 31
	s_lshr_b32 s10, s10, 26
	s_add_i32 s10, s28, s10
	s_ashr_i32 s31, s10, 6
	s_and_b32 s10, s10, 0x3ffffc0
	s_sub_i32 s29, s28, s10
	s_mulk_i32 s29, 0xc0
	v_add_u32_e32 v2, s29, v108
	s_lshr_b32 s10, s29, 6
	s_lshl_b32 s30, s31, 7
	v_ashrrev_i32_e32 v3, 31, v2
	s_add_i32 s10, s10, s31
	v_lshlrev_b64 v[2:3], 11, v[2:3]
	v_or_b32_e32 v4, s30, v108
	s_lshl_b32 s31, s10, 6
	s_lshl_b32 s10, s10, 7
	v_ashrrev_i32_e32 v5, 31, v4
	v_lshl_add_u64 v[104:105], v[100:101], 0, v[2:3]
	s_and_b32 s10, s10, 0x780
	v_readfirstlane_b32 s34, v109
	v_lshlrev_b64 v[4:5], 11, v[4:5]
	v_lshl_add_u64 v[2:3], v[104:105], 0, s[10:11]
	s_mov_b32 m0, s34
	v_readfirstlane_b32 s34, v128
	v_lshl_add_u64 v[106:107], v[102:103], 0, v[4:5]
	s_getreg_b32 s83, hwreg(HW_REG_HW_ID, 0, 4)
	s_bitcmp1_b32 s83, 0
	s_cbranch_scc0 .Lgm_ph5_noprio
	s_setprio 1
.Lgm_ph5_noprio:
	s_waitcnt vmcnt(0)
	s_barrier
	s_load_dwordx2 s[66:67], s[0:1], 0x118
	s_load_dwordx2 s[68:69], s[0:1], 0xd0
	v_and_b32_e32 v201, 0x3ff, v0
	v_readfirstlane_b32 s80, v0
	v_and_b32_e32 v200, 31, v201
	v_bfe_u32 v214, v201, 1, 3
	v_bfe_u32 v213, v201, 5, 1
	v_xor_b32_e32 v214, v214, v213
	v_lshlrev_b32_e32 v214, 4, v214
	s_and_b32 s80, s80, 0x3ff
	s_lshr_b32 s83, s80, 6
	s_lshl_b32 s80, s80, 4
	s_lshr_b32 s84, s83, 1
	s_and_b32 s83, s83, 1
	s_mul_i32 s84, s84, 0x3000
	s_lshl_b32 s83, s83, 13
	s_add_u32 s83, s83, 0xc000
	v_lshlrev_b32_e32 v200, 7, v200
	v_or_b32_e32 v200, v200, v214
	v_add_u32_e32 v215, s84, v200
	v_add_u32_e32 v211, s83, v200
	v_xor_b32_e32 v214, 0x20, v215
	v_xor_b32_e32 v210, 0x20, v211
	v_xor_b32_e32 v213, 0x40, v215
	v_xor_b32_e32 v209, 0x40, v211
	v_xor_b32_e32 v212, 0x60, v215
	v_xor_b32_e32 v208, 0x60, v211
	v_bfe_u32 v200, v201, 4, 3
	v_and_b32_e32 v206, 7, v201
	v_xor_b32_e32 v200, v200, v206
	v_lshlrev_b32_e32 v200, 4, v200
	v_lshrrev_b32_e32 v206, 3, v201
	v_lshl_or_b32 v207, v206, 11, v200
	v_add_u32_e32 v206, 0x10000, v207
	v_add_u32_e32 v205, 0x20000, v207
	v_add_u32_e32 v204, 0x30000, v207
	v_add_u32_e32 v203, 0x40000, v207
	v_add_u32_e32 v202, 0x50000, v207
	s_lshr_b32 s83, s28, 6
	s_and_b32 s84, s28, 63
	s_mov_b32 s79, 0
	s_mul_i32 s84, s84, 0x60000
	s_lshl_b32 s83, s83, 18
	s_waitcnt lgkmcnt(0)
	s_add_u32 s66, s66, s84
	s_addc_u32 s67, s67, 0
	s_add_u32 s68, s68, s83
	s_addc_u32 s69, s69, 0
	s_add_u32 s83, s79, 0
	s_and_b32 s83, s83, 15
	s_lshl_b32 s83, s83, 7
	s_add_u32 s70, s66, s83
	s_addc_u32 s71, s67, 0
	s_add_u32 s72, s68, s83
	s_addc_u32 s73, s69, 0
	s_add_u32 s81, s80, 0x0
	s_add_u32 s82, s80, 0xc000
	s_add_u32 m0, s81, 0x0
	s_nop 0
	global_load_lds_dwordx4 v207, s[70:71]
	s_add_u32 m0, s81, 0x1000
	s_nop 0
	global_load_lds_dwordx4 v206, s[70:71]
	s_add_u32 m0, s81, 0x2000
	s_nop 0
	global_load_lds_dwordx4 v205, s[70:71]
	s_add_u32 m0, s81, 0x3000
	s_nop 0
	global_load_lds_dwordx4 v204, s[70:71]
	s_add_u32 m0, s81, 0x4000
	s_nop 0
	global_load_lds_dwordx4 v203, s[70:71]
	s_add_u32 m0, s81, 0x5000
	s_nop 0
	global_load_lds_dwordx4 v202, s[70:71]
	s_add_u32 m0, s82, 0x0
	s_nop 0
	global_load_lds_dwordx4 v207, s[72:73]
	s_add_u32 m0, s82, 0x1000
	s_nop 0
	global_load_lds_dwordx4 v206, s[72:73]
	s_add_u32 m0, s82, 0x2000
	s_nop 0
	global_load_lds_dwordx4 v205, s[72:73]
	s_add_u32 m0, s82, 0x3000
	s_nop 0
	global_load_lds_dwordx4 v204, s[72:73]
	s_add_u32 s83, s79, 1
	s_and_b32 s83, s83, 15
	s_lshl_b32 s83, s83, 7
	s_add_u32 s70, s66, s83
	s_addc_u32 s71, s67, 0
	s_add_u32 s72, s68, s83
	s_addc_u32 s73, s69, 0
	s_add_u32 s81, s80, 0x6000
	s_add_u32 s82, s80, 0x10000
	s_add_u32 m0, s81, 0x0
	s_nop 0
	global_load_lds_dwordx4 v207, s[70:71]
	s_add_u32 m0, s81, 0x1000
	s_nop 0
	global_load_lds_dwordx4 v206, s[70:71]
	s_add_u32 m0, s81, 0x2000
	s_nop 0
	global_load_lds_dwordx4 v205, s[70:71]
	s_add_u32 m0, s81, 0x3000
	s_nop 0
	global_load_lds_dwordx4 v204, s[70:71]
	s_add_u32 m0, s81, 0x4000
	s_nop 0
	global_load_lds_dwordx4 v203, s[70:71]
	v_mov_b32_e32 v2, 0
	v_mov_b32_e32 v3, 0
	v_mov_b32_e32 v4, 0
	v_mov_b32_e32 v5, 0
	v_mov_b32_e32 v6, 0
	v_mov_b32_e32 v7, 0
	v_mov_b32_e32 v8, 0
	v_mov_b32_e32 v9, 0
	v_mov_b32_e32 v10, 0
	v_mov_b32_e32 v11, 0
	v_mov_b32_e32 v12, 0
	v_mov_b32_e32 v13, 0
	v_mov_b32_e32 v14, 0
	v_mov_b32_e32 v15, 0
	v_mov_b32_e32 v16, 0
	v_mov_b32_e32 v17, 0
	v_mov_b32_e32 v18, 0
	v_mov_b32_e32 v19, 0
	v_mov_b32_e32 v20, 0
	v_mov_b32_e32 v21, 0
	v_mov_b32_e32 v22, 0
	v_mov_b32_e32 v23, 0
	v_mov_b32_e32 v24, 0
	v_mov_b32_e32 v25, 0
	v_mov_b32_e32 v26, 0
	v_mov_b32_e32 v27, 0
	v_mov_b32_e32 v28, 0
	v_mov_b32_e32 v29, 0
	v_mov_b32_e32 v30, 0
	v_mov_b32_e32 v31, 0
	v_mov_b32_e32 v32, 0
	v_mov_b32_e32 v33, 0
	v_mov_b32_e32 v34, 0
	v_mov_b32_e32 v35, 0
	v_mov_b32_e32 v36, 0
	v_mov_b32_e32 v37, 0
	v_mov_b32_e32 v38, 0
	v_mov_b32_e32 v39, 0
	v_mov_b32_e32 v40, 0
	v_mov_b32_e32 v41, 0
	v_mov_b32_e32 v42, 0
	v_mov_b32_e32 v43, 0
	v_mov_b32_e32 v44, 0
	v_mov_b32_e32 v45, 0
	v_mov_b32_e32 v46, 0
	v_mov_b32_e32 v47, 0
	v_mov_b32_e32 v48, 0
	v_mov_b32_e32 v49, 0
	v_mov_b32_e32 v50, 0
	v_mov_b32_e32 v51, 0
	v_mov_b32_e32 v52, 0
	v_mov_b32_e32 v53, 0
	v_mov_b32_e32 v54, 0
	v_mov_b32_e32 v55, 0
	v_mov_b32_e32 v56, 0
	v_mov_b32_e32 v57, 0
	v_mov_b32_e32 v58, 0
	v_mov_b32_e32 v59, 0
	v_mov_b32_e32 v60, 0
	v_mov_b32_e32 v61, 0
	v_mov_b32_e32 v62, 0
	v_mov_b32_e32 v63, 0
	v_mov_b32_e32 v64, 0
	v_mov_b32_e32 v65, 0
	v_mov_b32_e32 v66, 0
	v_mov_b32_e32 v67, 0
	v_mov_b32_e32 v68, 0
	v_mov_b32_e32 v69, 0
	v_mov_b32_e32 v70, 0
	v_mov_b32_e32 v71, 0
	v_mov_b32_e32 v72, 0
	v_mov_b32_e32 v73, 0
	v_mov_b32_e32 v74, 0
	v_mov_b32_e32 v75, 0
	v_mov_b32_e32 v76, 0
	v_mov_b32_e32 v77, 0
	v_mov_b32_e32 v78, 0
	v_mov_b32_e32 v79, 0
	v_mov_b32_e32 v80, 0
	v_mov_b32_e32 v81, 0
	v_mov_b32_e32 v82, 0
	v_mov_b32_e32 v83, 0
	v_mov_b32_e32 v84, 0
	v_mov_b32_e32 v85, 0
	v_mov_b32_e32 v86, 0
	v_mov_b32_e32 v87, 0
	v_mov_b32_e32 v88, 0
	v_mov_b32_e32 v89, 0
	v_mov_b32_e32 v90, 0
	v_mov_b32_e32 v91, 0
	v_mov_b32_e32 v92, 0
	v_mov_b32_e32 v93, 0
	v_mov_b32_e32 v94, 0
	v_mov_b32_e32 v95, 0
	v_mov_b32_e32 v96, 0
	v_mov_b32_e32 v97, 0
	s_waitcnt vmcnt(5)
	s_barrier
	ds_read_b128 v[240:243], v211 offset:0
	ds_read_b128 v[252:255], v215 offset:0
	ds_read_b128 v[236:239], v211 offset:4096
	ds_read_b128 v[248:251], v215 offset:4096
	ds_read_b128 v[244:247], v215 offset:8192
	s_mov_b32 s78, 0
.Lgm_ph5_loop:
	s_waitcnt lgkmcnt(1)
	v_mfma_f32_32x32x16_bf16 v[82:97], v[240:243], v[252:255], v[82:97]
	ds_read_b128 v[220:223], v210 offset:0
	s_add_u32 m0, s81, 0x5000
	s_nop 0
	global_load_lds_dwordx4 v202, s[70:71]
	v_mfma_f32_32x32x16_bf16 v[66:81], v[236:239], v[252:255], v[66:81]
	ds_read_b128 v[232:235], v214 offset:0
	s_add_u32 m0, s82, 0x0
	s_nop 0
	global_load_lds_dwordx4 v207, s[72:73]
	v_mfma_f32_32x32x16_bf16 v[50:65], v[240:243], v[248:251], v[50:65]
	ds_read_b128 v[216:219], v210 offset:4096
	s_add_u32 m0, s82, 0x1000
	s_nop 0
	global_load_lds_dwordx4 v206, s[72:73]
	v_mfma_f32_32x32x16_bf16 v[34:49], v[236:239], v[248:251], v[34:49]
	ds_read_b128 v[228:231], v214 offset:4096
	s_add_u32 m0, s82, 0x2000
	s_nop 0
	global_load_lds_dwordx4 v205, s[72:73]
	s_waitcnt lgkmcnt(4)
	v_mfma_f32_32x32x16_bf16 v[18:33], v[240:243], v[244:247], v[18:33]
	ds_read_b128 v[224:227], v214 offset:8192
	v_mfma_f32_32x32x16_bf16 v[2:17], v[236:239], v[244:247], v[2:17]
	s_add_u32 m0, s82, 0x3000
	s_nop 0
	global_load_lds_dwordx4 v204, s[72:73]
	s_waitcnt lgkmcnt(1)
	v_mfma_f32_32x32x16_bf16 v[82:97], v[220:223], v[232:235], v[82:97]
	ds_read_b128 v[240:243], v209 offset:0
	v_mfma_f32_32x32x16_bf16 v[66:81], v[216:219], v[232:235], v[66:81]
	ds_read_b128 v[252:255], v213 offset:0
	v_mfma_f32_32x32x16_bf16 v[50:65], v[220:223], v[228:231], v[50:65]
	ds_read_b128 v[236:239], v209 offset:4096
	v_mfma_f32_32x32x16_bf16 v[34:49], v[216:219], v[228:231], v[34:49]
	ds_read_b128 v[248:251], v213 offset:4096
	s_waitcnt lgkmcnt(4)
	v_mfma_f32_32x32x16_bf16 v[18:33], v[220:223], v[224:227], v[18:33]
	ds_read_b128 v[244:247], v213 offset:8192
	v_mfma_f32_32x32x16_bf16 v[2:17], v[216:219], v[224:227], v[2:17]
	s_waitcnt lgkmcnt(1)
	v_mfma_f32_32x32x16_bf16 v[82:97], v[240:243], v[252:255], v[82:97]
	ds_read_b128 v[220:223], v208 offset:0
	s_add_u32 s83, s79, s78
	s_add_u32 s83, s83, 2
	s_and_b32 s83, s83, 15
	v_mfma_f32_32x32x16_bf16 v[66:81], v[236:239], v[252:255], v[66:81]
	ds_read_b128 v[232:235], v212 offset:0
	s_lshl_b32 s83, s83, 7
	s_add_u32 s70, s66, s83
	v_mfma_f32_32x32x16_bf16 v[50:65], v[240:243], v[248:251], v[50:65]
	ds_read_b128 v[216:219], v208 offset:4096
	s_addc_u32 s71, s67, 0
	s_add_u32 s72, s68, s83
	v_mfma_f32_32x32x16_bf16 v[34:49], v[236:239], v[248:251], v[34:49]
	ds_read_b128 v[228:231], v212 offset:4096
	s_addc_u32 s73, s69, 0
	s_add_u32 s81, s80, 0x0
	s_add_u32 s82, s80, 0xc000
	s_waitcnt lgkmcnt(4)
	v_mfma_f32_32x32x16_bf16 v[18:33], v[240:243], v[244:247], v[18:33]
	ds_read_b128 v[224:227], v212 offset:8192
	v_mfma_f32_32x32x16_bf16 v[2:17], v[236:239], v[244:247], v[2:17]
	s_waitcnt vmcnt(0) lgkmcnt(0)
	s_barrier
	v_mfma_f32_32x32x16_bf16 v[82:97], v[220:223], v[232:235], v[82:97]
	s_add_u32 m0, s81, 0x0
	ds_read_b128 v[240:243], v211 offset:16384
	global_load_lds_dwordx4 v207, s[70:71]
	v_mfma_f32_32x32x16_bf16 v[66:81], v[216:219], v[232:235], v[66:81]
	s_add_u32 m0, s81, 0x1000
	ds_read_b128 v[252:255], v215 offset:24576
	global_load_lds_dwordx4 v206, s[70:71]
	v_mfma_f32_32x32x16_bf16 v[50:65], v[220:223], v[228:231], v[50:65]
	s_add_u32 m0, s81, 0x2000
	ds_read_b128 v[236:239], v211 offset:20480
	global_load_lds_dwordx4 v205, s[70:71]
	v_mfma_f32_32x32x16_bf16 v[34:49], v[216:219], v[228:231], v[34:49]
	s_add_u32 m0, s81, 0x3000
	ds_read_b128 v[248:251], v215 offset:28672
	global_load_lds_dwordx4 v204, s[70:71]
	v_mfma_f32_32x32x16_bf16 v[18:33], v[220:223], v[224:227], v[18:33]
	s_add_u32 m0, s81, 0x4000
	ds_read_b128 v[244:247], v215 offset:32768
	global_load_lds_dwordx4 v203, s[70:71]
	v_mfma_f32_32x32x16_bf16 v[2:17], v[216:219], v[224:227], v[2:17]
	s_waitcnt lgkmcnt(1)
	v_mfma_f32_32x32x16_bf16 v[82:97], v[240:243], v[252:255], v[82:97]
	ds_read_b128 v[220:223], v210 offset:16384
	s_add_u32 m0, s81, 0x5000
	s_nop 0
	global_load_lds_dwordx4 v202, s[70:71]
	v_mfma_f32_32x32x16_bf16 v[66:81], v[236:239], v[252:255], v[66:81]
	ds_read_b128 v[232:235], v214 offset:24576
	s_add_u32 m0, s82, 0x0
	s_nop 0
	global_load_lds_dwordx4 v207, s[72:73]
	v_mfma_f32_32x32x16_bf16 v[50:65], v[240:243], v[248:251], v[50:65]
	ds_read_b128 v[216:219], v210 offset:20480
	s_add_u32 m0, s82, 0x1000
	s_nop 0
	global_load_lds_dwordx4 v206, s[72:73]
	v_mfma_f32_32x32x16_bf16 v[34:49], v[236:239], v[248:251], v[34:49]
	ds_read_b128 v[228:231], v214 offset:28672
	s_add_u32 m0, s82, 0x2000
	s_nop 0
	global_load_lds_dwordx4 v205, s[72:73]
	s_waitcnt lgkmcnt(4)
	v_mfma_f32_32x32x16_bf16 v[18:33], v[240:243], v[244:247], v[18:33]
	ds_read_b128 v[224:227], v214 offset:32768
	v_mfma_f32_32x32x16_bf16 v[2:17], v[236:239], v[244:247], v[2:17]
	s_add_u32 m0, s82, 0x3000
	s_nop 0
	global_load_lds_dwordx4 v204, s[72:73]
	s_waitcnt lgkmcnt(1)
	v_mfma_f32_32x32x16_bf16 v[82:97], v[220:223], v[232:235], v[82:97]
	ds_read_b128 v[240:243], v209 offset:16384
	v_mfma_f32_32x32x16_bf16 v[66:81], v[216:219], v[232:235], v[66:81]
	ds_read_b128 v[252:255], v213 offset:24576
	v_mfma_f32_32x32x16_bf16 v[50:65], v[220:223], v[228:231], v[50:65]
	ds_read_b128 v[236:239], v209 offset:20480
	v_mfma_f32_32x32x16_bf16 v[34:49], v[216:219], v[228:231], v[34:49]
	ds_read_b128 v[248:251], v213 offset:28672
	s_waitcnt lgkmcnt(4)
	v_mfma_f32_32x32x16_bf16 v[18:33], v[220:223], v[224:227], v[18:33]
	ds_read_b128 v[244:247], v213 offset:32768
	v_mfma_f32_32x32x16_bf16 v[2:17], v[216:219], v[224:227], v[2:17]
	s_waitcnt lgkmcnt(1)
	v_mfma_f32_32x32x16_bf16 v[82:97], v[240:243], v[252:255], v[82:97]
	ds_read_b128 v[220:223], v208 offset:16384
	s_add_u32 s83, s79, s78
	s_add_u32 s83, s83, 3
	s_and_b32 s83, s83, 15
	v_mfma_f32_32x32x16_bf16 v[66:81], v[236:239], v[252:255], v[66:81]
	ds_read_b128 v[232:235], v212 offset:24576
	s_lshl_b32 s83, s83, 7
	s_add_u32 s70, s66, s83
	v_mfma_f32_32x32x16_bf16 v[50:65], v[240:243], v[248:251], v[50:65]
	ds_read_b128 v[216:219], v208 offset:20480
	s_addc_u32 s71, s67, 0
	s_add_u32 s72, s68, s83
	v_mfma_f32_32x32x16_bf16 v[34:49], v[236:239], v[248:251], v[34:49]
	ds_read_b128 v[228:231], v212 offset:28672
	s_addc_u32 s73, s69, 0
	s_add_u32 s81, s80, 0x6000
	s_add_u32 s82, s80, 0x10000
	s_waitcnt lgkmcnt(4)
	v_mfma_f32_32x32x16_bf16 v[18:33], v[240:243], v[244:247], v[18:33]
	ds_read_b128 v[224:227], v212 offset:32768
	v_mfma_f32_32x32x16_bf16 v[2:17], v[236:239], v[244:247], v[2:17]
	s_waitcnt vmcnt(0) lgkmcnt(0)
	s_barrier
	v_mfma_f32_32x32x16_bf16 v[82:97], v[220:223], v[232:235], v[82:97]
	s_add_u32 m0, s81, 0x0
	ds_read_b128 v[240:243], v211 offset:0
	global_load_lds_dwordx4 v207, s[70:71]
	v_mfma_f32_32x32x16_bf16 v[66:81], v[216:219], v[232:235], v[66:81]
	s_add_u32 m0, s81, 0x1000
	ds_read_b128 v[252:255], v215 offset:0
	global_load_lds_dwordx4 v206, s[70:71]
	v_mfma_f32_32x32x16_bf16 v[50:65], v[220:223], v[228:231], v[50:65]
	s_add_u32 m0, s81, 0x2000
	ds_read_b128 v[236:239], v211 offset:4096
	global_load_lds_dwordx4 v205, s[70:71]
	v_mfma_f32_32x32x16_bf16 v[34:49], v[216:219], v[228:231], v[34:49]
	s_add_u32 m0, s81, 0x3000
	ds_read_b128 v[248:251], v215 offset:4096
	global_load_lds_dwordx4 v204, s[70:71]
	v_mfma_f32_32x32x16_bf16 v[18:33], v[220:223], v[224:227], v[18:33]
	s_add_u32 m0, s81, 0x4000
	ds_read_b128 v[244:247], v215 offset:8192
	global_load_lds_dwordx4 v203, s[70:71]
	v_mfma_f32_32x32x16_bf16 v[2:17], v[216:219], v[224:227], v[2:17]
	s_add_u32 s78, s78, 2
	s_cmp_lt_u32 s78, 14
	s_cbranch_scc1 .Lgm_ph5_loop
	s_waitcnt lgkmcnt(1)
	v_mfma_f32_32x32x16_bf16 v[82:97], v[240:243], v[252:255], v[82:97]
	ds_read_b128 v[220:223], v210 offset:0
	s_add_u32 m0, s81, 0x5000
	s_nop 0
	global_load_lds_dwordx4 v202, s[70:71]
	v_mfma_f32_32x32x16_bf16 v[66:81], v[236:239], v[252:255], v[66:81]
	ds_read_b128 v[232:235], v214 offset:0
	s_add_u32 m0, s82, 0x0
	s_nop 0
	global_load_lds_dwordx4 v207, s[72:73]
	v_mfma_f32_32x32x16_bf16 v[50:65], v[240:243], v[248:251], v[50:65]
	ds_read_b128 v[216:219], v210 offset:4096
	s_add_u32 m0, s82, 0x1000
	s_nop 0
	global_load_lds_dwordx4 v206, s[72:73]
	v_mfma_f32_32x32x16_bf16 v[34:49], v[236:239], v[248:251], v[34:49]
	ds_read_b128 v[228:231], v214 offset:4096
	s_add_u32 m0, s82, 0x2000
	s_nop 0
	global_load_lds_dwordx4 v205, s[72:73]
	s_waitcnt lgkmcnt(4)
	v_mfma_f32_32x32x16_bf16 v[18:33], v[240:243], v[244:247], v[18:33]
	ds_read_b128 v[224:227], v214 offset:8192
	v_mfma_f32_32x32x16_bf16 v[2:17], v[236:239], v[244:247], v[2:17]
	s_add_u32 m0, s82, 0x3000
	s_nop 0
	global_load_lds_dwordx4 v204, s[72:73]
	s_waitcnt lgkmcnt(1)
	v_mfma_f32_32x32x16_bf16 v[82:97], v[220:223], v[232:235], v[82:97]
	ds_read_b128 v[240:243], v209 offset:0
	v_mfma_f32_32x32x16_bf16 v[66:81], v[216:219], v[232:235], v[66:81]
	ds_read_b128 v[252:255], v213 offset:0
	v_mfma_f32_32x32x16_bf16 v[50:65], v[220:223], v[228:231], v[50:65]
	ds_read_b128 v[236:239], v209 offset:4096
	v_mfma_f32_32x32x16_bf16 v[34:49], v[216:219], v[228:231], v[34:49]
	ds_read_b128 v[248:251], v213 offset:4096
	s_waitcnt lgkmcnt(4)
	v_mfma_f32_32x32x16_bf16 v[18:33], v[220:223], v[224:227], v[18:33]
	ds_read_b128 v[244:247], v213 offset:8192
	v_mfma_f32_32x32x16_bf16 v[2:17], v[216:219], v[224:227], v[2:17]
	s_waitcnt lgkmcnt(1)
	v_mfma_f32_32x32x16_bf16 v[82:97], v[240:243], v[252:255], v[82:97]
	ds_read_b128 v[220:223], v208 offset:0
	v_mfma_f32_32x32x16_bf16 v[66:81], v[236:239], v[252:255], v[66:81]
	ds_read_b128 v[232:235], v212 offset:0
	v_mfma_f32_32x32x16_bf16 v[50:65], v[240:243], v[248:251], v[50:65]
	ds_read_b128 v[216:219], v208 offset:4096
	v_mfma_f32_32x32x16_bf16 v[34:49], v[236:239], v[248:251], v[34:49]
	ds_read_b128 v[228:231], v212 offset:4096
	s_waitcnt lgkmcnt(4)
	v_mfma_f32_32x32x16_bf16 v[18:33], v[240:243], v[244:247], v[18:33]
	ds_read_b128 v[224:227], v212 offset:8192
	v_mfma_f32_32x32x16_bf16 v[2:17], v[236:239], v[244:247], v[2:17]
	s_waitcnt vmcnt(0) lgkmcnt(0)
	s_barrier
	v_mfma_f32_32x32x16_bf16 v[82:97], v[220:223], v[232:235], v[82:97]
	ds_read_b128 v[240:243], v211 offset:16384
	v_mfma_f32_32x32x16_bf16 v[66:81], v[216:219], v[232:235], v[66:81]
	ds_read_b128 v[252:255], v215 offset:24576
	v_mfma_f32_32x32x16_bf16 v[50:65], v[220:223], v[228:231], v[50:65]
	ds_read_b128 v[236:239], v211 offset:20480
	v_mfma_f32_32x32x16_bf16 v[34:49], v[216:219], v[228:231], v[34:49]
	ds_read_b128 v[248:251], v215 offset:28672
	v_mfma_f32_32x32x16_bf16 v[18:33], v[220:223], v[224:227], v[18:33]
	ds_read_b128 v[244:247], v215 offset:32768
	v_mfma_f32_32x32x16_bf16 v[2:17], v[216:219], v[224:227], v[2:17]
	s_waitcnt lgkmcnt(1)
	v_mfma_f32_32x32x16_bf16 v[82:97], v[240:243], v[252:255], v[82:97]
	ds_read_b128 v[220:223], v210 offset:16384
	v_mfma_f32_32x32x16_bf16 v[66:81], v[236:239], v[252:255], v[66:81]
	ds_read_b128 v[232:235], v214 offset:24576
	v_mfma_f32_32x32x16_bf16 v[50:65], v[240:243], v[248:251], v[50:65]
	ds_read_b128 v[216:219], v210 offset:20480
	v_mfma_f32_32x32x16_bf16 v[34:49], v[236:239], v[248:251], v[34:49]
	ds_read_b128 v[228:231], v214 offset:28672
	s_waitcnt lgkmcnt(4)
	v_mfma_f32_32x32x16_bf16 v[18:33], v[240:243], v[244:247], v[18:33]
	ds_read_b128 v[224:227], v214 offset:32768
	v_mfma_f32_32x32x16_bf16 v[2:17], v[236:239], v[244:247], v[2:17]
	s_waitcnt lgkmcnt(1)
	v_mfma_f32_32x32x16_bf16 v[82:97], v[220:223], v[232:235], v[82:97]
	ds_read_b128 v[240:243], v209 offset:16384
	v_mfma_f32_32x32x16_bf16 v[66:81], v[216:219], v[232:235], v[66:81]
	ds_read_b128 v[252:255], v213 offset:24576
	v_mfma_f32_32x32x16_bf16 v[50:65], v[220:223], v[228:231], v[50:65]
	ds_read_b128 v[236:239], v209 offset:20480
	v_mfma_f32_32x32x16_bf16 v[34:49], v[216:219], v[228:231], v[34:49]
	ds_read_b128 v[248:251], v213 offset:28672
	s_waitcnt lgkmcnt(4)
	v_mfma_f32_32x32x16_bf16 v[18:33], v[220:223], v[224:227], v[18:33]
	ds_read_b128 v[244:247], v213 offset:32768
	v_mfma_f32_32x32x16_bf16 v[2:17], v[216:219], v[224:227], v[2:17]
	s_waitcnt lgkmcnt(1)
	v_mfma_f32_32x32x16_bf16 v[82:97], v[240:243], v[252:255], v[82:97]
	ds_read_b128 v[220:223], v208 offset:16384
	v_mfma_f32_32x32x16_bf16 v[66:81], v[236:239], v[252:255], v[66:81]
	ds_read_b128 v[232:235], v212 offset:24576
	v_mfma_f32_32x32x16_bf16 v[50:65], v[240:243], v[248:251], v[50:65]
	ds_read_b128 v[216:219], v208 offset:20480
	v_mfma_f32_32x32x16_bf16 v[34:49], v[236:239], v[248:251], v[34:49]
	ds_read_b128 v[228:231], v212 offset:28672
	s_waitcnt lgkmcnt(4)
	v_mfma_f32_32x32x16_bf16 v[18:33], v[240:243], v[244:247], v[18:33]
	ds_read_b128 v[224:227], v212 offset:32768
	v_mfma_f32_32x32x16_bf16 v[2:17], v[236:239], v[244:247], v[2:17]
	s_waitcnt vmcnt(0) lgkmcnt(0)
	s_barrier
	v_mfma_f32_32x32x16_bf16 v[82:97], v[220:223], v[232:235], v[82:97]
	v_mfma_f32_32x32x16_bf16 v[66:81], v[216:219], v[232:235], v[66:81]
	v_mfma_f32_32x32x16_bf16 v[50:65], v[220:223], v[228:231], v[50:65]
	v_mfma_f32_32x32x16_bf16 v[34:49], v[216:219], v[228:231], v[34:49]
	v_mfma_f32_32x32x16_bf16 v[18:33], v[220:223], v[224:227], v[18:33]
	v_mfma_f32_32x32x16_bf16 v[2:17], v[216:219], v[224:227], v[2:17]
	s_nop 7
	s_nop 7
	s_setprio 0
	s_waitcnt lgkmcnt(0)
	s_nop 10
	ds_write_b128 v147, v[82:85]
	ds_write_b128 v147, v[86:89] offset:32
	ds_write_b128 v147, v[90:93] offset:64
	ds_write_b128 v147, v[94:97] offset:96
	ds_write_b128 v147, v[66:69] offset:128
	ds_write_b128 v147, v[70:73] offset:160
	ds_write_b128 v147, v[74:77] offset:192
	ds_write_b128 v147, v[78:81] offset:224
	s_waitcnt lgkmcnt(0)
	v_add_u32_e32 v104, s29, v111
	v_or_b32_e32 v244, s30, v120
	v_lshlrev_b32_e32 v242, 2, v244
	v_add_u32_e32 v242, s3, v242
	v_lshlrev_b32_e32 v243, 1, v244
	v_mov_b32_e32 v240, v104
	v_add_u32_e32 v241, 0xfffff000, v240
	v_lshrrev_b32_e32 v241, 11, v241
	v_mad_u32_u24 v241, v241, s26, s26
	v_lshlrev_b32_e32 v241, 2, v241
	v_or_b32_e32 v232, v240, v119
	v_or_b32_e32 v233, v240, v121
	v_or_b32_e32 v234, v240, v122
	v_or_b32_e32 v235, v240, v123
	v_or_b32_e32 v236, v240, v124
	v_or_b32_e32 v237, v240, v125
	v_or_b32_e32 v238, v240, v126
	v_or_b32_e32 v239, v240, v127
	v_cmp_lt_i32_e64 s[82:83], s27, v232
	v_cmp_lt_i32_e64 s[84:85], s27, v233
	v_cmp_lt_i32_e64 s[86:87], s27, v234
	v_cmp_lt_i32_e64 s[88:89], s27, v235
	v_cmp_lt_i32_e64 s[90:91], s27, v236
	v_cmp_lt_i32_e64 s[92:93], s27, v237
	v_cmp_lt_i32_e64 s[94:95], s27, v238
	v_cmp_lt_i32_e64 s[96:97], s27, v239
	s_waitcnt lgkmcnt(0)
	v_cndmask_b32_e64 v200, 0, v241, s[82:83]
	v_cndmask_b32_e64 v204, 0, v241, s[84:85]
	v_cndmask_b32_e64 v208, 0, v241, s[86:87]
	v_cndmask_b32_e64 v212, 0, v241, s[88:89]
	v_cndmask_b32_e64 v216, 0, v241, s[90:91]
	v_cndmask_b32_e64 v220, 0, v241, s[92:93]
	v_cndmask_b32_e64 v224, 0, v241, s[94:95]
	v_cndmask_b32_e64 v228, 0, v241, s[96:97]
	v_add_u32_e32 v200, v200, v242
	v_add_u32_e32 v204, v204, v242
	v_add_u32_e32 v208, v208, v242
	v_add_u32_e32 v212, v212, v242
	v_add_u32_e32 v216, v216, v242
	v_add_u32_e32 v220, v220, v242
	v_add_u32_e32 v224, v224, v242
	v_add_u32_e32 v228, v228, v242
	ds_read_b128 v[82:85], v149
	global_load_dwordx4 v[200:203], v200, s[4:5]
	ds_read_b128 v[86:89], v149 offset:1088
	global_load_dwordx4 v[204:207], v204, s[4:5]
	ds_read_b128 v[90:93], v149 offset:2176
	global_load_dwordx4 v[208:211], v208, s[4:5]
	ds_read_b128 v[94:97], v149 offset:3264
	global_load_dwordx4 v[212:215], v212, s[4:5]
	ds_read_b128 v[66:69], v149 offset:4352
	global_load_dwordx4 v[216:219], v216, s[4:5]
	ds_read_b128 v[70:73], v149 offset:5440
	global_load_dwordx4 v[220:223], v220, s[4:5]
	ds_read_b128 v[74:77], v149 offset:6528
	global_load_dwordx4 v[224:227], v224, s[4:5]
	ds_read_b128 v[78:81], v149 offset:7616
	global_load_dwordx4 v[228:231], v228, s[4:5]
	v_lshl_add_u32 v232, v232, 11, v243
	v_lshl_add_u32 v233, v233, 11, v243
	v_lshl_add_u32 v234, v234, 11, v243
	v_lshl_add_u32 v235, v235, 11, v243
	v_lshl_add_u32 v236, v236, 11, v243
	v_lshl_add_u32 v237, v237, 11, v243
	v_lshl_add_u32 v238, v238, 11, v243
	v_lshl_add_u32 v239, v239, 11, v243
	s_waitcnt vmcnt(7) lgkmcnt(7)
	v_mul_f32_e32 v82, v82, v200
	v_mul_f32_e32 v83, v83, v201
	v_mul_f32_e32 v84, v84, v202
	v_mul_f32_e32 v85, v85, v203
	v_cvt_pk_bf16_f32 v82, v82, v83
	v_cvt_pk_bf16_f32 v83, v84, v85
	global_store_dwordx2 v232, v[82:83], s[6:7] sc1
	s_waitcnt vmcnt(7) lgkmcnt(6)
	v_mul_f32_e32 v86, v86, v204
	v_mul_f32_e32 v87, v87, v205
	v_mul_f32_e32 v88, v88, v206
	v_mul_f32_e32 v89, v89, v207
	v_cvt_pk_bf16_f32 v86, v86, v87
	v_cvt_pk_bf16_f32 v87, v88, v89
	global_store_dwordx2 v233, v[86:87], s[6:7] sc1
	s_waitcnt vmcnt(7) lgkmcnt(5)
	v_mul_f32_e32 v90, v90, v208
	v_mul_f32_e32 v91, v91, v209
	v_mul_f32_e32 v92, v92, v210
	v_mul_f32_e32 v93, v93, v211
	v_cvt_pk_bf16_f32 v90, v90, v91
	v_cvt_pk_bf16_f32 v91, v92, v93
	global_store_dwordx2 v234, v[90:91], s[6:7] sc1
	s_waitcnt vmcnt(7) lgkmcnt(4)
	v_mul_f32_e32 v94, v94, v212
	v_mul_f32_e32 v95, v95, v213
	v_mul_f32_e32 v96, v96, v214
	v_mul_f32_e32 v97, v97, v215
	v_cvt_pk_bf16_f32 v94, v94, v95
	v_cvt_pk_bf16_f32 v95, v96, v97
	global_store_dwordx2 v235, v[94:95], s[6:7] sc1
	s_waitcnt vmcnt(7) lgkmcnt(3)
	v_mul_f32_e32 v66, v66, v216
	v_mul_f32_e32 v67, v67, v217
	v_mul_f32_e32 v68, v68, v218
	v_mul_f32_e32 v69, v69, v219
	v_cvt_pk_bf16_f32 v66, v66, v67
	v_cvt_pk_bf16_f32 v67, v68, v69
	global_store_dwordx2 v236, v[66:67], s[6:7] sc1
	s_waitcnt vmcnt(7) lgkmcnt(2)
	v_mul_f32_e32 v70, v70, v220
	v_mul_f32_e32 v71, v71, v221
	v_mul_f32_e32 v72, v72, v222
	v_mul_f32_e32 v73, v73, v223
	v_cvt_pk_bf16_f32 v70, v70, v71
	v_cvt_pk_bf16_f32 v71, v72, v73
	global_store_dwordx2 v237, v[70:71], s[6:7] sc1
	s_waitcnt vmcnt(7) lgkmcnt(1)
	v_mul_f32_e32 v74, v74, v224
	v_mul_f32_e32 v75, v75, v225
	v_mul_f32_e32 v76, v76, v226
	v_mul_f32_e32 v77, v77, v227
	v_cvt_pk_bf16_f32 v74, v74, v75
	v_cvt_pk_bf16_f32 v75, v76, v77
	global_store_dwordx2 v238, v[74:75], s[6:7] sc1
	s_waitcnt vmcnt(7) lgkmcnt(0)
	v_mul_f32_e32 v78, v78, v228
	v_mul_f32_e32 v79, v79, v229
	v_mul_f32_e32 v80, v80, v230
	v_mul_f32_e32 v81, v81, v231
	v_cvt_pk_bf16_f32 v78, v78, v79
	v_cvt_pk_bf16_f32 v79, v80, v81
	global_store_dwordx2 v239, v[78:79], s[6:7] sc1
	ds_write_b128 v147, v[50:53]
	ds_write_b128 v147, v[54:57] offset:32
	ds_write_b128 v147, v[58:61] offset:64
	ds_write_b128 v147, v[62:65] offset:96
	ds_write_b128 v147, v[34:37] offset:128
	ds_write_b128 v147, v[38:41] offset:160
	ds_write_b128 v147, v[42:45] offset:192
	ds_write_b128 v147, v[46:49] offset:224
	v_add_u32_e32 v240, 0x20, v104
	v_add_u32_e32 v241, 0xfffff000, v240
	v_lshrrev_b32_e32 v241, 11, v241
	v_mad_u32_u24 v241, v241, s26, s26
	v_lshlrev_b32_e32 v241, 2, v241
	v_or_b32_e32 v232, v240, v119
	v_or_b32_e32 v233, v240, v121
	v_or_b32_e32 v234, v240, v122
	v_or_b32_e32 v235, v240, v123
	v_or_b32_e32 v236, v240, v124
	v_or_b32_e32 v237, v240, v125
	v_or_b32_e32 v238, v240, v126
	v_or_b32_e32 v239, v240, v127
	v_cmp_lt_i32_e64 s[82:83], s27, v232
	v_cmp_lt_i32_e64 s[84:85], s27, v233
	v_cmp_lt_i32_e64 s[86:87], s27, v234
	v_cmp_lt_i32_e64 s[88:89], s27, v235
	v_cmp_lt_i32_e64 s[90:91], s27, v236
	v_cmp_lt_i32_e64 s[92:93], s27, v237
	v_cmp_lt_i32_e64 s[94:95], s27, v238
	v_cmp_lt_i32_e64 s[96:97], s27, v239
	s_waitcnt lgkmcnt(0)
	v_cndmask_b32_e64 v200, 0, v241, s[82:83]
	v_cndmask_b32_e64 v204, 0, v241, s[84:85]
	v_cndmask_b32_e64 v208, 0, v241, s[86:87]
	v_cndmask_b32_e64 v212, 0, v241, s[88:89]
	v_cndmask_b32_e64 v216, 0, v241, s[90:91]
	v_cndmask_b32_e64 v220, 0, v241, s[92:93]
	v_cndmask_b32_e64 v224, 0, v241, s[94:95]
	v_cndmask_b32_e64 v228, 0, v241, s[96:97]
	v_add_u32_e32 v200, v200, v242
	v_add_u32_e32 v204, v204, v242
	v_add_u32_e32 v208, v208, v242
	v_add_u32_e32 v212, v212, v242
	v_add_u32_e32 v216, v216, v242
	v_add_u32_e32 v220, v220, v242
	v_add_u32_e32 v224, v224, v242
	v_add_u32_e32 v228, v228, v242
	ds_read_b128 v[50:53], v149
	global_load_dwordx4 v[200:203], v200, s[4:5]
	ds_read_b128 v[54:57], v149 offset:1088
	global_load_dwordx4 v[204:207], v204, s[4:5]
	ds_read_b128 v[58:61], v149 offset:2176
	global_load_dwordx4 v[208:211], v208, s[4:5]
	ds_read_b128 v[62:65], v149 offset:3264
	global_load_dwordx4 v[212:215], v212, s[4:5]
	ds_read_b128 v[34:37], v149 offset:4352
	global_load_dwordx4 v[216:219], v216, s[4:5]
	ds_read_b128 v[38:41], v149 offset:5440
	global_load_dwordx4 v[220:223], v220, s[4:5]
	ds_read_b128 v[42:45], v149 offset:6528
	global_load_dwordx4 v[224:227], v224, s[4:5]
	ds_read_b128 v[46:49], v149 offset:7616
	global_load_dwordx4 v[228:231], v228, s[4:5]
	v_lshl_add_u32 v232, v232, 11, v243
	v_lshl_add_u32 v233, v233, 11, v243
	v_lshl_add_u32 v234, v234, 11, v243
	v_lshl_add_u32 v235, v235, 11, v243
	v_lshl_add_u32 v236, v236, 11, v243
	v_lshl_add_u32 v237, v237, 11, v243
	v_lshl_add_u32 v238, v238, 11, v243
	v_lshl_add_u32 v239, v239, 11, v243
	s_waitcnt vmcnt(7) lgkmcnt(7)
	v_mul_f32_e32 v50, v50, v200
	v_mul_f32_e32 v51, v51, v201
	v_mul_f32_e32 v52, v52, v202
	v_mul_f32_e32 v53, v53, v203
	v_cvt_pk_bf16_f32 v50, v50, v51
	v_cvt_pk_bf16_f32 v51, v52, v53
	global_store_dwordx2 v232, v[50:51], s[6:7] sc1
	s_waitcnt vmcnt(7) lgkmcnt(6)
	v_mul_f32_e32 v54, v54, v204
	v_mul_f32_e32 v55, v55, v205
	v_mul_f32_e32 v56, v56, v206
	v_mul_f32_e32 v57, v57, v207
	v_cvt_pk_bf16_f32 v54, v54, v55
	v_cvt_pk_bf16_f32 v55, v56, v57
	global_store_dwordx2 v233, v[54:55], s[6:7] sc1
	s_waitcnt vmcnt(7) lgkmcnt(5)
	v_mul_f32_e32 v58, v58, v208
	v_mul_f32_e32 v59, v59, v209
	v_mul_f32_e32 v60, v60, v210
	v_mul_f32_e32 v61, v61, v211
	v_cvt_pk_bf16_f32 v58, v58, v59
	v_cvt_pk_bf16_f32 v59, v60, v61
	global_store_dwordx2 v234, v[58:59], s[6:7] sc1
	s_waitcnt vmcnt(7) lgkmcnt(4)
	v_mul_f32_e32 v62, v62, v212
	v_mul_f32_e32 v63, v63, v213
	v_mul_f32_e32 v64, v64, v214
	v_mul_f32_e32 v65, v65, v215
	v_cvt_pk_bf16_f32 v62, v62, v63
	v_cvt_pk_bf16_f32 v63, v64, v65
	global_store_dwordx2 v235, v[62:63], s[6:7] sc1
	s_waitcnt vmcnt(7) lgkmcnt(3)
	v_mul_f32_e32 v34, v34, v216
	v_mul_f32_e32 v35, v35, v217
	v_mul_f32_e32 v36, v36, v218
	v_mul_f32_e32 v37, v37, v219
	v_cvt_pk_bf16_f32 v34, v34, v35
	v_cvt_pk_bf16_f32 v35, v36, v37
	global_store_dwordx2 v236, v[34:35], s[6:7] sc1
	s_waitcnt vmcnt(7) lgkmcnt(2)
	v_mul_f32_e32 v38, v38, v220
	v_mul_f32_e32 v39, v39, v221
	v_mul_f32_e32 v40, v40, v222
	v_mul_f32_e32 v41, v41, v223
	v_cvt_pk_bf16_f32 v38, v38, v39
	v_cvt_pk_bf16_f32 v39, v40, v41
	global_store_dwordx2 v237, v[38:39], s[6:7] sc1
	s_waitcnt vmcnt(7) lgkmcnt(1)
	v_mul_f32_e32 v42, v42, v224
	v_mul_f32_e32 v43, v43, v225
	v_mul_f32_e32 v44, v44, v226
	v_mul_f32_e32 v45, v45, v227
	v_cvt_pk_bf16_f32 v42, v42, v43
	v_cvt_pk_bf16_f32 v43, v44, v45
	global_store_dwordx2 v238, v[42:43], s[6:7] sc1
	s_waitcnt vmcnt(7) lgkmcnt(0)
	v_mul_f32_e32 v46, v46, v228
	v_mul_f32_e32 v47, v47, v229
	v_mul_f32_e32 v48, v48, v230
	v_mul_f32_e32 v49, v49, v231
	v_cvt_pk_bf16_f32 v46, v46, v47
	v_cvt_pk_bf16_f32 v47, v48, v49
	global_store_dwordx2 v239, v[46:47], s[6:7] sc1
	ds_write_b128 v147, v[18:21]
	ds_write_b128 v147, v[22:25] offset:32
	ds_write_b128 v147, v[26:29] offset:64
	ds_write_b128 v147, v[30:33] offset:96
	ds_write_b128 v147, v[2:5] offset:128
	ds_write_b128 v147, v[6:9] offset:160
	ds_write_b128 v147, v[10:13] offset:192
	ds_write_b128 v147, v[14:17] offset:224
	v_add_u32_e32 v240, 0x40, v104
	v_add_u32_e32 v241, 0xfffff000, v240
	v_lshrrev_b32_e32 v241, 11, v241
	v_mad_u32_u24 v241, v241, s26, s26
	v_lshlrev_b32_e32 v241, 2, v241
	v_or_b32_e32 v232, v240, v119
	v_or_b32_e32 v233, v240, v121
	v_or_b32_e32 v234, v240, v122
	v_or_b32_e32 v235, v240, v123
	v_or_b32_e32 v236, v240, v124
	v_or_b32_e32 v237, v240, v125
	v_or_b32_e32 v238, v240, v126
	v_or_b32_e32 v239, v240, v127
	v_cmp_lt_i32_e64 s[82:83], s27, v232
	v_cmp_lt_i32_e64 s[84:85], s27, v233
	v_cmp_lt_i32_e64 s[86:87], s27, v234
	v_cmp_lt_i32_e64 s[88:89], s27, v235
	v_cmp_lt_i32_e64 s[90:91], s27, v236
	v_cmp_lt_i32_e64 s[92:93], s27, v237
	v_cmp_lt_i32_e64 s[94:95], s27, v238
	v_cmp_lt_i32_e64 s[96:97], s27, v239
	s_waitcnt lgkmcnt(0)
	v_cndmask_b32_e64 v200, 0, v241, s[82:83]
	v_cndmask_b32_e64 v204, 0, v241, s[84:85]
	v_cndmask_b32_e64 v208, 0, v241, s[86:87]
	v_cndmask_b32_e64 v212, 0, v241, s[88:89]
	v_cndmask_b32_e64 v216, 0, v241, s[90:91]
	v_cndmask_b32_e64 v220, 0, v241, s[92:93]
	v_cndmask_b32_e64 v224, 0, v241, s[94:95]
	v_cndmask_b32_e64 v228, 0, v241, s[96:97]
	v_add_u32_e32 v200, v200, v242
	v_add_u32_e32 v204, v204, v242
	v_add_u32_e32 v208, v208, v242
	v_add_u32_e32 v212, v212, v242
	v_add_u32_e32 v216, v216, v242
	v_add_u32_e32 v220, v220, v242
	v_add_u32_e32 v224, v224, v242
	v_add_u32_e32 v228, v228, v242
	ds_read_b128 v[18:21], v149
	global_load_dwordx4 v[200:203], v200, s[4:5]
	ds_read_b128 v[22:25], v149 offset:1088
	global_load_dwordx4 v[204:207], v204, s[4:5]
	ds_read_b128 v[26:29], v149 offset:2176
	global_load_dwordx4 v[208:211], v208, s[4:5]
	ds_read_b128 v[30:33], v149 offset:3264
	global_load_dwordx4 v[212:215], v212, s[4:5]
	ds_read_b128 v[2:5], v149 offset:4352
	global_load_dwordx4 v[216:219], v216, s[4:5]
	ds_read_b128 v[6:9], v149 offset:5440
	global_load_dwordx4 v[220:223], v220, s[4:5]
	ds_read_b128 v[10:13], v149 offset:6528
	global_load_dwordx4 v[224:227], v224, s[4:5]
	ds_read_b128 v[14:17], v149 offset:7616
	global_load_dwordx4 v[228:231], v228, s[4:5]
	v_lshl_add_u32 v232, v232, 11, v243
	v_lshl_add_u32 v233, v233, 11, v243
	v_lshl_add_u32 v234, v234, 11, v243
	v_lshl_add_u32 v235, v235, 11, v243
	v_lshl_add_u32 v236, v236, 11, v243
	v_lshl_add_u32 v237, v237, 11, v243
	v_lshl_add_u32 v238, v238, 11, v243
	v_lshl_add_u32 v239, v239, 11, v243
	s_waitcnt vmcnt(7) lgkmcnt(7)
	v_mul_f32_e32 v18, v18, v200
	v_mul_f32_e32 v19, v19, v201
	v_mul_f32_e32 v20, v20, v202
	v_mul_f32_e32 v21, v21, v203
	v_cvt_pk_bf16_f32 v18, v18, v19
	v_cvt_pk_bf16_f32 v19, v20, v21
	global_store_dwordx2 v232, v[18:19], s[6:7] sc1
	s_waitcnt vmcnt(7) lgkmcnt(6)
	v_mul_f32_e32 v22, v22, v204
	v_mul_f32_e32 v23, v23, v205
	v_mul_f32_e32 v24, v24, v206
	v_mul_f32_e32 v25, v25, v207
	v_cvt_pk_bf16_f32 v22, v22, v23
	v_cvt_pk_bf16_f32 v23, v24, v25
	global_store_dwordx2 v233, v[22:23], s[6:7] sc1
	s_waitcnt vmcnt(7) lgkmcnt(5)
	v_mul_f32_e32 v26, v26, v208
	v_mul_f32_e32 v27, v27, v209
	v_mul_f32_e32 v28, v28, v210
	v_mul_f32_e32 v29, v29, v211
	v_cvt_pk_bf16_f32 v26, v26, v27
	v_cvt_pk_bf16_f32 v27, v28, v29
	global_store_dwordx2 v234, v[26:27], s[6:7] sc1
	s_waitcnt vmcnt(7) lgkmcnt(4)
	v_mul_f32_e32 v30, v30, v212
	v_mul_f32_e32 v31, v31, v213
	v_mul_f32_e32 v32, v32, v214
	v_mul_f32_e32 v33, v33, v215
	v_cvt_pk_bf16_f32 v30, v30, v31
	v_cvt_pk_bf16_f32 v31, v32, v33
	global_store_dwordx2 v235, v[30:31], s[6:7] sc1
	s_waitcnt vmcnt(7) lgkmcnt(3)
	v_mul_f32_e32 v2, v2, v216
	v_mul_f32_e32 v3, v3, v217
	v_mul_f32_e32 v4, v4, v218
	v_mul_f32_e32 v5, v5, v219
	v_cvt_pk_bf16_f32 v2, v2, v3
	v_cvt_pk_bf16_f32 v3, v4, v5
	global_store_dwordx2 v236, v[2:3], s[6:7] sc1
	s_waitcnt vmcnt(7) lgkmcnt(2)
	v_mul_f32_e32 v6, v6, v220
	v_mul_f32_e32 v7, v7, v221
	v_mul_f32_e32 v8, v8, v222
	v_mul_f32_e32 v9, v9, v223
	v_cvt_pk_bf16_f32 v6, v6, v7
	v_cvt_pk_bf16_f32 v7, v8, v9
	global_store_dwordx2 v237, v[6:7], s[6:7] sc1
	s_waitcnt vmcnt(7) lgkmcnt(1)
	v_mul_f32_e32 v10, v10, v224
	v_mul_f32_e32 v11, v11, v225
	v_mul_f32_e32 v12, v12, v226
	v_mul_f32_e32 v13, v13, v227
	v_cvt_pk_bf16_f32 v10, v10, v11
	v_cvt_pk_bf16_f32 v11, v12, v13
	global_store_dwordx2 v238, v[10:11], s[6:7] sc1
	s_waitcnt vmcnt(7) lgkmcnt(0)
	v_mul_f32_e32 v14, v14, v228
	v_mul_f32_e32 v15, v15, v229
	v_mul_f32_e32 v16, v16, v230
	v_mul_f32_e32 v17, v17, v231
	v_cvt_pk_bf16_f32 v14, v14, v15
	v_cvt_pk_bf16_f32 v15, v16, v17
	global_store_dwordx2 v239, v[14:15], s[6:7] sc1
	s_waitcnt lgkmcnt(0)
	s_load_dword s10, s[8:9], 0x0
	s_waitcnt lgkmcnt(0)
	s_add_i32 s28, s10, s28
	s_cmpk_lt_i32 s28, 0x200
	s_cbranch_scc1 .LBB0_489

.LBB0_626:
	s_ashr_i32 s4, s56, 31
	s_lshr_b32 s4, s4, 26
	s_add_i32 s4, s56, s4
	s_ashr_i32 s6, s4, 6
	s_and_b32 s4, s4, 0x3ffffc0
	s_sub_i32 s4, s56, s4
	s_mulk_i32 s4, 0xc0
	v_add_u32_e32 v2, s4, v147
	s_lshr_b32 s7, s4, 6
	s_lshl_b32 s5, s6, 7
	v_ashrrev_i32_e32 v3, 31, v2
	s_add_i32 s7, s7, s6
	v_lshlrev_b64 v[2:3], 11, v[2:3]
	v_or_b32_e32 v4, s5, v147
	s_lshl_b32 s6, s7, 6
	s_lshl_b32 s7, s7, 7
	v_ashrrev_i32_e32 v5, 31, v4
	v_lshl_add_u64 v[138:139], v[100:101], 0, v[2:3]
	s_and_b32 s12, s7, 0x780
	v_readfirstlane_b32 s7, v149
	v_lshlrev_b64 v[4:5], 11, v[4:5]
	v_lshl_add_u64 v[2:3], v[138:139], 0, s[12:13]
	s_mov_b32 m0, s7
	v_readfirstlane_b32 s7, v172
	v_lshl_add_u64 v[140:141], v[102:103], 0, v[4:5]
	s_getreg_b32 s83, hwreg(HW_REG_HW_ID, 0, 4)
	s_bitcmp1_b32 s83, 0
	s_cbranch_scc0 .Lgm_ph7_noprio
	s_setprio 1
.Lgm_ph7_noprio:
	s_waitcnt vmcnt(0)
	s_barrier
	s_load_dwordx2 s[66:67], s[0:1], 0x90
	s_load_dwordx2 s[68:69], s[0:1], 0xd8
	v_and_b32_e32 v201, 0x3ff, v0
	v_readfirstlane_b32 s80, v0
	v_and_b32_e32 v200, 31, v201
	v_bfe_u32 v214, v201, 1, 3
	v_bfe_u32 v213, v201, 5, 1
	v_xor_b32_e32 v214, v214, v213
	v_lshlrev_b32_e32 v214, 4, v214
	s_and_b32 s80, s80, 0x3ff
	s_lshr_b32 s83, s80, 6
	s_lshl_b32 s80, s80, 4
	s_lshr_b32 s84, s83, 1
	s_and_b32 s83, s83, 1
	s_mul_i32 s84, s84, 0x3000
	s_lshl_b32 s83, s83, 13
	s_add_u32 s83, s83, 0xc000
	v_lshlrev_b32_e32 v200, 7, v200
	v_or_b32_e32 v200, v200, v214
	v_add_u32_e32 v215, s84, v200
	v_add_u32_e32 v211, s83, v200
	v_xor_b32_e32 v214, 0x20, v215
	v_xor_b32_e32 v210, 0x20, v211
	v_xor_b32_e32 v213, 0x40, v215
	v_xor_b32_e32 v209, 0x40, v211
	v_xor_b32_e32 v212, 0x60, v215
	v_xor_b32_e32 v208, 0x60, v211
	v_bfe_u32 v200, v201, 4, 3
	v_and_b32_e32 v206, 7, v201
	v_xor_b32_e32 v200, v200, v206
	v_lshlrev_b32_e32 v200, 4, v200
	v_lshrrev_b32_e32 v206, 3, v201
	v_lshl_or_b32 v207, v206, 11, v200
	v_add_u32_e32 v206, 0x10000, v207
	v_add_u32_e32 v205, 0x20000, v207
	v_add_u32_e32 v204, 0x30000, v207
	v_add_u32_e32 v203, 0x40000, v207
	v_add_u32_e32 v202, 0x50000, v207
	s_lshr_b32 s83, s56, 6
	s_and_b32 s84, s56, 63
	s_mov_b32 s79, 0
	s_mul_i32 s84, s84, 0x60000
	s_lshl_b32 s83, s83, 18
	s_waitcnt lgkmcnt(0)
	s_add_u32 s66, s66, s84
	s_addc_u32 s67, s67, 0
	s_add_u32 s68, s68, s83
	s_addc_u32 s69, s69, 0
	s_add_u32 s83, s79, 0
	s_and_b32 s83, s83, 15
	s_lshl_b32 s83, s83, 7
	s_add_u32 s70, s66, s83
	s_addc_u32 s71, s67, 0
	s_add_u32 s72, s68, s83
	s_addc_u32 s73, s69, 0
	s_add_u32 s81, s80, 0x0
	s_add_u32 s82, s80, 0xc000
	s_add_u32 m0, s81, 0x0
	s_nop 0
	global_load_lds_dwordx4 v207, s[70:71]
	s_add_u32 m0, s81, 0x1000
	s_nop 0
	global_load_lds_dwordx4 v206, s[70:71]
	s_add_u32 m0, s81, 0x2000
	s_nop 0
	global_load_lds_dwordx4 v205, s[70:71]
	s_add_u32 m0, s81, 0x3000
	s_nop 0
	global_load_lds_dwordx4 v204, s[70:71]
	s_add_u32 m0, s81, 0x4000
	s_nop 0
	global_load_lds_dwordx4 v203, s[70:71]
	s_add_u32 m0, s81, 0x5000
	s_nop 0
	global_load_lds_dwordx4 v202, s[70:71]
	s_add_u32 m0, s82, 0x0
	s_nop 0
	global_load_lds_dwordx4 v207, s[72:73]
	s_add_u32 m0, s82, 0x1000
	s_nop 0
	global_load_lds_dwordx4 v206, s[72:73]
	s_add_u32 m0, s82, 0x2000
	s_nop 0
	global_load_lds_dwordx4 v205, s[72:73]
	s_add_u32 m0, s82, 0x3000
	s_nop 0
	global_load_lds_dwordx4 v204, s[72:73]
	s_add_u32 s83, s79, 1
	s_and_b32 s83, s83, 15
	s_lshl_b32 s83, s83, 7
	s_add_u32 s70, s66, s83
	s_addc_u32 s71, s67, 0
	s_add_u32 s72, s68, s83
	s_addc_u32 s73, s69, 0
	s_add_u32 s81, s80, 0x6000
	s_add_u32 s82, s80, 0x10000
	s_add_u32 m0, s81, 0x0
	s_nop 0
	global_load_lds_dwordx4 v207, s[70:71]
	s_add_u32 m0, s81, 0x1000
	s_nop 0
	global_load_lds_dwordx4 v206, s[70:71]
	s_add_u32 m0, s81, 0x2000
	s_nop 0
	global_load_lds_dwordx4 v205, s[70:71]
	s_add_u32 m0, s81, 0x3000
	s_nop 0
	global_load_lds_dwordx4 v204, s[70:71]
	s_add_u32 m0, s81, 0x4000
	s_nop 0
	global_load_lds_dwordx4 v203, s[70:71]
	v_mov_b32_e32 v2, 0
	v_mov_b32_e32 v3, 0
	v_mov_b32_e32 v4, 0
	v_mov_b32_e32 v5, 0
	v_mov_b32_e32 v6, 0
	v_mov_b32_e32 v7, 0
	v_mov_b32_e32 v8, 0
	v_mov_b32_e32 v9, 0
	v_mov_b32_e32 v10, 0
	v_mov_b32_e32 v11, 0
	v_mov_b32_e32 v12, 0
	v_mov_b32_e32 v13, 0
	v_mov_b32_e32 v14, 0
	v_mov_b32_e32 v15, 0
	v_mov_b32_e32 v16, 0
	v_mov_b32_e32 v17, 0
	v_mov_b32_e32 v18, 0
	v_mov_b32_e32 v19, 0
	v_mov_b32_e32 v20, 0
	v_mov_b32_e32 v21, 0
	v_mov_b32_e32 v22, 0
	v_mov_b32_e32 v23, 0
	v_mov_b32_e32 v24, 0
	v_mov_b32_e32 v25, 0
	v_mov_b32_e32 v26, 0
	v_mov_b32_e32 v27, 0
	v_mov_b32_e32 v28, 0
	v_mov_b32_e32 v29, 0
	v_mov_b32_e32 v30, 0
	v_mov_b32_e32 v31, 0
	v_mov_b32_e32 v32, 0
	v_mov_b32_e32 v33, 0
	v_mov_b32_e32 v34, 0
	v_mov_b32_e32 v35, 0
	v_mov_b32_e32 v36, 0
	v_mov_b32_e32 v37, 0
	v_mov_b32_e32 v38, 0
	v_mov_b32_e32 v39, 0
	v_mov_b32_e32 v40, 0
	v_mov_b32_e32 v41, 0
	v_mov_b32_e32 v42, 0
	v_mov_b32_e32 v43, 0
	v_mov_b32_e32 v44, 0
	v_mov_b32_e32 v45, 0
	v_mov_b32_e32 v46, 0
	v_mov_b32_e32 v47, 0
	v_mov_b32_e32 v48, 0
	v_mov_b32_e32 v49, 0
	v_mov_b32_e32 v50, 0
	v_mov_b32_e32 v51, 0
	v_mov_b32_e32 v52, 0
	v_mov_b32_e32 v53, 0
	v_mov_b32_e32 v54, 0
	v_mov_b32_e32 v55, 0
	v_mov_b32_e32 v56, 0
	v_mov_b32_e32 v57, 0
	v_mov_b32_e32 v58, 0
	v_mov_b32_e32 v59, 0
	v_mov_b32_e32 v60, 0
	v_mov_b32_e32 v61, 0
	v_mov_b32_e32 v62, 0
	v_mov_b32_e32 v63, 0
	v_mov_b32_e32 v64, 0
	v_mov_b32_e32 v65, 0
	v_mov_b32_e32 v66, 0
	v_mov_b32_e32 v67, 0
	v_mov_b32_e32 v68, 0
	v_mov_b32_e32 v69, 0
	v_mov_b32_e32 v70, 0
	v_mov_b32_e32 v71, 0
	v_mov_b32_e32 v72, 0
	v_mov_b32_e32 v73, 0
	v_mov_b32_e32 v74, 0
	v_mov_b32_e32 v75, 0
	v_mov_b32_e32 v76, 0
	v_mov_b32_e32 v77, 0
	v_mov_b32_e32 v78, 0
	v_mov_b32_e32 v79, 0
	v_mov_b32_e32 v80, 0
	v_mov_b32_e32 v81, 0
	v_mov_b32_e32 v82, 0
	v_mov_b32_e32 v83, 0
	v_mov_b32_e32 v84, 0
	v_mov_b32_e32 v85, 0
	v_mov_b32_e32 v86, 0
	v_mov_b32_e32 v87, 0
	v_mov_b32_e32 v88, 0
	v_mov_b32_e32 v89, 0
	v_mov_b32_e32 v90, 0
	v_mov_b32_e32 v91, 0
	v_mov_b32_e32 v92, 0
	v_mov_b32_e32 v93, 0
	v_mov_b32_e32 v94, 0
	v_mov_b32_e32 v95, 0
	v_mov_b32_e32 v96, 0
	v_mov_b32_e32 v97, 0
	s_waitcnt vmcnt(5)
	s_barrier
	ds_read_b128 v[240:243], v211 offset:0
	ds_read_b128 v[252:255], v215 offset:0
	ds_read_b128 v[236:239], v211 offset:4096
	ds_read_b128 v[248:251], v215 offset:4096
	ds_read_b128 v[244:247], v215 offset:8192
	s_mov_b32 s78, 0
.Lgm_ph7_loop:
	s_waitcnt lgkmcnt(1)
	v_mfma_f32_32x32x16_bf16 v[82:97], v[240:243], v[252:255], v[82:97]
	ds_read_b128 v[220:223], v210 offset:0
	s_add_u32 m0, s81, 0x5000
	s_nop 0
	global_load_lds_dwordx4 v202, s[70:71]
	v_mfma_f32_32x32x16_bf16 v[66:81], v[236:239], v[252:255], v[66:81]
	ds_read_b128 v[232:235], v214 offset:0
	s_add_u32 m0, s82, 0x0
	s_nop 0
	global_load_lds_dwordx4 v207, s[72:73]
	v_mfma_f32_32x32x16_bf16 v[50:65], v[240:243], v[248:251], v[50:65]
	ds_read_b128 v[216:219], v210 offset:4096
	s_add_u32 m0, s82, 0x1000
	s_nop 0
	global_load_lds_dwordx4 v206, s[72:73]
	v_mfma_f32_32x32x16_bf16 v[34:49], v[236:239], v[248:251], v[34:49]
	ds_read_b128 v[228:231], v214 offset:4096
	s_add_u32 m0, s82, 0x2000
	s_nop 0
	global_load_lds_dwordx4 v205, s[72:73]
	s_waitcnt lgkmcnt(4)
	v_mfma_f32_32x32x16_bf16 v[18:33], v[240:243], v[244:247], v[18:33]
	ds_read_b128 v[224:227], v214 offset:8192
	v_mfma_f32_32x32x16_bf16 v[2:17], v[236:239], v[244:247], v[2:17]
	s_add_u32 m0, s82, 0x3000
	s_nop 0
	global_load_lds_dwordx4 v204, s[72:73]
	s_waitcnt lgkmcnt(1)
	v_mfma_f32_32x32x16_bf16 v[82:97], v[220:223], v[232:235], v[82:97]
	ds_read_b128 v[240:243], v209 offset:0
	v_mfma_f32_32x32x16_bf16 v[66:81], v[216:219], v[232:235], v[66:81]
	ds_read_b128 v[252:255], v213 offset:0
	v_mfma_f32_32x32x16_bf16 v[50:65], v[220:223], v[228:231], v[50:65]
	ds_read_b128 v[236:239], v209 offset:4096
	v_mfma_f32_32x32x16_bf16 v[34:49], v[216:219], v[228:231], v[34:49]
	ds_read_b128 v[248:251], v213 offset:4096
	s_waitcnt lgkmcnt(4)
	v_mfma_f32_32x32x16_bf16 v[18:33], v[220:223], v[224:227], v[18:33]
	ds_read_b128 v[244:247], v213 offset:8192
	v_mfma_f32_32x32x16_bf16 v[2:17], v[216:219], v[224:227], v[2:17]
	s_waitcnt lgkmcnt(1)
	v_mfma_f32_32x32x16_bf16 v[82:97], v[240:243], v[252:255], v[82:97]
	ds_read_b128 v[220:223], v208 offset:0
	s_add_u32 s83, s79, s78
	s_add_u32 s83, s83, 2
	s_and_b32 s83, s83, 15
	v_mfma_f32_32x32x16_bf16 v[66:81], v[236:239], v[252:255], v[66:81]
	ds_read_b128 v[232:235], v212 offset:0
	s_lshl_b32 s83, s83, 7
	s_add_u32 s70, s66, s83
	v_mfma_f32_32x32x16_bf16 v[50:65], v[240:243], v[248:251], v[50:65]
	ds_read_b128 v[216:219], v208 offset:4096
	s_addc_u32 s71, s67, 0
	s_add_u32 s72, s68, s83
	v_mfma_f32_32x32x16_bf16 v[34:49], v[236:239], v[248:251], v[34:49]
	ds_read_b128 v[228:231], v212 offset:4096
	s_addc_u32 s73, s69, 0
	s_add_u32 s81, s80, 0x0
	s_add_u32 s82, s80, 0xc000
	s_waitcnt lgkmcnt(4)
	v_mfma_f32_32x32x16_bf16 v[18:33], v[240:243], v[244:247], v[18:33]
	ds_read_b128 v[224:227], v212 offset:8192
	v_mfma_f32_32x32x16_bf16 v[2:17], v[236:239], v[244:247], v[2:17]
	s_waitcnt vmcnt(0) lgkmcnt(0)
	s_barrier
	v_mfma_f32_32x32x16_bf16 v[82:97], v[220:223], v[232:235], v[82:97]
	s_add_u32 m0, s81, 0x0
	ds_read_b128 v[240:243], v211 offset:16384
	global_load_lds_dwordx4 v207, s[70:71]
	v_mfma_f32_32x32x16_bf16 v[66:81], v[216:219], v[232:235], v[66:81]
	s_add_u32 m0, s81, 0x1000
	ds_read_b128 v[252:255], v215 offset:24576
	global_load_lds_dwordx4 v206, s[70:71]
	v_mfma_f32_32x32x16_bf16 v[50:65], v[220:223], v[228:231], v[50:65]
	s_add_u32 m0, s81, 0x2000
	ds_read_b128 v[236:239], v211 offset:20480
	global_load_lds_dwordx4 v205, s[70:71]
	v_mfma_f32_32x32x16_bf16 v[34:49], v[216:219], v[228:231], v[34:49]
	s_add_u32 m0, s81, 0x3000
	ds_read_b128 v[248:251], v215 offset:28672
	global_load_lds_dwordx4 v204, s[70:71]
	v_mfma_f32_32x32x16_bf16 v[18:33], v[220:223], v[224:227], v[18:33]
	s_add_u32 m0, s81, 0x4000
	ds_read_b128 v[244:247], v215 offset:32768
	global_load_lds_dwordx4 v203, s[70:71]
	v_mfma_f32_32x32x16_bf16 v[2:17], v[216:219], v[224:227], v[2:17]
	s_waitcnt lgkmcnt(1)
	v_mfma_f32_32x32x16_bf16 v[82:97], v[240:243], v[252:255], v[82:97]
	ds_read_b128 v[220:223], v210 offset:16384
	s_add_u32 m0, s81, 0x5000
	s_nop 0
	global_load_lds_dwordx4 v202, s[70:71]
	v_mfma_f32_32x32x16_bf16 v[66:81], v[236:239], v[252:255], v[66:81]
	ds_read_b128 v[232:235], v214 offset:24576
	s_add_u32 m0, s82, 0x0
	s_nop 0
	global_load_lds_dwordx4 v207, s[72:73]
	v_mfma_f32_32x32x16_bf16 v[50:65], v[240:243], v[248:251], v[50:65]
	ds_read_b128 v[216:219], v210 offset:20480
	s_add_u32 m0, s82, 0x1000
	s_nop 0
	global_load_lds_dwordx4 v206, s[72:73]
	v_mfma_f32_32x32x16_bf16 v[34:49], v[236:239], v[248:251], v[34:49]
	ds_read_b128 v[228:231], v214 offset:28672
	s_add_u32 m0, s82, 0x2000
	s_nop 0
	global_load_lds_dwordx4 v205, s[72:73]
	s_waitcnt lgkmcnt(4)
	v_mfma_f32_32x32x16_bf16 v[18:33], v[240:243], v[244:247], v[18:33]
	ds_read_b128 v[224:227], v214 offset:32768
	v_mfma_f32_32x32x16_bf16 v[2:17], v[236:239], v[244:247], v[2:17]
	s_add_u32 m0, s82, 0x3000
	s_nop 0
	global_load_lds_dwordx4 v204, s[72:73]
	s_waitcnt lgkmcnt(1)
	v_mfma_f32_32x32x16_bf16 v[82:97], v[220:223], v[232:235], v[82:97]
	ds_read_b128 v[240:243], v209 offset:16384
	v_mfma_f32_32x32x16_bf16 v[66:81], v[216:219], v[232:235], v[66:81]
	ds_read_b128 v[252:255], v213 offset:24576
	v_mfma_f32_32x32x16_bf16 v[50:65], v[220:223], v[228:231], v[50:65]
	ds_read_b128 v[236:239], v209 offset:20480
	v_mfma_f32_32x32x16_bf16 v[34:49], v[216:219], v[228:231], v[34:49]
	ds_read_b128 v[248:251], v213 offset:28672
	s_waitcnt lgkmcnt(4)
	v_mfma_f32_32x32x16_bf16 v[18:33], v[220:223], v[224:227], v[18:33]
	ds_read_b128 v[244:247], v213 offset:32768
	v_mfma_f32_32x32x16_bf16 v[2:17], v[216:219], v[224:227], v[2:17]
	s_waitcnt lgkmcnt(1)
	v_mfma_f32_32x32x16_bf16 v[82:97], v[240:243], v[252:255], v[82:97]
	ds_read_b128 v[220:223], v208 offset:16384
	s_add_u32 s83, s79, s78
	s_add_u32 s83, s83, 3
	s_and_b32 s83, s83, 15
	v_mfma_f32_32x32x16_bf16 v[66:81], v[236:239], v[252:255], v[66:81]
	ds_read_b128 v[232:235], v212 offset:24576
	s_lshl_b32 s83, s83, 7
	s_add_u32 s70, s66, s83
	v_mfma_f32_32x32x16_bf16 v[50:65], v[240:243], v[248:251], v[50:65]
	ds_read_b128 v[216:219], v208 offset:20480
	s_addc_u32 s71, s67, 0
	s_add_u32 s72, s68, s83
	v_mfma_f32_32x32x16_bf16 v[34:49], v[236:239], v[248:251], v[34:49]
	ds_read_b128 v[228:231], v212 offset:28672
	s_addc_u32 s73, s69, 0
	s_add_u32 s81, s80, 0x6000
	s_add_u32 s82, s80, 0x10000
	s_waitcnt lgkmcnt(4)
	v_mfma_f32_32x32x16_bf16 v[18:33], v[240:243], v[244:247], v[18:33]
	ds_read_b128 v[224:227], v212 offset:32768
	v_mfma_f32_32x32x16_bf16 v[2:17], v[236:239], v[244:247], v[2:17]
	s_waitcnt vmcnt(0) lgkmcnt(0)
	s_barrier
	v_mfma_f32_32x32x16_bf16 v[82:97], v[220:223], v[232:235], v[82:97]
	s_add_u32 m0, s81, 0x0
	ds_read_b128 v[240:243], v211 offset:0
	global_load_lds_dwordx4 v207, s[70:71]
	v_mfma_f32_32x32x16_bf16 v[66:81], v[216:219], v[232:235], v[66:81]
	s_add_u32 m0, s81, 0x1000
	ds_read_b128 v[252:255], v215 offset:0
	global_load_lds_dwordx4 v206, s[70:71]
	v_mfma_f32_32x32x16_bf16 v[50:65], v[220:223], v[228:231], v[50:65]
	s_add_u32 m0, s81, 0x2000
	ds_read_b128 v[236:239], v211 offset:4096
	global_load_lds_dwordx4 v205, s[70:71]
	v_mfma_f32_32x32x16_bf16 v[34:49], v[216:219], v[228:231], v[34:49]
	s_add_u32 m0, s81, 0x3000
	ds_read_b128 v[248:251], v215 offset:4096
	global_load_lds_dwordx4 v204, s[70:71]
	v_mfma_f32_32x32x16_bf16 v[18:33], v[220:223], v[224:227], v[18:33]
	s_add_u32 m0, s81, 0x4000
	ds_read_b128 v[244:247], v215 offset:8192
	global_load_lds_dwordx4 v203, s[70:71]
	v_mfma_f32_32x32x16_bf16 v[2:17], v[216:219], v[224:227], v[2:17]
	s_add_u32 s78, s78, 2
	s_cmp_lt_u32 s78, 14
	s_cbranch_scc1 .Lgm_ph7_loop
	s_waitcnt lgkmcnt(1)
	v_mfma_f32_32x32x16_bf16 v[82:97], v[240:243], v[252:255], v[82:97]
	ds_read_b128 v[220:223], v210 offset:0
	s_add_u32 m0, s81, 0x5000
	s_nop 0
	global_load_lds_dwordx4 v202, s[70:71]
	v_mfma_f32_32x32x16_bf16 v[66:81], v[236:239], v[252:255], v[66:81]
	ds_read_b128 v[232:235], v214 offset:0
	s_add_u32 m0, s82, 0x0
	s_nop 0
	global_load_lds_dwordx4 v207, s[72:73]
	v_mfma_f32_32x32x16_bf16 v[50:65], v[240:243], v[248:251], v[50:65]
	ds_read_b128 v[216:219], v210 offset:4096
	s_add_u32 m0, s82, 0x1000
	s_nop 0
	global_load_lds_dwordx4 v206, s[72:73]
	v_mfma_f32_32x32x16_bf16 v[34:49], v[236:239], v[248:251], v[34:49]
	ds_read_b128 v[228:231], v214 offset:4096
	s_add_u32 m0, s82, 0x2000
	s_nop 0
	global_load_lds_dwordx4 v205, s[72:73]
	s_waitcnt lgkmcnt(4)
	v_mfma_f32_32x32x16_bf16 v[18:33], v[240:243], v[244:247], v[18:33]
	ds_read_b128 v[224:227], v214 offset:8192
	v_mfma_f32_32x32x16_bf16 v[2:17], v[236:239], v[244:247], v[2:17]
	s_add_u32 m0, s82, 0x3000
	s_nop 0
	global_load_lds_dwordx4 v204, s[72:73]
	s_waitcnt lgkmcnt(1)
	v_mfma_f32_32x32x16_bf16 v[82:97], v[220:223], v[232:235], v[82:97]
	ds_read_b128 v[240:243], v209 offset:0
	v_mfma_f32_32x32x16_bf16 v[66:81], v[216:219], v[232:235], v[66:81]
	ds_read_b128 v[252:255], v213 offset:0
	v_mfma_f32_32x32x16_bf16 v[50:65], v[220:223], v[228:231], v[50:65]
	ds_read_b128 v[236:239], v209 offset:4096
	v_mfma_f32_32x32x16_bf16 v[34:49], v[216:219], v[228:231], v[34:49]
	ds_read_b128 v[248:251], v213 offset:4096
	s_waitcnt lgkmcnt(4)
	v_mfma_f32_32x32x16_bf16 v[18:33], v[220:223], v[224:227], v[18:33]
	ds_read_b128 v[244:247], v213 offset:8192
	v_mfma_f32_32x32x16_bf16 v[2:17], v[216:219], v[224:227], v[2:17]
	s_waitcnt lgkmcnt(1)
	v_mfma_f32_32x32x16_bf16 v[82:97], v[240:243], v[252:255], v[82:97]
	ds_read_b128 v[220:223], v208 offset:0
	v_mfma_f32_32x32x16_bf16 v[66:81], v[236:239], v[252:255], v[66:81]
	ds_read_b128 v[232:235], v212 offset:0
	v_mfma_f32_32x32x16_bf16 v[50:65], v[240:243], v[248:251], v[50:65]
	ds_read_b128 v[216:219], v208 offset:4096
	v_mfma_f32_32x32x16_bf16 v[34:49], v[236:239], v[248:251], v[34:49]
	ds_read_b128 v[228:231], v212 offset:4096
	s_waitcnt lgkmcnt(4)
	v_mfma_f32_32x32x16_bf16 v[18:33], v[240:243], v[244:247], v[18:33]
	ds_read_b128 v[224:227], v212 offset:8192
	v_mfma_f32_32x32x16_bf16 v[2:17], v[236:239], v[244:247], v[2:17]
	s_waitcnt vmcnt(0) lgkmcnt(0)
	s_barrier
	v_mfma_f32_32x32x16_bf16 v[82:97], v[220:223], v[232:235], v[82:97]
	ds_read_b128 v[240:243], v211 offset:16384
	v_mfma_f32_32x32x16_bf16 v[66:81], v[216:219], v[232:235], v[66:81]
	ds_read_b128 v[252:255], v215 offset:24576
	v_mfma_f32_32x32x16_bf16 v[50:65], v[220:223], v[228:231], v[50:65]
	ds_read_b128 v[236:239], v211 offset:20480
	v_mfma_f32_32x32x16_bf16 v[34:49], v[216:219], v[228:231], v[34:49]
	ds_read_b128 v[248:251], v215 offset:28672
	v_mfma_f32_32x32x16_bf16 v[18:33], v[220:223], v[224:227], v[18:33]
	ds_read_b128 v[244:247], v215 offset:32768
	v_mfma_f32_32x32x16_bf16 v[2:17], v[216:219], v[224:227], v[2:17]
	s_waitcnt lgkmcnt(1)
	v_mfma_f32_32x32x16_bf16 v[82:97], v[240:243], v[252:255], v[82:97]
	ds_read_b128 v[220:223], v210 offset:16384
	v_mfma_f32_32x32x16_bf16 v[66:81], v[236:239], v[252:255], v[66:81]
	ds_read_b128 v[232:235], v214 offset:24576
	v_mfma_f32_32x32x16_bf16 v[50:65], v[240:243], v[248:251], v[50:65]
	ds_read_b128 v[216:219], v210 offset:20480
	v_mfma_f32_32x32x16_bf16 v[34:49], v[236:239], v[248:251], v[34:49]
	ds_read_b128 v[228:231], v214 offset:28672
	s_waitcnt lgkmcnt(4)
	v_mfma_f32_32x32x16_bf16 v[18:33], v[240:243], v[244:247], v[18:33]
	ds_read_b128 v[224:227], v214 offset:32768
	v_mfma_f32_32x32x16_bf16 v[2:17], v[236:239], v[244:247], v[2:17]
	s_waitcnt lgkmcnt(1)
	v_mfma_f32_32x32x16_bf16 v[82:97], v[220:223], v[232:235], v[82:97]
	ds_read_b128 v[240:243], v209 offset:16384
	v_mfma_f32_32x32x16_bf16 v[66:81], v[216:219], v[232:235], v[66:81]
	ds_read_b128 v[252:255], v213 offset:24576
	v_mfma_f32_32x32x16_bf16 v[50:65], v[220:223], v[228:231], v[50:65]
	ds_read_b128 v[236:239], v209 offset:20480
	v_mfma_f32_32x32x16_bf16 v[34:49], v[216:219], v[228:231], v[34:49]
	ds_read_b128 v[248:251], v213 offset:28672
	s_waitcnt lgkmcnt(4)
	v_mfma_f32_32x32x16_bf16 v[18:33], v[220:223], v[224:227], v[18:33]
	ds_read_b128 v[244:247], v213 offset:32768
	v_mfma_f32_32x32x16_bf16 v[2:17], v[216:219], v[224:227], v[2:17]
	s_waitcnt lgkmcnt(1)
	v_mfma_f32_32x32x16_bf16 v[82:97], v[240:243], v[252:255], v[82:97]
	ds_read_b128 v[220:223], v208 offset:16384
	v_mfma_f32_32x32x16_bf16 v[66:81], v[236:239], v[252:255], v[66:81]
	ds_read_b128 v[232:235], v212 offset:24576
	v_mfma_f32_32x32x16_bf16 v[50:65], v[240:243], v[248:251], v[50:65]
	ds_read_b128 v[216:219], v208 offset:20480
	v_mfma_f32_32x32x16_bf16 v[34:49], v[236:239], v[248:251], v[34:49]
	ds_read_b128 v[228:231], v212 offset:28672
	s_waitcnt lgkmcnt(4)
	v_mfma_f32_32x32x16_bf16 v[18:33], v[240:243], v[244:247], v[18:33]
	ds_read_b128 v[224:227], v212 offset:32768
	v_mfma_f32_32x32x16_bf16 v[2:17], v[236:239], v[244:247], v[2:17]
	s_waitcnt vmcnt(0) lgkmcnt(0)
	s_barrier
	v_mfma_f32_32x32x16_bf16 v[82:97], v[220:223], v[232:235], v[82:97]
	v_mfma_f32_32x32x16_bf16 v[66:81], v[216:219], v[232:235], v[66:81]
	v_mfma_f32_32x32x16_bf16 v[50:65], v[220:223], v[228:231], v[50:65]
	v_mfma_f32_32x32x16_bf16 v[34:49], v[216:219], v[228:231], v[34:49]
	v_mfma_f32_32x32x16_bf16 v[18:33], v[220:223], v[224:227], v[18:33]
	v_mfma_f32_32x32x16_bf16 v[2:17], v[216:219], v[224:227], v[2:17]
	s_nop 7
	s_nop 7
	s_setprio 0
	s_waitcnt lgkmcnt(0)
	v_add_u32_e32 v140, s4, v154
	v_add_u32_e32 v98, 0xfffff000, v140
	v_lshrrev_b32_e32 v98, 11, v98
	v_or_b32_e32 v138, s5, v162
	v_ashrrev_i32_e32 v141, 31, v140
	v_mul_u32_u24_e32 v98, 0x900, v98
	v_and_b32_e32 v139, 0x7ff, v140
	v_cmp_lt_i32_e64 s[6:7], s48, v140
	v_cmp_gt_i32_e64 s[8:9], s3, v140
	v_add3_u32 v139, v139, v98, s49
	v_mad_i64_i32 v[152:153], s[4:5], v140, s50, 0
	v_cmp_gt_i32_e64 s[10:11], s51, v138
	v_lshlrev_b64 v[142:143], 11, v[140:141]
	v_lshlrev_b64 v[144:145], 6, v[140:141]
	s_and_saveexec_b64 s[4:5], s[10:11]
	s_cbranch_execz .LBB0_656
	v_cmp_lt_i32_e32 vcc, s52, v138
	s_and_saveexec_b64 s[40:41], vcc
	s_xor_b64 s[40:41], exec, s[40:41]
	s_cbranch_execz .LBB0_654
	v_cmp_lt_u32_e32 vcc, s53, v138
	s_and_saveexec_b64 s[42:43], vcc
	s_xor_b64 s[42:43], exec, s[42:43]
	s_cbranch_execz .LBB0_632
	v_mul_f32_e32 v98, 0xbfb8aa3b, v82
	v_exp_f32_e32 v190, v98
	v_mul_f32_e32 v98, 0xbfb8aa3b, v83
	v_exp_f32_e32 v191, v98
	v_or_b32_e32 v98, v138, v104
	v_pk_add_f32 v[190:191], v[190:191], 1.0 op_sel_hi:[1,0]
	s_nop 0
	v_div_scale_f32 v141, s[44:45], v191, v191, v83
	v_rcp_f32_e32 v192, v141
	v_div_scale_f32 v193, vcc, v83, v191, v83
	v_fma_f32 v194, -v141, v192, 1.0
	v_fmac_f32_e32 v192, v194, v192
	v_mul_f32_e32 v194, v193, v192
	v_fma_f32 v195, -v141, v194, v193
	v_fmac_f32_e32 v194, v195, v192
	v_div_scale_f32 v195, s[44:45], v190, v190, v82
	v_rcp_f32_e32 v196, v195
	v_fma_f32 v141, -v141, v194, v193
	v_div_fmas_f32 v141, v141, v192, v194
	v_mul_f32_e32 v192, 0xbfb8aa3b, v84
	v_mul_f32_e32 v193, 0xbfb8aa3b, v85
	v_exp_f32_e32 v192, v192
	v_exp_f32_e32 v193, v193
	v_div_fixup_f32 v83, v141, v191, v83
	v_fma_f32 v141, -v195, v196, 1.0
	v_fmac_f32_e32 v196, v141, v196
	v_div_scale_f32 v141, vcc, v82, v190, v82
	v_mul_f32_e32 v191, v141, v196
	v_fma_f32 v194, -v195, v191, v141
	v_pk_add_f32 v[192:193], v[192:193], 1.0 op_sel_hi:[1,0]
	v_fmac_f32_e32 v191, v194, v196
	v_div_scale_f32 v194, s[44:45], v193, v193, v85
	v_fma_f32 v141, -v195, v191, v141
	v_rcp_f32_e32 v195, v194
	v_div_fmas_f32 v141, v141, v196, v191
	v_div_fixup_f32 v82, v141, v190, v82
	v_cvt_pk_bf16_f32 v190, v82, v83
	v_fma_f32 v82, -v194, v195, 1.0
	v_fmac_f32_e32 v195, v82, v195
	v_div_scale_f32 v82, vcc, v85, v193, v85
	v_mul_f32_e32 v83, v82, v195
	v_fma_f32 v141, -v194, v83, v82
	v_fmac_f32_e32 v83, v141, v195
	v_div_scale_f32 v141, s[44:45], v192, v192, v84
	v_rcp_f32_e32 v191, v141
	v_fma_f32 v82, -v194, v83, v82
	v_div_fmas_f32 v82, v82, v195, v83
	v_div_fixup_f32 v85, v82, v193, v85
	v_fma_f32 v82, -v141, v191, 1.0
	v_fmac_f32_e32 v191, v82, v191
	v_div_scale_f32 v82, vcc, v84, v192, v84
	v_mul_f32_e32 v193, v82, v191
	v_fma_f32 v83, -v141, v193, v82
	v_fmac_f32_e32 v193, v83, v191
	v_fma_f32 v141, -v141, v193, v82
	v_mul_f32_e32 v82, 0xbfb8aa3b, v86
	v_mul_f32_e32 v83, 0xbfb8aa3b, v87
	v_exp_f32_e32 v82, v82
	v_exp_f32_e32 v83, v83
	v_div_fmas_f32 v141, v141, v191, v193
	v_div_fixup_f32 v84, v141, v192, v84
	v_cvt_pk_bf16_f32 v191, v84, v85
	v_pk_add_f32 v[84:85], v[82:83], 1.0 op_sel_hi:[1,0]
	v_lshl_add_u64 v[82:83], s[14:15], 0, v[142:143]
	v_div_scale_f32 v141, s[44:45], v85, v85, v87
	v_rcp_f32_e32 v192, v141
	v_lshl_add_u64 v[82:83], v[98:99], 1, v[82:83]
	global_store_dwordx2 v[82:83], v[190:191], off offset:-1664
	v_fma_f32 v98, -v141, v192, 1.0
	v_fmac_f32_e32 v192, v98, v192
	v_div_scale_f32 v98, vcc, v87, v85, v87
	v_mul_f32_e32 v190, v98, v192
	v_fma_f32 v191, -v141, v190, v98
	v_fmac_f32_e32 v190, v191, v192
	v_fma_f32 v98, -v141, v190, v98
	v_div_scale_f32 v141, s[44:45], v84, v84, v86
	v_rcp_f32_e32 v193, v141
	v_div_fmas_f32 v98, v98, v192, v190
	v_mul_f32_e32 v190, 0xbfb8aa3b, v88
	v_mul_f32_e32 v191, 0xbfb8aa3b, v89
	v_div_fixup_f32 v85, v98, v85, v87
	v_fma_f32 v87, -v141, v193, 1.0
	v_exp_f32_e32 v190, v190
	v_exp_f32_e32 v191, v191
	v_fmac_f32_e32 v193, v87, v193
	v_div_scale_f32 v87, vcc, v86, v84, v86
	v_mul_f32_e32 v98, v87, v193
	v_fma_f32 v192, -v141, v98, v87
	v_fmac_f32_e32 v98, v192, v193
	v_pk_add_f32 v[190:191], v[190:191], 1.0 op_sel_hi:[1,0]
	v_fma_f32 v87, -v141, v98, v87
	v_div_scale_f32 v141, s[44:45], v191, v191, v89
	v_rcp_f32_e32 v192, v141
	v_div_fmas_f32 v87, v87, v193, v98
	v_div_fixup_f32 v84, v87, v84, v86
	v_cvt_pk_bf16_f32 v84, v84, v85
	v_fma_f32 v85, -v141, v192, 1.0
	v_fmac_f32_e32 v192, v85, v192
	v_div_scale_f32 v85, vcc, v89, v191, v89
	v_mul_f32_e32 v86, v85, v192
	v_fma_f32 v87, -v141, v86, v85
	v_fmac_f32_e32 v86, v87, v192
	v_div_scale_f32 v98, s[44:45], v190, v190, v88
	v_fma_f32 v85, -v141, v86, v85
	v_rcp_f32_e32 v141, v98
	v_div_fmas_f32 v85, v85, v192, v86
	v_div_fixup_f32 v85, v85, v191, v89
	v_div_scale_f32 v89, vcc, v88, v190, v88
	v_fma_f32 v86, -v98, v141, 1.0
	v_fmac_f32_e32 v141, v86, v141
	v_mul_f32_e32 v191, v89, v141
	v_fma_f32 v86, -v98, v191, v89
	v_fmac_f32_e32 v191, v86, v141
	v_mul_f32_e32 v86, 0xbfb8aa3b, v90
	v_mul_f32_e32 v87, 0xbfb8aa3b, v91
	v_exp_f32_e32 v86, v86
	v_exp_f32_e32 v87, v87
	v_fma_f32 v89, -v98, v191, v89
	v_div_fmas_f32 v89, v89, v141, v191
	v_div_fixup_f32 v88, v89, v190, v88
	v_pk_add_f32 v[86:87], v[86:87], 1.0 op_sel_hi:[1,0]
	v_cvt_pk_bf16_f32 v85, v88, v85
	v_div_scale_f32 v98, s[44:45], v87, v87, v91
	v_rcp_f32_e32 v141, v98
	global_store_dwordx2 v[82:83], v[84:85], off offset:-1648
	v_fma_f32 v84, -v98, v141, 1.0
	v_fmac_f32_e32 v141, v84, v141
	v_div_scale_f32 v84, vcc, v91, v87, v91
	v_mul_f32_e32 v85, v84, v141
	v_fma_f32 v88, -v98, v85, v84
	v_fmac_f32_e32 v85, v88, v141
	v_div_scale_f32 v88, s[44:45], v86, v86, v90
	v_rcp_f32_e32 v89, v88
	v_fma_f32 v84, -v98, v85, v84
	v_div_fmas_f32 v84, v84, v141, v85
	v_div_fixup_f32 v87, v84, v87, v91
	v_fma_f32 v84, -v88, v89, 1.0
	v_fmac_f32_e32 v89, v84, v89
	v_mul_f32_e32 v84, 0xbfb8aa3b, v92
	v_mul_f32_e32 v85, 0xbfb8aa3b, v93
	v_exp_f32_e32 v84, v84
	v_exp_f32_e32 v85, v85
	v_div_scale_f32 v91, vcc, v90, v86, v90
	v_mul_f32_e32 v98, v91, v89
	v_fma_f32 v141, -v88, v98, v91
	v_fmac_f32_e32 v98, v141, v89
	v_pk_add_f32 v[84:85], v[84:85], 1.0 op_sel_hi:[1,0]
	v_fma_f32 v88, -v88, v98, v91
	v_div_scale_f32 v91, s[44:45], v85, v85, v93
	v_rcp_f32_e32 v141, v91
	v_div_fmas_f32 v88, v88, v89, v98
	v_div_fixup_f32 v86, v88, v86, v90
	v_cvt_pk_bf16_f32 v86, v86, v87
	v_fma_f32 v87, -v91, v141, 1.0
	v_fmac_f32_e32 v141, v87, v141
	v_div_scale_f32 v87, vcc, v93, v85, v93
	v_mul_f32_e32 v88, v87, v141
	v_fma_f32 v89, -v91, v88, v87
	v_fmac_f32_e32 v88, v89, v141
	v_div_scale_f32 v90, s[44:45], v84, v84, v92
	v_fma_f32 v87, -v91, v88, v87
	v_rcp_f32_e32 v91, v90
	v_div_fmas_f32 v87, v87, v141, v88
	v_div_fixup_f32 v85, v87, v85, v93
	v_mul_f32_e32 v89, 0xbfb8aa3b, v95
	v_fma_f32 v87, -v90, v91, 1.0
	v_fmac_f32_e32 v91, v87, v91
	v_div_scale_f32 v87, vcc, v92, v84, v92
	v_mul_f32_e32 v93, v87, v91
	v_fma_f32 v88, -v90, v93, v87
	v_fmac_f32_e32 v93, v88, v91
	v_mul_f32_e32 v88, 0xbfb8aa3b, v94
	v_exp_f32_e32 v88, v88
	v_exp_f32_e32 v89, v89
	v_fma_f32 v87, -v90, v93, v87
	v_div_fmas_f32 v87, v87, v91, v93
	v_div_fixup_f32 v84, v87, v84, v92
	v_pk_add_f32 v[88:89], v[88:89], 1.0 op_sel_hi:[1,0]
	v_cvt_pk_bf16_f32 v87, v84, v85
	v_div_scale_f32 v90, s[44:45], v89, v89, v95
	v_rcp_f32_e32 v91, v90
	global_store_dwordx2 v[82:83], v[86:87], off offset:-1632
	v_fma_f32 v84, -v90, v91, 1.0
	v_fmac_f32_e32 v91, v84, v91
	v_div_scale_f32 v84, vcc, v95, v89, v95
	v_mul_f32_e32 v85, v84, v91
	v_fma_f32 v86, -v90, v85, v84
	v_fmac_f32_e32 v85, v86, v91
	v_div_scale_f32 v86, s[44:45], v88, v88, v94
	v_rcp_f32_e32 v87, v86
	v_fma_f32 v84, -v90, v85, v84
	v_div_fmas_f32 v84, v84, v91, v85
	v_div_fixup_f32 v89, v84, v89, v95
	v_fma_f32 v84, -v86, v87, 1.0
	v_fmac_f32_e32 v87, v84, v87
	v_mul_f32_e32 v84, 0xbfb8aa3b, v96
	v_mul_f32_e32 v85, 0xbfb8aa3b, v97
	v_exp_f32_e32 v84, v84
	v_exp_f32_e32 v85, v85
	v_div_scale_f32 v90, vcc, v94, v88, v94
	v_mul_f32_e32 v91, v90, v87
	v_fma_f32 v92, -v86, v91, v90
	v_fmac_f32_e32 v91, v92, v87
	v_pk_add_f32 v[84:85], v[84:85], 1.0 op_sel_hi:[1,0]
	v_fma_f32 v86, -v86, v91, v90
	v_div_scale_f32 v90, s[44:45], v85, v85, v97
	v_rcp_f32_e32 v92, v90
	v_div_fmas_f32 v86, v86, v87, v91
	v_div_fixup_f32 v86, v86, v88, v94
	v_cvt_pk_bf16_f32 v86, v86, v89
	v_fma_f32 v87, -v90, v92, 1.0
	v_fmac_f32_e32 v92, v87, v92
	v_div_scale_f32 v87, vcc, v97, v85, v97
	v_mul_f32_e32 v88, v87, v92
	v_fma_f32 v89, -v90, v88, v87
	v_fmac_f32_e32 v88, v89, v92
	v_div_scale_f32 v89, s[44:45], v84, v84, v96
	v_fma_f32 v87, -v90, v88, v87
	v_rcp_f32_e32 v90, v89
	v_div_fmas_f32 v87, v87, v92, v88
	v_div_fixup_f32 v85, v87, v85, v97
	v_fma_f32 v87, -v89, v90, 1.0
	v_fmac_f32_e32 v90, v87, v90
	v_div_scale_f32 v87, vcc, v96, v84, v96
	v_mul_f32_e32 v88, v87, v90
	v_fma_f32 v91, -v89, v88, v87
	v_fmac_f32_e32 v88, v91, v90
	v_fma_f32 v87, -v89, v88, v87
	v_div_fmas_f32 v87, v87, v90, v88
	v_div_fixup_f32 v84, v87, v84, v96
	v_cvt_pk_bf16_f32 v87, v84, v85
	global_store_dwordx2 v[82:83], v[86:87], off offset:-1616

.Lgm_ph11_noprio:
	s_waitcnt vmcnt(0)
	s_barrier
	s_load_dwordx2 s[66:67], s[0:1], 0x128
	s_load_dwordx2 s[68:69], s[0:1], 0xf0
	v_and_b32_e32 v201, 0x3ff, v0
	v_readfirstlane_b32 s80, v0
	v_and_b32_e32 v200, 31, v201
	v_bfe_u32 v214, v201, 1, 3
	v_bfe_u32 v213, v201, 5, 1
	v_xor_b32_e32 v214, v214, v213
	v_lshlrev_b32_e32 v214, 4, v214
	s_and_b32 s80, s80, 0x3ff
	s_lshr_b32 s83, s80, 6
	s_lshl_b32 s80, s80, 4
	s_lshr_b32 s84, s83, 1
	s_and_b32 s83, s83, 1
	s_mul_i32 s84, s84, 0x3000
	s_lshl_b32 s83, s83, 13
	s_add_u32 s83, s83, 0xc000
	v_lshlrev_b32_e32 v200, 7, v200
	v_or_b32_e32 v200, v200, v214
	v_add_u32_e32 v215, s84, v200
	v_add_u32_e32 v211, s83, v200
	v_xor_b32_e32 v214, 0x20, v215
	v_xor_b32_e32 v210, 0x20, v211
	v_xor_b32_e32 v213, 0x40, v215
	v_xor_b32_e32 v209, 0x40, v211
	v_xor_b32_e32 v212, 0x60, v215
	v_xor_b32_e32 v208, 0x60, v211
	v_bfe_u32 v200, v201, 4, 3
	v_and_b32_e32 v206, 7, v201
	v_xor_b32_e32 v200, v200, v206
	v_lshlrev_b32_e32 v200, 4, v200
	v_lshrrev_b32_e32 v206, 3, v201
	v_lshl_or_b32 v207, v206, 11, v200
	v_add_u32_e32 v206, 0x10000, v207
	v_add_u32_e32 v205, 0x20000, v207
	v_add_u32_e32 v204, 0x30000, v207
	v_add_u32_e32 v203, 0x40000, v207
	v_add_u32_e32 v202, 0x50000, v207
	s_lshr_b32 s83, s28, 6
	s_and_b32 s84, s28, 63
	s_mov_b32 s79, 0
	s_mul_i32 s84, s84, 0x60000
	s_lshl_b32 s83, s83, 18
	s_waitcnt lgkmcnt(0)
	s_add_u32 s66, s66, s84
	s_addc_u32 s67, s67, 0
	s_add_u32 s68, s68, s83
	s_addc_u32 s69, s69, 0
	s_add_u32 s83, s79, 0
	s_and_b32 s83, s83, 15
	s_lshl_b32 s83, s83, 7
	s_add_u32 s70, s66, s83
	s_addc_u32 s71, s67, 0
	s_add_u32 s72, s68, s83
	s_addc_u32 s73, s69, 0
	s_add_u32 s81, s80, 0x0
	s_add_u32 s82, s80, 0xc000
	s_add_u32 m0, s81, 0x0
	s_nop 0
	global_load_lds_dwordx4 v207, s[70:71]
	s_add_u32 m0, s81, 0x1000
	s_nop 0
	global_load_lds_dwordx4 v206, s[70:71]
	s_add_u32 m0, s81, 0x2000
	s_nop 0
	global_load_lds_dwordx4 v205, s[70:71]
	s_add_u32 m0, s81, 0x3000
	s_nop 0
	global_load_lds_dwordx4 v204, s[70:71]
	s_add_u32 m0, s81, 0x4000
	s_nop 0
	global_load_lds_dwordx4 v203, s[70:71]
	s_add_u32 m0, s81, 0x5000
	s_nop 0
	global_load_lds_dwordx4 v202, s[70:71]
	s_add_u32 m0, s82, 0x0
	s_nop 0
	global_load_lds_dwordx4 v207, s[72:73]
	s_add_u32 m0, s82, 0x1000
	s_nop 0
	global_load_lds_dwordx4 v206, s[72:73]
	s_add_u32 m0, s82, 0x2000
	s_nop 0
	global_load_lds_dwordx4 v205, s[72:73]
	s_add_u32 m0, s82, 0x3000
	s_nop 0
	global_load_lds_dwordx4 v204, s[72:73]
	s_add_u32 s83, s79, 1
	s_and_b32 s83, s83, 15
	s_lshl_b32 s83, s83, 7
	s_add_u32 s70, s66, s83
	s_addc_u32 s71, s67, 0
	s_add_u32 s72, s68, s83
	s_addc_u32 s73, s69, 0
	s_add_u32 s81, s80, 0x6000
	s_add_u32 s82, s80, 0x10000
	s_add_u32 m0, s81, 0x0
	s_nop 0
	global_load_lds_dwordx4 v207, s[70:71]
	s_add_u32 m0, s81, 0x1000
	s_nop 0
	global_load_lds_dwordx4 v206, s[70:71]
	s_add_u32 m0, s81, 0x2000
	s_nop 0
	global_load_lds_dwordx4 v205, s[70:71]
	s_add_u32 m0, s81, 0x3000
	s_nop 0
	global_load_lds_dwordx4 v204, s[70:71]
	s_add_u32 m0, s81, 0x4000
	s_nop 0
	global_load_lds_dwordx4 v203, s[70:71]
	v_mov_b32_e32 v2, 0
	v_mov_b32_e32 v3, 0
	v_mov_b32_e32 v4, 0
	v_mov_b32_e32 v5, 0
	v_mov_b32_e32 v6, 0
	v_mov_b32_e32 v7, 0
	v_mov_b32_e32 v8, 0
	v_mov_b32_e32 v9, 0
	v_mov_b32_e32 v10, 0
	v_mov_b32_e32 v11, 0
	v_mov_b32_e32 v12, 0
	v_mov_b32_e32 v13, 0
	v_mov_b32_e32 v14, 0
	v_mov_b32_e32 v15, 0
	v_mov_b32_e32 v16, 0
	v_mov_b32_e32 v17, 0
	v_mov_b32_e32 v18, 0
	v_mov_b32_e32 v19, 0
	v_mov_b32_e32 v20, 0
	v_mov_b32_e32 v21, 0
	v_mov_b32_e32 v22, 0
	v_mov_b32_e32 v23, 0
	v_mov_b32_e32 v24, 0
	v_mov_b32_e32 v25, 0
	v_mov_b32_e32 v26, 0
	v_mov_b32_e32 v27, 0
	v_mov_b32_e32 v28, 0
	v_mov_b32_e32 v29, 0
	v_mov_b32_e32 v30, 0
	v_mov_b32_e32 v31, 0
	v_mov_b32_e32 v32, 0
	v_mov_b32_e32 v33, 0
	v_mov_b32_e32 v34, 0
	v_mov_b32_e32 v35, 0
	v_mov_b32_e32 v36, 0
	v_mov_b32_e32 v37, 0
	v_mov_b32_e32 v38, 0
	v_mov_b32_e32 v39, 0
	v_mov_b32_e32 v40, 0
	v_mov_b32_e32 v41, 0
	v_mov_b32_e32 v42, 0
	v_mov_b32_e32 v43, 0
	v_mov_b32_e32 v44, 0
	v_mov_b32_e32 v45, 0
	v_mov_b32_e32 v46, 0
	v_mov_b32_e32 v47, 0
	v_mov_b32_e32 v48, 0
	v_mov_b32_e32 v49, 0
	v_mov_b32_e32 v50, 0
	v_mov_b32_e32 v51, 0
	v_mov_b32_e32 v52, 0
	v_mov_b32_e32 v53, 0
	v_mov_b32_e32 v54, 0
	v_mov_b32_e32 v55, 0
	v_mov_b32_e32 v56, 0
	v_mov_b32_e32 v57, 0
	v_mov_b32_e32 v58, 0
	v_mov_b32_e32 v59, 0
	v_mov_b32_e32 v60, 0
	v_mov_b32_e32 v61, 0
	v_mov_b32_e32 v62, 0
	v_mov_b32_e32 v63, 0
	v_mov_b32_e32 v64, 0
	v_mov_b32_e32 v65, 0
	v_mov_b32_e32 v66, 0
	v_mov_b32_e32 v67, 0
	v_mov_b32_e32 v68, 0
	v_mov_b32_e32 v69, 0
	v_mov_b32_e32 v70, 0
	v_mov_b32_e32 v71, 0
	v_mov_b32_e32 v72, 0
	v_mov_b32_e32 v73, 0
	v_mov_b32_e32 v74, 0
	v_mov_b32_e32 v75, 0
	v_mov_b32_e32 v76, 0
	v_mov_b32_e32 v77, 0
	v_mov_b32_e32 v78, 0
	v_mov_b32_e32 v79, 0
	v_mov_b32_e32 v80, 0
	v_mov_b32_e32 v81, 0
	v_mov_b32_e32 v82, 0
	v_mov_b32_e32 v83, 0
	v_mov_b32_e32 v84, 0
	v_mov_b32_e32 v85, 0
	v_mov_b32_e32 v86, 0
	v_mov_b32_e32 v87, 0
	v_mov_b32_e32 v88, 0
	v_mov_b32_e32 v89, 0
	v_mov_b32_e32 v90, 0
	v_mov_b32_e32 v91, 0
	v_mov_b32_e32 v92, 0
	v_mov_b32_e32 v93, 0
	v_mov_b32_e32 v94, 0
	v_mov_b32_e32 v95, 0
	v_mov_b32_e32 v96, 0
	v_mov_b32_e32 v97, 0
	s_waitcnt vmcnt(5)
	s_barrier
	ds_read_b128 v[240:243], v211 offset:0
	ds_read_b128 v[252:255], v215 offset:0
	ds_read_b128 v[236:239], v211 offset:4096
	ds_read_b128 v[248:251], v215 offset:4096
	ds_read_b128 v[244:247], v215 offset:8192
	s_mov_b32 s78, 0
.Lgm_ph11_loop:
	s_waitcnt lgkmcnt(1)
	v_mfma_f32_32x32x16_bf16 v[82:97], v[240:243], v[252:255], v[82:97]
	ds_read_b128 v[220:223], v210 offset:0
	s_add_u32 m0, s81, 0x5000
	s_nop 0
	global_load_lds_dwordx4 v202, s[70:71]
	v_mfma_f32_32x32x16_bf16 v[66:81], v[236:239], v[252:255], v[66:81]
	ds_read_b128 v[232:235], v214 offset:0
	s_add_u32 m0, s82, 0x0
	s_nop 0
	global_load_lds_dwordx4 v207, s[72:73]
	v_mfma_f32_32x32x16_bf16 v[50:65], v[240:243], v[248:251], v[50:65]
	ds_read_b128 v[216:219], v210 offset:4096
	s_add_u32 m0, s82, 0x1000
	s_nop 0
	global_load_lds_dwordx4 v206, s[72:73]
	v_mfma_f32_32x32x16_bf16 v[34:49], v[236:239], v[248:251], v[34:49]
	ds_read_b128 v[228:231], v214 offset:4096
	s_add_u32 m0, s82, 0x2000
	s_nop 0
	global_load_lds_dwordx4 v205, s[72:73]
	s_waitcnt lgkmcnt(4)
	v_mfma_f32_32x32x16_bf16 v[18:33], v[240:243], v[244:247], v[18:33]
	ds_read_b128 v[224:227], v214 offset:8192
	v_mfma_f32_32x32x16_bf16 v[2:17], v[236:239], v[244:247], v[2:17]
	s_add_u32 m0, s82, 0x3000
	s_nop 0
	global_load_lds_dwordx4 v204, s[72:73]
	s_waitcnt lgkmcnt(1)
	v_mfma_f32_32x32x16_bf16 v[82:97], v[220:223], v[232:235], v[82:97]
	ds_read_b128 v[240:243], v209 offset:0
	v_mfma_f32_32x32x16_bf16 v[66:81], v[216:219], v[232:235], v[66:81]
	ds_read_b128 v[252:255], v213 offset:0
	v_mfma_f32_32x32x16_bf16 v[50:65], v[220:223], v[228:231], v[50:65]
	ds_read_b128 v[236:239], v209 offset:4096
	v_mfma_f32_32x32x16_bf16 v[34:49], v[216:219], v[228:231], v[34:49]
	ds_read_b128 v[248:251], v213 offset:4096
	s_waitcnt lgkmcnt(4)
	v_mfma_f32_32x32x16_bf16 v[18:33], v[220:223], v[224:227], v[18:33]
	ds_read_b128 v[244:247], v213 offset:8192
	v_mfma_f32_32x32x16_bf16 v[2:17], v[216:219], v[224:227], v[2:17]
	s_waitcnt lgkmcnt(1)
	v_mfma_f32_32x32x16_bf16 v[82:97], v[240:243], v[252:255], v[82:97]
	ds_read_b128 v[220:223], v208 offset:0
	s_add_u32 s83, s79, s78
	s_add_u32 s83, s83, 2
	s_and_b32 s83, s83, 15
	v_mfma_f32_32x32x16_bf16 v[66:81], v[236:239], v[252:255], v[66:81]
	ds_read_b128 v[232:235], v212 offset:0
	s_lshl_b32 s83, s83, 7
	s_add_u32 s70, s66, s83
	v_mfma_f32_32x32x16_bf16 v[50:65], v[240:243], v[248:251], v[50:65]
	ds_read_b128 v[216:219], v208 offset:4096
	s_addc_u32 s71, s67, 0
	s_add_u32 s72, s68, s83
	v_mfma_f32_32x32x16_bf16 v[34:49], v[236:239], v[248:251], v[34:49]
	ds_read_b128 v[228:231], v212 offset:4096
	s_addc_u32 s73, s69, 0
	s_add_u32 s81, s80, 0x0
	s_add_u32 s82, s80, 0xc000
	s_waitcnt lgkmcnt(4)
	v_mfma_f32_32x32x16_bf16 v[18:33], v[240:243], v[244:247], v[18:33]
	ds_read_b128 v[224:227], v212 offset:8192
	v_mfma_f32_32x32x16_bf16 v[2:17], v[236:239], v[244:247], v[2:17]
	s_waitcnt vmcnt(0) lgkmcnt(0)
	s_barrier
	v_mfma_f32_32x32x16_bf16 v[82:97], v[220:223], v[232:235], v[82:97]
	s_add_u32 m0, s81, 0x0
	ds_read_b128 v[240:243], v211 offset:16384
	global_load_lds_dwordx4 v207, s[70:71]
	v_mfma_f32_32x32x16_bf16 v[66:81], v[216:219], v[232:235], v[66:81]
	s_add_u32 m0, s81, 0x1000
	ds_read_b128 v[252:255], v215 offset:24576
	global_load_lds_dwordx4 v206, s[70:71]
	v_mfma_f32_32x32x16_bf16 v[50:65], v[220:223], v[228:231], v[50:65]
	s_add_u32 m0, s81, 0x2000
	ds_read_b128 v[236:239], v211 offset:20480
	global_load_lds_dwordx4 v205, s[70:71]
	v_mfma_f32_32x32x16_bf16 v[34:49], v[216:219], v[228:231], v[34:49]
	s_add_u32 m0, s81, 0x3000
	ds_read_b128 v[248:251], v215 offset:28672
	global_load_lds_dwordx4 v204, s[70:71]
	v_mfma_f32_32x32x16_bf16 v[18:33], v[220:223], v[224:227], v[18:33]
	s_add_u32 m0, s81, 0x4000
	ds_read_b128 v[244:247], v215 offset:32768
	global_load_lds_dwordx4 v203, s[70:71]
	v_mfma_f32_32x32x16_bf16 v[2:17], v[216:219], v[224:227], v[2:17]
	s_waitcnt lgkmcnt(1)
	v_mfma_f32_32x32x16_bf16 v[82:97], v[240:243], v[252:255], v[82:97]
	ds_read_b128 v[220:223], v210 offset:16384
	s_add_u32 m0, s81, 0x5000
	s_nop 0
	global_load_lds_dwordx4 v202, s[70:71]
	v_mfma_f32_32x32x16_bf16 v[66:81], v[236:239], v[252:255], v[66:81]
	ds_read_b128 v[232:235], v214 offset:24576
	s_add_u32 m0, s82, 0x0
	s_nop 0
	global_load_lds_dwordx4 v207, s[72:73]
	v_mfma_f32_32x32x16_bf16 v[50:65], v[240:243], v[248:251], v[50:65]
	ds_read_b128 v[216:219], v210 offset:20480
	s_add_u32 m0, s82, 0x1000
	s_nop 0
	global_load_lds_dwordx4 v206, s[72:73]
	v_mfma_f32_32x32x16_bf16 v[34:49], v[236:239], v[248:251], v[34:49]
	ds_read_b128 v[228:231], v214 offset:28672
	s_add_u32 m0, s82, 0x2000
	s_nop 0
	global_load_lds_dwordx4 v205, s[72:73]
	s_waitcnt lgkmcnt(4)
	v_mfma_f32_32x32x16_bf16 v[18:33], v[240:243], v[244:247], v[18:33]
	ds_read_b128 v[224:227], v214 offset:32768
	v_mfma_f32_32x32x16_bf16 v[2:17], v[236:239], v[244:247], v[2:17]
	s_add_u32 m0, s82, 0x3000
	s_nop 0
	global_load_lds_dwordx4 v204, s[72:73]
	s_waitcnt lgkmcnt(1)
	v_mfma_f32_32x32x16_bf16 v[82:97], v[220:223], v[232:235], v[82:97]
	ds_read_b128 v[240:243], v209 offset:16384
	v_mfma_f32_32x32x16_bf16 v[66:81], v[216:219], v[232:235], v[66:81]
	ds_read_b128 v[252:255], v213 offset:24576
	v_mfma_f32_32x32x16_bf16 v[50:65], v[220:223], v[228:231], v[50:65]
	ds_read_b128 v[236:239], v209 offset:20480
	v_mfma_f32_32x32x16_bf16 v[34:49], v[216:219], v[228:231], v[34:49]
	ds_read_b128 v[248:251], v213 offset:28672
	s_waitcnt lgkmcnt(4)
	v_mfma_f32_32x32x16_bf16 v[18:33], v[220:223], v[224:227], v[18:33]
	ds_read_b128 v[244:247], v213 offset:32768
	v_mfma_f32_32x32x16_bf16 v[2:17], v[216:219], v[224:227], v[2:17]
	s_waitcnt lgkmcnt(1)
	v_mfma_f32_32x32x16_bf16 v[82:97], v[240:243], v[252:255], v[82:97]
	ds_read_b128 v[220:223], v208 offset:16384
	s_add_u32 s83, s79, s78
	s_add_u32 s83, s83, 3
	s_and_b32 s83, s83, 15
	v_mfma_f32_32x32x16_bf16 v[66:81], v[236:239], v[252:255], v[66:81]
	ds_read_b128 v[232:235], v212 offset:24576
	s_lshl_b32 s83, s83, 7
	s_add_u32 s70, s66, s83
	v_mfma_f32_32x32x16_bf16 v[50:65], v[240:243], v[248:251], v[50:65]
	ds_read_b128 v[216:219], v208 offset:20480
	s_addc_u32 s71, s67, 0
	s_add_u32 s72, s68, s83
	v_mfma_f32_32x32x16_bf16 v[34:49], v[236:239], v[248:251], v[34:49]
	ds_read_b128 v[228:231], v212 offset:28672
	s_addc_u32 s73, s69, 0
	s_add_u32 s81, s80, 0x6000
	s_add_u32 s82, s80, 0x10000
	s_waitcnt lgkmcnt(4)
	v_mfma_f32_32x32x16_bf16 v[18:33], v[240:243], v[244:247], v[18:33]
	ds_read_b128 v[224:227], v212 offset:32768
	v_mfma_f32_32x32x16_bf16 v[2:17], v[236:239], v[244:247], v[2:17]
	s_waitcnt vmcnt(0) lgkmcnt(0)
	s_barrier
	v_mfma_f32_32x32x16_bf16 v[82:97], v[220:223], v[232:235], v[82:97]
	s_add_u32 m0, s81, 0x0
	ds_read_b128 v[240:243], v211 offset:0
	global_load_lds_dwordx4 v207, s[70:71]
	v_mfma_f32_32x32x16_bf16 v[66:81], v[216:219], v[232:235], v[66:81]
	s_add_u32 m0, s81, 0x1000
	ds_read_b128 v[252:255], v215 offset:0
	global_load_lds_dwordx4 v206, s[70:71]
	v_mfma_f32_32x32x16_bf16 v[50:65], v[220:223], v[228:231], v[50:65]
	s_add_u32 m0, s81, 0x2000
	ds_read_b128 v[236:239], v211 offset:4096
	global_load_lds_dwordx4 v205, s[70:71]
	v_mfma_f32_32x32x16_bf16 v[34:49], v[216:219], v[228:231], v[34:49]
	s_add_u32 m0, s81, 0x3000
	ds_read_b128 v[248:251], v215 offset:4096
	global_load_lds_dwordx4 v204, s[70:71]
	v_mfma_f32_32x32x16_bf16 v[18:33], v[220:223], v[224:227], v[18:33]
	s_add_u32 m0, s81, 0x4000
	ds_read_b128 v[244:247], v215 offset:8192
	global_load_lds_dwordx4 v203, s[70:71]
	v_mfma_f32_32x32x16_bf16 v[2:17], v[216:219], v[224:227], v[2:17]
	s_add_u32 s78, s78, 2
	s_cmp_lt_u32 s78, 14
	s_cbranch_scc1 .Lgm_ph11_loop
	s_waitcnt lgkmcnt(1)
	v_mfma_f32_32x32x16_bf16 v[82:97], v[240:243], v[252:255], v[82:97]
	ds_read_b128 v[220:223], v210 offset:0
	s_add_u32 m0, s81, 0x5000
	s_nop 0
	global_load_lds_dwordx4 v202, s[70:71]
	v_mfma_f32_32x32x16_bf16 v[66:81], v[236:239], v[252:255], v[66:81]
	ds_read_b128 v[232:235], v214 offset:0
	s_add_u32 m0, s82, 0x0
	s_nop 0
	global_load_lds_dwordx4 v207, s[72:73]
	v_mfma_f32_32x32x16_bf16 v[50:65], v[240:243], v[248:251], v[50:65]
	ds_read_b128 v[216:219], v210 offset:4096
	s_add_u32 m0, s82, 0x1000
	s_nop 0
	global_load_lds_dwordx4 v206, s[72:73]
	v_mfma_f32_32x32x16_bf16 v[34:49], v[236:239], v[248:251], v[34:49]
	ds_read_b128 v[228:231], v214 offset:4096
	s_add_u32 m0, s82, 0x2000
	s_nop 0
	global_load_lds_dwordx4 v205, s[72:73]
	s_waitcnt lgkmcnt(4)
	v_mfma_f32_32x32x16_bf16 v[18:33], v[240:243], v[244:247], v[18:33]
	ds_read_b128 v[224:227], v214 offset:8192
	v_mfma_f32_32x32x16_bf16 v[2:17], v[236:239], v[244:247], v[2:17]
	s_add_u32 m0, s82, 0x3000
	s_nop 0
	global_load_lds_dwordx4 v204, s[72:73]
	s_waitcnt lgkmcnt(1)
	v_mfma_f32_32x32x16_bf16 v[82:97], v[220:223], v[232:235], v[82:97]
	ds_read_b128 v[240:243], v209 offset:0
	v_mfma_f32_32x32x16_bf16 v[66:81], v[216:219], v[232:235], v[66:81]
	ds_read_b128 v[252:255], v213 offset:0
	v_mfma_f32_32x32x16_bf16 v[50:65], v[220:223], v[228:231], v[50:65]
	ds_read_b128 v[236:239], v209 offset:4096
	v_mfma_f32_32x32x16_bf16 v[34:49], v[216:219], v[228:231], v[34:49]
	ds_read_b128 v[248:251], v213 offset:4096
	s_waitcnt lgkmcnt(4)
	v_mfma_f32_32x32x16_bf16 v[18:33], v[220:223], v[224:227], v[18:33]
	ds_read_b128 v[244:247], v213 offset:8192
	v_mfma_f32_32x32x16_bf16 v[2:17], v[216:219], v[224:227], v[2:17]
	s_waitcnt lgkmcnt(1)
	v_mfma_f32_32x32x16_bf16 v[82:97], v[240:243], v[252:255], v[82:97]
	ds_read_b128 v[220:223], v208 offset:0
	v_mfma_f32_32x32x16_bf16 v[66:81], v[236:239], v[252:255], v[66:81]
	ds_read_b128 v[232:235], v212 offset:0
	v_mfma_f32_32x32x16_bf16 v[50:65], v[240:243], v[248:251], v[50:65]
	ds_read_b128 v[216:219], v208 offset:4096
	v_mfma_f32_32x32x16_bf16 v[34:49], v[236:239], v[248:251], v[34:49]
	ds_read_b128 v[228:231], v212 offset:4096
	s_waitcnt lgkmcnt(4)
	v_mfma_f32_32x32x16_bf16 v[18:33], v[240:243], v[244:247], v[18:33]
	ds_read_b128 v[224:227], v212 offset:8192
	v_mfma_f32_32x32x16_bf16 v[2:17], v[236:239], v[244:247], v[2:17]
	s_waitcnt vmcnt(0) lgkmcnt(0)
	s_barrier
	v_mfma_f32_32x32x16_bf16 v[82:97], v[220:223], v[232:235], v[82:97]
	ds_read_b128 v[240:243], v211 offset:16384
	v_mfma_f32_32x32x16_bf16 v[66:81], v[216:219], v[232:235], v[66:81]
	ds_read_b128 v[252:255], v215 offset:24576
	v_mfma_f32_32x32x16_bf16 v[50:65], v[220:223], v[228:231], v[50:65]
	ds_read_b128 v[236:239], v211 offset:20480
	v_mfma_f32_32x32x16_bf16 v[34:49], v[216:219], v[228:231], v[34:49]
	ds_read_b128 v[248:251], v215 offset:28672
	v_mfma_f32_32x32x16_bf16 v[18:33], v[220:223], v[224:227], v[18:33]
	ds_read_b128 v[244:247], v215 offset:32768
	v_mfma_f32_32x32x16_bf16 v[2:17], v[216:219], v[224:227], v[2:17]
	s_waitcnt lgkmcnt(1)
	v_mfma_f32_32x32x16_bf16 v[82:97], v[240:243], v[252:255], v[82:97]
	ds_read_b128 v[220:223], v210 offset:16384
	v_mfma_f32_32x32x16_bf16 v[66:81], v[236:239], v[252:255], v[66:81]
	ds_read_b128 v[232:235], v214 offset:24576
	v_mfma_f32_32x32x16_bf16 v[50:65], v[240:243], v[248:251], v[50:65]
	ds_read_b128 v[216:219], v210 offset:20480
	v_mfma_f32_32x32x16_bf16 v[34:49], v[236:239], v[248:251], v[34:49]
	ds_read_b128 v[228:231], v214 offset:28672
	s_waitcnt lgkmcnt(4)
	v_mfma_f32_32x32x16_bf16 v[18:33], v[240:243], v[244:247], v[18:33]
	ds_read_b128 v[224:227], v214 offset:32768
	v_mfma_f32_32x32x16_bf16 v[2:17], v[236:239], v[244:247], v[2:17]
	s_waitcnt lgkmcnt(1)
	v_mfma_f32_32x32x16_bf16 v[82:97], v[220:223], v[232:235], v[82:97]
	ds_read_b128 v[240:243], v209 offset:16384
	v_mfma_f32_32x32x16_bf16 v[66:81], v[216:219], v[232:235], v[66:81]
	ds_read_b128 v[252:255], v213 offset:24576
	v_mfma_f32_32x32x16_bf16 v[50:65], v[220:223], v[228:231], v[50:65]
	ds_read_b128 v[236:239], v209 offset:20480
	v_mfma_f32_32x32x16_bf16 v[34:49], v[216:219], v[228:231], v[34:49]
	ds_read_b128 v[248:251], v213 offset:28672
	s_waitcnt lgkmcnt(4)
	v_mfma_f32_32x32x16_bf16 v[18:33], v[220:223], v[224:227], v[18:33]
	ds_read_b128 v[244:247], v213 offset:32768
	v_mfma_f32_32x32x16_bf16 v[2:17], v[216:219], v[224:227], v[2:17]
	s_waitcnt lgkmcnt(1)
	v_mfma_f32_32x32x16_bf16 v[82:97], v[240:243], v[252:255], v[82:97]
	ds_read_b128 v[220:223], v208 offset:16384
	v_mfma_f32_32x32x16_bf16 v[66:81], v[236:239], v[252:255], v[66:81]
	ds_read_b128 v[232:235], v212 offset:24576
	v_mfma_f32_32x32x16_bf16 v[50:65], v[240:243], v[248:251], v[50:65]
	ds_read_b128 v[216:219], v208 offset:20480
	v_mfma_f32_32x32x16_bf16 v[34:49], v[236:239], v[248:251], v[34:49]
	ds_read_b128 v[228:231], v212 offset:28672
	s_waitcnt lgkmcnt(4)
	v_mfma_f32_32x32x16_bf16 v[18:33], v[240:243], v[244:247], v[18:33]
	ds_read_b128 v[224:227], v212 offset:32768
	v_mfma_f32_32x32x16_bf16 v[2:17], v[236:239], v[244:247], v[2:17]
	s_waitcnt vmcnt(0) lgkmcnt(0)
	s_barrier
	v_mfma_f32_32x32x16_bf16 v[82:97], v[220:223], v[232:235], v[82:97]
	v_mfma_f32_32x32x16_bf16 v[66:81], v[216:219], v[232:235], v[66:81]
	v_mfma_f32_32x32x16_bf16 v[50:65], v[220:223], v[228:231], v[50:65]
	v_mfma_f32_32x32x16_bf16 v[34:49], v[216:219], v[228:231], v[34:49]
	v_mfma_f32_32x32x16_bf16 v[18:33], v[220:223], v[224:227], v[18:33]
	v_mfma_f32_32x32x16_bf16 v[2:17], v[216:219], v[224:227], v[2:17]
	s_nop 7
	s_nop 7
	s_setprio 0
	s_waitcnt lgkmcnt(0)
	s_nop 10
	ds_write_b128 v147, v[82:85]
	ds_write_b128 v147, v[86:89] offset:32
	ds_write_b128 v147, v[90:93] offset:64
	ds_write_b128 v147, v[94:97] offset:96
	ds_write_b128 v147, v[66:69] offset:128
	ds_write_b128 v147, v[70:73] offset:160
	ds_write_b128 v147, v[74:77] offset:192
	ds_write_b128 v147, v[78:81] offset:224
	s_waitcnt lgkmcnt(0)
	v_add_u32_e32 v104, s29, v111
	v_or_b32_e32 v244, s30, v120
	v_lshlrev_b32_e32 v242, 2, v244
	v_add_u32_e32 v242, s3, v242
	v_lshlrev_b32_e32 v243, 1, v244
	v_mov_b32_e32 v240, v104
	v_add_u32_e32 v241, 0xfffff000, v240
	v_lshrrev_b32_e32 v241, 11, v241
	v_mad_u32_u24 v241, v241, s26, s26
	v_lshlrev_b32_e32 v241, 2, v241
	v_or_b32_e32 v232, v240, v119
	v_or_b32_e32 v233, v240, v121
	v_or_b32_e32 v234, v240, v122
	v_or_b32_e32 v235, v240, v123
	v_or_b32_e32 v236, v240, v124
	v_or_b32_e32 v237, v240, v125
	v_or_b32_e32 v238, v240, v126
	v_or_b32_e32 v239, v240, v127
	v_cmp_lt_i32_e64 s[82:83], s27, v232
	v_cmp_lt_i32_e64 s[84:85], s27, v233
	v_cmp_lt_i32_e64 s[86:87], s27, v234
	v_cmp_lt_i32_e64 s[88:89], s27, v235
	v_cmp_lt_i32_e64 s[90:91], s27, v236
	v_cmp_lt_i32_e64 s[92:93], s27, v237
	v_cmp_lt_i32_e64 s[94:95], s27, v238
	v_cmp_lt_i32_e64 s[96:97], s27, v239
	s_waitcnt lgkmcnt(0)
	v_cndmask_b32_e64 v200, 0, v241, s[82:83]
	v_cndmask_b32_e64 v204, 0, v241, s[84:85]
	v_cndmask_b32_e64 v208, 0, v241, s[86:87]
	v_cndmask_b32_e64 v212, 0, v241, s[88:89]
	v_cndmask_b32_e64 v216, 0, v241, s[90:91]
	v_cndmask_b32_e64 v220, 0, v241, s[92:93]
	v_cndmask_b32_e64 v224, 0, v241, s[94:95]
	v_cndmask_b32_e64 v228, 0, v241, s[96:97]
	v_add_u32_e32 v200, v200, v242
	v_add_u32_e32 v204, v204, v242
	v_add_u32_e32 v208, v208, v242
	v_add_u32_e32 v212, v212, v242
	v_add_u32_e32 v216, v216, v242
	v_add_u32_e32 v220, v220, v242
	v_add_u32_e32 v224, v224, v242
	v_add_u32_e32 v228, v228, v242
	ds_read_b128 v[82:85], v149
	global_load_dwordx4 v[200:203], v200, s[6:7]
	ds_read_b128 v[86:89], v149 offset:1088
	global_load_dwordx4 v[204:207], v204, s[6:7]
	ds_read_b128 v[90:93], v149 offset:2176
	global_load_dwordx4 v[208:211], v208, s[6:7]
	ds_read_b128 v[94:97], v149 offset:3264
	global_load_dwordx4 v[212:215], v212, s[6:7]
	ds_read_b128 v[66:69], v149 offset:4352
	global_load_dwordx4 v[216:219], v216, s[6:7]
	ds_read_b128 v[70:73], v149 offset:5440
	global_load_dwordx4 v[220:223], v220, s[6:7]
	ds_read_b128 v[74:77], v149 offset:6528
	global_load_dwordx4 v[224:227], v224, s[6:7]
	ds_read_b128 v[78:81], v149 offset:7616
	global_load_dwordx4 v[228:231], v228, s[6:7]
	v_lshl_add_u32 v232, v232, 11, v243
	v_lshl_add_u32 v233, v233, 11, v243
	v_lshl_add_u32 v234, v234, 11, v243
	v_lshl_add_u32 v235, v235, 11, v243
	v_lshl_add_u32 v236, v236, 11, v243
	v_lshl_add_u32 v237, v237, 11, v243
	v_lshl_add_u32 v238, v238, 11, v243
	v_lshl_add_u32 v239, v239, 11, v243
	s_waitcnt vmcnt(7) lgkmcnt(7)
	v_mul_f32_e32 v82, v82, v200
	v_mul_f32_e32 v83, v83, v201
	v_mul_f32_e32 v84, v84, v202
	v_mul_f32_e32 v85, v85, v203
	v_cvt_pk_bf16_f32 v82, v82, v83
	v_cvt_pk_bf16_f32 v83, v84, v85
	global_store_dwordx2 v232, v[82:83], s[4:5] sc1
	s_waitcnt vmcnt(7) lgkmcnt(6)
	v_mul_f32_e32 v86, v86, v204
	v_mul_f32_e32 v87, v87, v205
	v_mul_f32_e32 v88, v88, v206
	v_mul_f32_e32 v89, v89, v207
	v_cvt_pk_bf16_f32 v86, v86, v87
	v_cvt_pk_bf16_f32 v87, v88, v89
	global_store_dwordx2 v233, v[86:87], s[4:5] sc1
	s_waitcnt vmcnt(7) lgkmcnt(5)
	v_mul_f32_e32 v90, v90, v208
	v_mul_f32_e32 v91, v91, v209
	v_mul_f32_e32 v92, v92, v210
	v_mul_f32_e32 v93, v93, v211
	v_cvt_pk_bf16_f32 v90, v90, v91
	v_cvt_pk_bf16_f32 v91, v92, v93
	global_store_dwordx2 v234, v[90:91], s[4:5] sc1
	s_waitcnt vmcnt(7) lgkmcnt(4)
	v_mul_f32_e32 v94, v94, v212
	v_mul_f32_e32 v95, v95, v213
	v_mul_f32_e32 v96, v96, v214
	v_mul_f32_e32 v97, v97, v215
	v_cvt_pk_bf16_f32 v94, v94, v95
	v_cvt_pk_bf16_f32 v95, v96, v97
	global_store_dwordx2 v235, v[94:95], s[4:5] sc1
	s_waitcnt vmcnt(7) lgkmcnt(3)
	v_mul_f32_e32 v66, v66, v216
	v_mul_f32_e32 v67, v67, v217
	v_mul_f32_e32 v68, v68, v218
	v_mul_f32_e32 v69, v69, v219
	v_cvt_pk_bf16_f32 v66, v66, v67
	v_cvt_pk_bf16_f32 v67, v68, v69
	global_store_dwordx2 v236, v[66:67], s[4:5] sc1
	s_waitcnt vmcnt(7) lgkmcnt(2)
	v_mul_f32_e32 v70, v70, v220
	v_mul_f32_e32 v71, v71, v221
	v_mul_f32_e32 v72, v72, v222
	v_mul_f32_e32 v73, v73, v223
	v_cvt_pk_bf16_f32 v70, v70, v71
	v_cvt_pk_bf16_f32 v71, v72, v73
	global_store_dwordx2 v237, v[70:71], s[4:5] sc1
	s_waitcnt vmcnt(7) lgkmcnt(1)
	v_mul_f32_e32 v74, v74, v224
	v_mul_f32_e32 v75, v75, v225
	v_mul_f32_e32 v76, v76, v226
	v_mul_f32_e32 v77, v77, v227
	v_cvt_pk_bf16_f32 v74, v74, v75
	v_cvt_pk_bf16_f32 v75, v76, v77
	global_store_dwordx2 v238, v[74:75], s[4:5] sc1
	s_waitcnt vmcnt(7) lgkmcnt(0)
	v_mul_f32_e32 v78, v78, v228
	v_mul_f32_e32 v79, v79, v229
	v_mul_f32_e32 v80, v80, v230
	v_mul_f32_e32 v81, v81, v231
	v_cvt_pk_bf16_f32 v78, v78, v79
	v_cvt_pk_bf16_f32 v79, v80, v81
	global_store_dwordx2 v239, v[78:79], s[4:5] sc1
	ds_write_b128 v147, v[50:53]
	ds_write_b128 v147, v[54:57] offset:32
	ds_write_b128 v147, v[58:61] offset:64
	ds_write_b128 v147, v[62:65] offset:96
	ds_write_b128 v147, v[34:37] offset:128
	ds_write_b128 v147, v[38:41] offset:160
	ds_write_b128 v147, v[42:45] offset:192
	ds_write_b128 v147, v[46:49] offset:224
	v_add_u32_e32 v240, 0x20, v104
	v_add_u32_e32 v241, 0xfffff000, v240
	v_lshrrev_b32_e32 v241, 11, v241
	v_mad_u32_u24 v241, v241, s26, s26
	v_lshlrev_b32_e32 v241, 2, v241
	v_or_b32_e32 v232, v240, v119
	v_or_b32_e32 v233, v240, v121
	v_or_b32_e32 v234, v240, v122
	v_or_b32_e32 v235, v240, v123
	v_or_b32_e32 v236, v240, v124
	v_or_b32_e32 v237, v240, v125
	v_or_b32_e32 v238, v240, v126
	v_or_b32_e32 v239, v240, v127
	v_cmp_lt_i32_e64 s[82:83], s27, v232
	v_cmp_lt_i32_e64 s[84:85], s27, v233
	v_cmp_lt_i32_e64 s[86:87], s27, v234
	v_cmp_lt_i32_e64 s[88:89], s27, v235
	v_cmp_lt_i32_e64 s[90:91], s27, v236
	v_cmp_lt_i32_e64 s[92:93], s27, v237
	v_cmp_lt_i32_e64 s[94:95], s27, v238
	v_cmp_lt_i32_e64 s[96:97], s27, v239
	s_waitcnt lgkmcnt(0)
	v_cndmask_b32_e64 v200, 0, v241, s[82:83]
	v_cndmask_b32_e64 v204, 0, v241, s[84:85]
	v_cndmask_b32_e64 v208, 0, v241, s[86:87]
	v_cndmask_b32_e64 v212, 0, v241, s[88:89]
	v_cndmask_b32_e64 v216, 0, v241, s[90:91]
	v_cndmask_b32_e64 v220, 0, v241, s[92:93]
	v_cndmask_b32_e64 v224, 0, v241, s[94:95]
	v_cndmask_b32_e64 v228, 0, v241, s[96:97]
	v_add_u32_e32 v200, v200, v242
	v_add_u32_e32 v204, v204, v242
	v_add_u32_e32 v208, v208, v242
	v_add_u32_e32 v212, v212, v242
	v_add_u32_e32 v216, v216, v242
	v_add_u32_e32 v220, v220, v242
	v_add_u32_e32 v224, v224, v242
	v_add_u32_e32 v228, v228, v242
	ds_read_b128 v[50:53], v149
	global_load_dwordx4 v[200:203], v200, s[6:7]
	ds_read_b128 v[54:57], v149 offset:1088
	global_load_dwordx4 v[204:207], v204, s[6:7]
	ds_read_b128 v[58:61], v149 offset:2176
	global_load_dwordx4 v[208:211], v208, s[6:7]
	ds_read_b128 v[62:65], v149 offset:3264
	global_load_dwordx4 v[212:215], v212, s[6:7]
	ds_read_b128 v[34:37], v149 offset:4352
	global_load_dwordx4 v[216:219], v216, s[6:7]
	ds_read_b128 v[38:41], v149 offset:5440
	global_load_dwordx4 v[220:223], v220, s[6:7]
	ds_read_b128 v[42:45], v149 offset:6528
	global_load_dwordx4 v[224:227], v224, s[6:7]
	ds_read_b128 v[46:49], v149 offset:7616
	global_load_dwordx4 v[228:231], v228, s[6:7]
	v_lshl_add_u32 v232, v232, 11, v243
	v_lshl_add_u32 v233, v233, 11, v243
	v_lshl_add_u32 v234, v234, 11, v243
	v_lshl_add_u32 v235, v235, 11, v243
	v_lshl_add_u32 v236, v236, 11, v243
	v_lshl_add_u32 v237, v237, 11, v243
	v_lshl_add_u32 v238, v238, 11, v243
	v_lshl_add_u32 v239, v239, 11, v243
	s_waitcnt vmcnt(7) lgkmcnt(7)
	v_mul_f32_e32 v50, v50, v200
	v_mul_f32_e32 v51, v51, v201
	v_mul_f32_e32 v52, v52, v202
	v_mul_f32_e32 v53, v53, v203
	v_cvt_pk_bf16_f32 v50, v50, v51
	v_cvt_pk_bf16_f32 v51, v52, v53
	global_store_dwordx2 v232, v[50:51], s[4:5] sc1
	s_waitcnt vmcnt(7) lgkmcnt(6)
	v_mul_f32_e32 v54, v54, v204
	v_mul_f32_e32 v55, v55, v205
	v_mul_f32_e32 v56, v56, v206
	v_mul_f32_e32 v57, v57, v207
	v_cvt_pk_bf16_f32 v54, v54, v55
	v_cvt_pk_bf16_f32 v55, v56, v57
	global_store_dwordx2 v233, v[54:55], s[4:5] sc1
	s_waitcnt vmcnt(7) lgkmcnt(5)
	v_mul_f32_e32 v58, v58, v208
	v_mul_f32_e32 v59, v59, v209
	v_mul_f32_e32 v60, v60, v210
	v_mul_f32_e32 v61, v61, v211
	v_cvt_pk_bf16_f32 v58, v58, v59
	v_cvt_pk_bf16_f32 v59, v60, v61
	global_store_dwordx2 v234, v[58:59], s[4:5] sc1
	s_waitcnt vmcnt(7) lgkmcnt(4)
	v_mul_f32_e32 v62, v62, v212
	v_mul_f32_e32 v63, v63, v213
	v_mul_f32_e32 v64, v64, v214
	v_mul_f32_e32 v65, v65, v215
	v_cvt_pk_bf16_f32 v62, v62, v63
	v_cvt_pk_bf16_f32 v63, v64, v65
	global_store_dwordx2 v235, v[62:63], s[4:5] sc1
	s_waitcnt vmcnt(7) lgkmcnt(3)
	v_mul_f32_e32 v34, v34, v216
	v_mul_f32_e32 v35, v35, v217
	v_mul_f32_e32 v36, v36, v218
	v_mul_f32_e32 v37, v37, v219
	v_cvt_pk_bf16_f32 v34, v34, v35
	v_cvt_pk_bf16_f32 v35, v36, v37
	global_store_dwordx2 v236, v[34:35], s[4:5] sc1
	s_waitcnt vmcnt(7) lgkmcnt(2)
	v_mul_f32_e32 v38, v38, v220
	v_mul_f32_e32 v39, v39, v221
	v_mul_f32_e32 v40, v40, v222
	v_mul_f32_e32 v41, v41, v223
	v_cvt_pk_bf16_f32 v38, v38, v39
	v_cvt_pk_bf16_f32 v39, v40, v41
	global_store_dwordx2 v237, v[38:39], s[4:5] sc1
	s_waitcnt vmcnt(7) lgkmcnt(1)
	v_mul_f32_e32 v42, v42, v224
	v_mul_f32_e32 v43, v43, v225
	v_mul_f32_e32 v44, v44, v226
	v_mul_f32_e32 v45, v45, v227
	v_cvt_pk_bf16_f32 v42, v42, v43
	v_cvt_pk_bf16_f32 v43, v44, v45
	global_store_dwordx2 v238, v[42:43], s[4:5] sc1
	s_waitcnt vmcnt(7) lgkmcnt(0)
	v_mul_f32_e32 v46, v46, v228
	v_mul_f32_e32 v47, v47, v229
	v_mul_f32_e32 v48, v48, v230
	v_mul_f32_e32 v49, v49, v231
	v_cvt_pk_bf16_f32 v46, v46, v47
	v_cvt_pk_bf16_f32 v47, v48, v49
	global_store_dwordx2 v239, v[46:47], s[4:5] sc1
	ds_write_b128 v147, v[18:21]
	ds_write_b128 v147, v[22:25] offset:32
	ds_write_b128 v147, v[26:29] offset:64
	ds_write_b128 v147, v[30:33] offset:96
	ds_write_b128 v147, v[2:5] offset:128
	ds_write_b128 v147, v[6:9] offset:160
	ds_write_b128 v147, v[10:13] offset:192
	ds_write_b128 v147, v[14:17] offset:224
	v_add_u32_e32 v240, 0x40, v104
	v_add_u32_e32 v241, 0xfffff000, v240
	v_lshrrev_b32_e32 v241, 11, v241
	v_mad_u32_u24 v241, v241, s26, s26
	v_lshlrev_b32_e32 v241, 2, v241
	v_or_b32_e32 v232, v240, v119
	v_or_b32_e32 v233, v240, v121
	v_or_b32_e32 v234, v240, v122
	v_or_b32_e32 v235, v240, v123
	v_or_b32_e32 v236, v240, v124
	v_or_b32_e32 v237, v240, v125
	v_or_b32_e32 v238, v240, v126
	v_or_b32_e32 v239, v240, v127
	v_cmp_lt_i32_e64 s[82:83], s27, v232
	v_cmp_lt_i32_e64 s[84:85], s27, v233
	v_cmp_lt_i32_e64 s[86:87], s27, v234
	v_cmp_lt_i32_e64 s[88:89], s27, v235
	v_cmp_lt_i32_e64 s[90:91], s27, v236
	v_cmp_lt_i32_e64 s[92:93], s27, v237
	v_cmp_lt_i32_e64 s[94:95], s27, v238
	v_cmp_lt_i32_e64 s[96:97], s27, v239
	s_waitcnt lgkmcnt(0)
	v_cndmask_b32_e64 v200, 0, v241, s[82:83]
	v_cndmask_b32_e64 v204, 0, v241, s[84:85]
	v_cndmask_b32_e64 v208, 0, v241, s[86:87]
	v_cndmask_b32_e64 v212, 0, v241, s[88:89]
	v_cndmask_b32_e64 v216, 0, v241, s[90:91]
	v_cndmask_b32_e64 v220, 0, v241, s[92:93]
	v_cndmask_b32_e64 v224, 0, v241, s[94:95]
	v_cndmask_b32_e64 v228, 0, v241, s[96:97]
	v_add_u32_e32 v200, v200, v242
	v_add_u32_e32 v204, v204, v242
	v_add_u32_e32 v208, v208, v242
	v_add_u32_e32 v212, v212, v242
	v_add_u32_e32 v216, v216, v242
	v_add_u32_e32 v220, v220, v242
	v_add_u32_e32 v224, v224, v242
	v_add_u32_e32 v228, v228, v242
	ds_read_b128 v[18:21], v149
	global_load_dwordx4 v[200:203], v200, s[6:7]
	ds_read_b128 v[22:25], v149 offset:1088
	global_load_dwordx4 v[204:207], v204, s[6:7]
	ds_read_b128 v[26:29], v149 offset:2176
	global_load_dwordx4 v[208:211], v208, s[6:7]
	ds_read_b128 v[30:33], v149 offset:3264
	global_load_dwordx4 v[212:215], v212, s[6:7]
	ds_read_b128 v[2:5], v149 offset:4352
	global_load_dwordx4 v[216:219], v216, s[6:7]
	ds_read_b128 v[6:9], v149 offset:5440
	global_load_dwordx4 v[220:223], v220, s[6:7]
	ds_read_b128 v[10:13], v149 offset:6528
	global_load_dwordx4 v[224:227], v224, s[6:7]
	ds_read_b128 v[14:17], v149 offset:7616
	global_load_dwordx4 v[228:231], v228, s[6:7]
	v_lshl_add_u32 v232, v232, 11, v243
	v_lshl_add_u32 v233, v233, 11, v243
	v_lshl_add_u32 v234, v234, 11, v243
	v_lshl_add_u32 v235, v235, 11, v243
	v_lshl_add_u32 v236, v236, 11, v243
	v_lshl_add_u32 v237, v237, 11, v243
	v_lshl_add_u32 v238, v238, 11, v243
	v_lshl_add_u32 v239, v239, 11, v243
	s_waitcnt vmcnt(7) lgkmcnt(7)
	v_mul_f32_e32 v18, v18, v200
	v_mul_f32_e32 v19, v19, v201
	v_mul_f32_e32 v20, v20, v202
	v_mul_f32_e32 v21, v21, v203
	v_cvt_pk_bf16_f32 v18, v18, v19
	v_cvt_pk_bf16_f32 v19, v20, v21
	global_store_dwordx2 v232, v[18:19], s[4:5] sc1
	s_waitcnt vmcnt(7) lgkmcnt(6)
	v_mul_f32_e32 v22, v22, v204
	v_mul_f32_e32 v23, v23, v205
	v_mul_f32_e32 v24, v24, v206
	v_mul_f32_e32 v25, v25, v207
	v_cvt_pk_bf16_f32 v22, v22, v23
	v_cvt_pk_bf16_f32 v23, v24, v25
	global_store_dwordx2 v233, v[22:23], s[4:5] sc1
	s_waitcnt vmcnt(7) lgkmcnt(5)
	v_mul_f32_e32 v26, v26, v208
	v_mul_f32_e32 v27, v27, v209
	v_mul_f32_e32 v28, v28, v210
	v_mul_f32_e32 v29, v29, v211
	v_cvt_pk_bf16_f32 v26, v26, v27
	v_cvt_pk_bf16_f32 v27, v28, v29
	global_store_dwordx2 v234, v[26:27], s[4:5] sc1
	s_waitcnt vmcnt(7) lgkmcnt(4)
	v_mul_f32_e32 v30, v30, v212
	v_mul_f32_e32 v31, v31, v213
	v_mul_f32_e32 v32, v32, v214
	v_mul_f32_e32 v33, v33, v215
	v_cvt_pk_bf16_f32 v30, v30, v31
	v_cvt_pk_bf16_f32 v31, v32, v33
	global_store_dwordx2 v235, v[30:31], s[4:5] sc1
	s_waitcnt vmcnt(7) lgkmcnt(3)
	v_mul_f32_e32 v2, v2, v216
	v_mul_f32_e32 v3, v3, v217
	v_mul_f32_e32 v4, v4, v218
	v_mul_f32_e32 v5, v5, v219
	v_cvt_pk_bf16_f32 v2, v2, v3
	v_cvt_pk_bf16_f32 v3, v4, v5
	global_store_dwordx2 v236, v[2:3], s[4:5] sc1
	s_waitcnt vmcnt(7) lgkmcnt(2)
	v_mul_f32_e32 v6, v6, v220
	v_mul_f32_e32 v7, v7, v221
	v_mul_f32_e32 v8, v8, v222
	v_mul_f32_e32 v9, v9, v223
	v_cvt_pk_bf16_f32 v6, v6, v7
	v_cvt_pk_bf16_f32 v7, v8, v9
	global_store_dwordx2 v237, v[6:7], s[4:5] sc1
	s_waitcnt vmcnt(7) lgkmcnt(1)
	v_mul_f32_e32 v10, v10, v224
	v_mul_f32_e32 v11, v11, v225
	v_mul_f32_e32 v12, v12, v226
	v_mul_f32_e32 v13, v13, v227
	v_cvt_pk_bf16_f32 v10, v10, v11
	v_cvt_pk_bf16_f32 v11, v12, v13
	global_store_dwordx2 v238, v[10:11], s[4:5] sc1
	s_waitcnt vmcnt(7) lgkmcnt(0)
	v_mul_f32_e32 v14, v14, v228
	v_mul_f32_e32 v15, v15, v229
	v_mul_f32_e32 v16, v16, v230
	v_mul_f32_e32 v17, v17, v231
	v_cvt_pk_bf16_f32 v14, v14, v15
	v_cvt_pk_bf16_f32 v15, v16, v17
	global_store_dwordx2 v239, v[14:15], s[4:5] sc1
	s_waitcnt lgkmcnt(0)
	s_load_dword s10, s[8:9], 0x0
	s_waitcnt lgkmcnt(0)
	s_add_i32 s28, s10, s28
	s_cmpk_lt_i32 s28, 0x200
	s_cbranch_scc1 .LBB0_1133

.LBB0_1270:
	s_ashr_i32 s4, s64, 31
	s_lshr_b32 s4, s4, 26
	s_add_i32 s4, s64, s4
	s_ashr_i32 s5, s4, 6
	s_and_b32 s4, s4, 0x3ffffc0
	s_sub_i32 s6, s64, s4
	s_mulk_i32 s6, 0xc0
	v_add_u32_e32 v2, s6, v116
	s_lshr_b32 s7, s6, 6
	s_lshl_b32 s4, s5, 7
	v_ashrrev_i32_e32 v3, 31, v2
	s_add_i32 s7, s7, s5
	v_lshlrev_b64 v[2:3], 11, v[2:3]
	v_or_b32_e32 v4, s4, v116
	s_lshl_b32 s46, s7, 6
	s_lshl_b32 s7, s7, 7
	v_ashrrev_i32_e32 v5, 31, v4
	v_lshl_add_u64 v[112:113], v[104:105], 0, v[2:3]
	s_and_b32 s16, s7, 0x780
	v_readfirstlane_b32 s7, v117
	v_add_u32_e32 v6, 0x1000, v117
	v_lshlrev_b64 v[4:5], 11, v[4:5]
	v_lshl_add_u64 v[2:3], v[112:113], 0, s[16:17]
	s_mov_b32 m0, s7
	v_readfirstlane_b32 s7, v6
	v_add_u32_e32 v6, 0x2000, v117
	v_lshl_add_u64 v[114:115], v[106:107], 0, v[4:5]
	s_getreg_b32 s83, hwreg(HW_REG_HW_ID, 0, 4)
	s_bitcmp1_b32 s83, 0
	s_cbranch_scc0 .Lgm_ph13_noprio
	s_setprio 1
.Lgm_ph13_noprio:
	s_waitcnt vmcnt(0)
	s_barrier
	s_load_dwordx2 s[66:67], s[0:1], 0x90
	s_load_dwordx2 s[68:69], s[0:1], 0xf8
	v_and_b32_e32 v201, 0x3ff, v0
	v_readfirstlane_b32 s80, v0
	v_and_b32_e32 v200, 31, v201
	v_bfe_u32 v214, v201, 1, 3
	v_bfe_u32 v213, v201, 5, 1
	v_xor_b32_e32 v214, v214, v213
	v_lshlrev_b32_e32 v214, 4, v214
	s_and_b32 s80, s80, 0x3ff
	s_lshr_b32 s83, s80, 6
	s_lshl_b32 s80, s80, 4
	s_lshr_b32 s84, s83, 1
	s_and_b32 s83, s83, 1
	s_mul_i32 s84, s84, 0x3000
	s_lshl_b32 s83, s83, 13
	s_add_u32 s83, s83, 0xc000
	v_lshlrev_b32_e32 v200, 7, v200
	v_or_b32_e32 v200, v200, v214
	v_add_u32_e32 v215, s84, v200
	v_add_u32_e32 v211, s83, v200
	v_xor_b32_e32 v214, 0x20, v215
	v_xor_b32_e32 v210, 0x20, v211
	v_xor_b32_e32 v213, 0x40, v215
	v_xor_b32_e32 v209, 0x40, v211
	v_xor_b32_e32 v212, 0x60, v215
	v_xor_b32_e32 v208, 0x60, v211
	v_bfe_u32 v200, v201, 4, 3
	v_and_b32_e32 v206, 7, v201
	v_xor_b32_e32 v200, v200, v206
	v_lshlrev_b32_e32 v200, 4, v200
	v_lshrrev_b32_e32 v206, 3, v201
	v_lshl_or_b32 v207, v206, 11, v200
	v_add_u32_e32 v206, 0x10000, v207
	v_add_u32_e32 v205, 0x20000, v207
	v_add_u32_e32 v204, 0x30000, v207
	v_add_u32_e32 v203, 0x40000, v207
	v_add_u32_e32 v202, 0x50000, v207
	s_lshr_b32 s83, s64, 6
	s_and_b32 s84, s64, 63
	s_mov_b32 s79, 0
	s_mul_i32 s84, s84, 0x60000
	s_lshl_b32 s83, s83, 18
	s_waitcnt lgkmcnt(0)
	s_add_u32 s66, s66, s84
	s_addc_u32 s67, s67, 0
	s_add_u32 s68, s68, s83
	s_addc_u32 s69, s69, 0
	s_add_u32 s83, s79, 0
	s_and_b32 s83, s83, 15
	s_lshl_b32 s83, s83, 7
	s_add_u32 s70, s66, s83
	s_addc_u32 s71, s67, 0
	s_add_u32 s72, s68, s83
	s_addc_u32 s73, s69, 0
	s_add_u32 s81, s80, 0x0
	s_add_u32 s82, s80, 0xc000
	s_add_u32 m0, s81, 0x0
	s_nop 0
	global_load_lds_dwordx4 v207, s[70:71]
	s_add_u32 m0, s81, 0x1000
	s_nop 0
	global_load_lds_dwordx4 v206, s[70:71]
	s_add_u32 m0, s81, 0x2000
	s_nop 0
	global_load_lds_dwordx4 v205, s[70:71]
	s_add_u32 m0, s81, 0x3000
	s_nop 0
	global_load_lds_dwordx4 v204, s[70:71]
	s_add_u32 m0, s81, 0x4000
	s_nop 0
	global_load_lds_dwordx4 v203, s[70:71]
	s_add_u32 m0, s81, 0x5000
	s_nop 0
	global_load_lds_dwordx4 v202, s[70:71]
	s_add_u32 m0, s82, 0x0
	s_nop 0
	global_load_lds_dwordx4 v207, s[72:73]
	s_add_u32 m0, s82, 0x1000
	s_nop 0
	global_load_lds_dwordx4 v206, s[72:73]
	s_add_u32 m0, s82, 0x2000
	s_nop 0
	global_load_lds_dwordx4 v205, s[72:73]
	s_add_u32 m0, s82, 0x3000
	s_nop 0
	global_load_lds_dwordx4 v204, s[72:73]
	s_add_u32 s83, s79, 1
	s_and_b32 s83, s83, 15
	s_lshl_b32 s83, s83, 7
	s_add_u32 s70, s66, s83
	s_addc_u32 s71, s67, 0
	s_add_u32 s72, s68, s83
	s_addc_u32 s73, s69, 0
	s_add_u32 s81, s80, 0x6000
	s_add_u32 s82, s80, 0x10000
	s_add_u32 m0, s81, 0x0
	s_nop 0
	global_load_lds_dwordx4 v207, s[70:71]
	s_add_u32 m0, s81, 0x1000
	s_nop 0
	global_load_lds_dwordx4 v206, s[70:71]
	s_add_u32 m0, s81, 0x2000
	s_nop 0
	global_load_lds_dwordx4 v205, s[70:71]
	s_add_u32 m0, s81, 0x3000
	s_nop 0
	global_load_lds_dwordx4 v204, s[70:71]
	s_add_u32 m0, s81, 0x4000
	s_nop 0
	global_load_lds_dwordx4 v203, s[70:71]
	v_mov_b32_e32 v2, 0
	v_mov_b32_e32 v3, 0
	v_mov_b32_e32 v4, 0
	v_mov_b32_e32 v5, 0
	v_mov_b32_e32 v6, 0
	v_mov_b32_e32 v7, 0
	v_mov_b32_e32 v8, 0
	v_mov_b32_e32 v9, 0
	v_mov_b32_e32 v10, 0
	v_mov_b32_e32 v11, 0
	v_mov_b32_e32 v12, 0
	v_mov_b32_e32 v13, 0
	v_mov_b32_e32 v14, 0
	v_mov_b32_e32 v15, 0
	v_mov_b32_e32 v16, 0
	v_mov_b32_e32 v17, 0
	v_mov_b32_e32 v18, 0
	v_mov_b32_e32 v19, 0
	v_mov_b32_e32 v20, 0
	v_mov_b32_e32 v21, 0
	v_mov_b32_e32 v22, 0
	v_mov_b32_e32 v23, 0
	v_mov_b32_e32 v24, 0
	v_mov_b32_e32 v25, 0
	v_mov_b32_e32 v26, 0
	v_mov_b32_e32 v27, 0
	v_mov_b32_e32 v28, 0
	v_mov_b32_e32 v29, 0
	v_mov_b32_e32 v30, 0
	v_mov_b32_e32 v31, 0
	v_mov_b32_e32 v32, 0
	v_mov_b32_e32 v33, 0
	v_mov_b32_e32 v34, 0
	v_mov_b32_e32 v35, 0
	v_mov_b32_e32 v36, 0
	v_mov_b32_e32 v37, 0
	v_mov_b32_e32 v38, 0
	v_mov_b32_e32 v39, 0
	v_mov_b32_e32 v40, 0
	v_mov_b32_e32 v41, 0
	v_mov_b32_e32 v42, 0
	v_mov_b32_e32 v43, 0
	v_mov_b32_e32 v44, 0
	v_mov_b32_e32 v45, 0
	v_mov_b32_e32 v46, 0
	v_mov_b32_e32 v47, 0
	v_mov_b32_e32 v48, 0
	v_mov_b32_e32 v49, 0
	v_mov_b32_e32 v50, 0
	v_mov_b32_e32 v51, 0
	v_mov_b32_e32 v52, 0
	v_mov_b32_e32 v53, 0
	v_mov_b32_e32 v54, 0
	v_mov_b32_e32 v55, 0
	v_mov_b32_e32 v56, 0
	v_mov_b32_e32 v57, 0
	v_mov_b32_e32 v58, 0
	v_mov_b32_e32 v59, 0
	v_mov_b32_e32 v60, 0
	v_mov_b32_e32 v61, 0
	v_mov_b32_e32 v62, 0
	v_mov_b32_e32 v63, 0
	v_mov_b32_e32 v64, 0
	v_mov_b32_e32 v65, 0
	v_mov_b32_e32 v66, 0
	v_mov_b32_e32 v67, 0
	v_mov_b32_e32 v68, 0
	v_mov_b32_e32 v69, 0
	v_mov_b32_e32 v70, 0
	v_mov_b32_e32 v71, 0
	v_mov_b32_e32 v72, 0
	v_mov_b32_e32 v73, 0
	v_mov_b32_e32 v74, 0
	v_mov_b32_e32 v75, 0
	v_mov_b32_e32 v76, 0
	v_mov_b32_e32 v77, 0
	v_mov_b32_e32 v78, 0
	v_mov_b32_e32 v79, 0
	v_mov_b32_e32 v80, 0
	v_mov_b32_e32 v81, 0
	v_mov_b32_e32 v82, 0
	v_mov_b32_e32 v83, 0
	v_mov_b32_e32 v84, 0
	v_mov_b32_e32 v85, 0
	v_mov_b32_e32 v86, 0
	v_mov_b32_e32 v87, 0
	v_mov_b32_e32 v88, 0
	v_mov_b32_e32 v89, 0
	v_mov_b32_e32 v90, 0
	v_mov_b32_e32 v91, 0
	v_mov_b32_e32 v92, 0
	v_mov_b32_e32 v93, 0
	v_mov_b32_e32 v94, 0
	v_mov_b32_e32 v95, 0
	v_mov_b32_e32 v96, 0
	v_mov_b32_e32 v97, 0
	s_waitcnt vmcnt(5)
	s_barrier
	ds_read_b128 v[240:243], v211 offset:0
	ds_read_b128 v[252:255], v215 offset:0
	ds_read_b128 v[236:239], v211 offset:4096
	ds_read_b128 v[248:251], v215 offset:4096
	ds_read_b128 v[244:247], v215 offset:8192
	s_mov_b32 s78, 0
.Lgm_ph13_loop:
	s_waitcnt lgkmcnt(1)
	v_mfma_f32_32x32x16_bf16 v[82:97], v[240:243], v[252:255], v[82:97]
	ds_read_b128 v[220:223], v210 offset:0
	s_add_u32 m0, s81, 0x5000
	s_nop 0
	global_load_lds_dwordx4 v202, s[70:71]
	v_mfma_f32_32x32x16_bf16 v[66:81], v[236:239], v[252:255], v[66:81]
	ds_read_b128 v[232:235], v214 offset:0
	s_add_u32 m0, s82, 0x0
	s_nop 0
	global_load_lds_dwordx4 v207, s[72:73]
	v_mfma_f32_32x32x16_bf16 v[50:65], v[240:243], v[248:251], v[50:65]
	ds_read_b128 v[216:219], v210 offset:4096
	s_add_u32 m0, s82, 0x1000
	s_nop 0
	global_load_lds_dwordx4 v206, s[72:73]
	v_mfma_f32_32x32x16_bf16 v[34:49], v[236:239], v[248:251], v[34:49]
	ds_read_b128 v[228:231], v214 offset:4096
	s_add_u32 m0, s82, 0x2000
	s_nop 0
	global_load_lds_dwordx4 v205, s[72:73]
	s_waitcnt lgkmcnt(4)
	v_mfma_f32_32x32x16_bf16 v[18:33], v[240:243], v[244:247], v[18:33]
	ds_read_b128 v[224:227], v214 offset:8192
	v_mfma_f32_32x32x16_bf16 v[2:17], v[236:239], v[244:247], v[2:17]
	s_add_u32 m0, s82, 0x3000
	s_nop 0
	global_load_lds_dwordx4 v204, s[72:73]
	s_waitcnt lgkmcnt(1)
	v_mfma_f32_32x32x16_bf16 v[82:97], v[220:223], v[232:235], v[82:97]
	ds_read_b128 v[240:243], v209 offset:0
	v_mfma_f32_32x32x16_bf16 v[66:81], v[216:219], v[232:235], v[66:81]
	ds_read_b128 v[252:255], v213 offset:0
	v_mfma_f32_32x32x16_bf16 v[50:65], v[220:223], v[228:231], v[50:65]
	ds_read_b128 v[236:239], v209 offset:4096
	v_mfma_f32_32x32x16_bf16 v[34:49], v[216:219], v[228:231], v[34:49]
	ds_read_b128 v[248:251], v213 offset:4096
	s_waitcnt lgkmcnt(4)
	v_mfma_f32_32x32x16_bf16 v[18:33], v[220:223], v[224:227], v[18:33]
	ds_read_b128 v[244:247], v213 offset:8192
	v_mfma_f32_32x32x16_bf16 v[2:17], v[216:219], v[224:227], v[2:17]
	s_waitcnt lgkmcnt(1)
	v_mfma_f32_32x32x16_bf16 v[82:97], v[240:243], v[252:255], v[82:97]
	ds_read_b128 v[220:223], v208 offset:0
	s_add_u32 s83, s79, s78
	s_add_u32 s83, s83, 2
	s_and_b32 s83, s83, 15
	v_mfma_f32_32x32x16_bf16 v[66:81], v[236:239], v[252:255], v[66:81]
	ds_read_b128 v[232:235], v212 offset:0
	s_lshl_b32 s83, s83, 7
	s_add_u32 s70, s66, s83
	v_mfma_f32_32x32x16_bf16 v[50:65], v[240:243], v[248:251], v[50:65]
	ds_read_b128 v[216:219], v208 offset:4096
	s_addc_u32 s71, s67, 0
	s_add_u32 s72, s68, s83
	v_mfma_f32_32x32x16_bf16 v[34:49], v[236:239], v[248:251], v[34:49]
	ds_read_b128 v[228:231], v212 offset:4096
	s_addc_u32 s73, s69, 0
	s_add_u32 s81, s80, 0x0
	s_add_u32 s82, s80, 0xc000
	s_waitcnt lgkmcnt(4)
	v_mfma_f32_32x32x16_bf16 v[18:33], v[240:243], v[244:247], v[18:33]
	ds_read_b128 v[224:227], v212 offset:8192
	v_mfma_f32_32x32x16_bf16 v[2:17], v[236:239], v[244:247], v[2:17]
	s_waitcnt vmcnt(0) lgkmcnt(0)
	s_barrier
	v_mfma_f32_32x32x16_bf16 v[82:97], v[220:223], v[232:235], v[82:97]
	s_add_u32 m0, s81, 0x0
	ds_read_b128 v[240:243], v211 offset:16384
	global_load_lds_dwordx4 v207, s[70:71]
	v_mfma_f32_32x32x16_bf16 v[66:81], v[216:219], v[232:235], v[66:81]
	s_add_u32 m0, s81, 0x1000
	ds_read_b128 v[252:255], v215 offset:24576
	global_load_lds_dwordx4 v206, s[70:71]
	v_mfma_f32_32x32x16_bf16 v[50:65], v[220:223], v[228:231], v[50:65]
	s_add_u32 m0, s81, 0x2000
	ds_read_b128 v[236:239], v211 offset:20480
	global_load_lds_dwordx4 v205, s[70:71]
	v_mfma_f32_32x32x16_bf16 v[34:49], v[216:219], v[228:231], v[34:49]
	s_add_u32 m0, s81, 0x3000
	ds_read_b128 v[248:251], v215 offset:28672
	global_load_lds_dwordx4 v204, s[70:71]
	v_mfma_f32_32x32x16_bf16 v[18:33], v[220:223], v[224:227], v[18:33]
	s_add_u32 m0, s81, 0x4000
	ds_read_b128 v[244:247], v215 offset:32768
	global_load_lds_dwordx4 v203, s[70:71]
	v_mfma_f32_32x32x16_bf16 v[2:17], v[216:219], v[224:227], v[2:17]
	s_waitcnt lgkmcnt(1)
	v_mfma_f32_32x32x16_bf16 v[82:97], v[240:243], v[252:255], v[82:97]
	ds_read_b128 v[220:223], v210 offset:16384
	s_add_u32 m0, s81, 0x5000
	s_nop 0
	global_load_lds_dwordx4 v202, s[70:71]
	v_mfma_f32_32x32x16_bf16 v[66:81], v[236:239], v[252:255], v[66:81]
	ds_read_b128 v[232:235], v214 offset:24576
	s_add_u32 m0, s82, 0x0
	s_nop 0
	global_load_lds_dwordx4 v207, s[72:73]
	v_mfma_f32_32x32x16_bf16 v[50:65], v[240:243], v[248:251], v[50:65]
	ds_read_b128 v[216:219], v210 offset:20480
	s_add_u32 m0, s82, 0x1000
	s_nop 0
	global_load_lds_dwordx4 v206, s[72:73]
	v_mfma_f32_32x32x16_bf16 v[34:49], v[236:239], v[248:251], v[34:49]
	ds_read_b128 v[228:231], v214 offset:28672
	s_add_u32 m0, s82, 0x2000
	s_nop 0
	global_load_lds_dwordx4 v205, s[72:73]
	s_waitcnt lgkmcnt(4)
	v_mfma_f32_32x32x16_bf16 v[18:33], v[240:243], v[244:247], v[18:33]
	ds_read_b128 v[224:227], v214 offset:32768
	v_mfma_f32_32x32x16_bf16 v[2:17], v[236:239], v[244:247], v[2:17]
	s_add_u32 m0, s82, 0x3000
	s_nop 0
	global_load_lds_dwordx4 v204, s[72:73]
	s_waitcnt lgkmcnt(1)
	v_mfma_f32_32x32x16_bf16 v[82:97], v[220:223], v[232:235], v[82:97]
	ds_read_b128 v[240:243], v209 offset:16384
	v_mfma_f32_32x32x16_bf16 v[66:81], v[216:219], v[232:235], v[66:81]
	ds_read_b128 v[252:255], v213 offset:24576
	v_mfma_f32_32x32x16_bf16 v[50:65], v[220:223], v[228:231], v[50:65]
	ds_read_b128 v[236:239], v209 offset:20480
	v_mfma_f32_32x32x16_bf16 v[34:49], v[216:219], v[228:231], v[34:49]
	ds_read_b128 v[248:251], v213 offset:28672
	s_waitcnt lgkmcnt(4)
	v_mfma_f32_32x32x16_bf16 v[18:33], v[220:223], v[224:227], v[18:33]
	ds_read_b128 v[244:247], v213 offset:32768
	v_mfma_f32_32x32x16_bf16 v[2:17], v[216:219], v[224:227], v[2:17]
	s_waitcnt lgkmcnt(1)
	v_mfma_f32_32x32x16_bf16 v[82:97], v[240:243], v[252:255], v[82:97]
	ds_read_b128 v[220:223], v208 offset:16384
	s_add_u32 s83, s79, s78
	s_add_u32 s83, s83, 3
	s_and_b32 s83, s83, 15
	v_mfma_f32_32x32x16_bf16 v[66:81], v[236:239], v[252:255], v[66:81]
	ds_read_b128 v[232:235], v212 offset:24576
	s_lshl_b32 s83, s83, 7
	s_add_u32 s70, s66, s83
	v_mfma_f32_32x32x16_bf16 v[50:65], v[240:243], v[248:251], v[50:65]
	ds_read_b128 v[216:219], v208 offset:20480
	s_addc_u32 s71, s67, 0
	s_add_u32 s72, s68, s83
	v_mfma_f32_32x32x16_bf16 v[34:49], v[236:239], v[248:251], v[34:49]
	ds_read_b128 v[228:231], v212 offset:28672
	s_addc_u32 s73, s69, 0
	s_add_u32 s81, s80, 0x6000
	s_add_u32 s82, s80, 0x10000
	s_waitcnt lgkmcnt(4)
	v_mfma_f32_32x32x16_bf16 v[18:33], v[240:243], v[244:247], v[18:33]
	ds_read_b128 v[224:227], v212 offset:32768
	v_mfma_f32_32x32x16_bf16 v[2:17], v[236:239], v[244:247], v[2:17]
	s_waitcnt vmcnt(0) lgkmcnt(0)
	s_barrier
	v_mfma_f32_32x32x16_bf16 v[82:97], v[220:223], v[232:235], v[82:97]
	s_add_u32 m0, s81, 0x0
	ds_read_b128 v[240:243], v211 offset:0
	global_load_lds_dwordx4 v207, s[70:71]
	v_mfma_f32_32x32x16_bf16 v[66:81], v[216:219], v[232:235], v[66:81]
	s_add_u32 m0, s81, 0x1000
	ds_read_b128 v[252:255], v215 offset:0
	global_load_lds_dwordx4 v206, s[70:71]
	v_mfma_f32_32x32x16_bf16 v[50:65], v[220:223], v[228:231], v[50:65]
	s_add_u32 m0, s81, 0x2000
	ds_read_b128 v[236:239], v211 offset:4096
	global_load_lds_dwordx4 v205, s[70:71]
	v_mfma_f32_32x32x16_bf16 v[34:49], v[216:219], v[228:231], v[34:49]
	s_add_u32 m0, s81, 0x3000
	ds_read_b128 v[248:251], v215 offset:4096
	global_load_lds_dwordx4 v204, s[70:71]
	v_mfma_f32_32x32x16_bf16 v[18:33], v[220:223], v[224:227], v[18:33]
	s_add_u32 m0, s81, 0x4000
	ds_read_b128 v[244:247], v215 offset:8192
	global_load_lds_dwordx4 v203, s[70:71]
	v_mfma_f32_32x32x16_bf16 v[2:17], v[216:219], v[224:227], v[2:17]
	s_add_u32 s78, s78, 2
	s_cmp_lt_u32 s78, 14
	s_cbranch_scc1 .Lgm_ph13_loop
	s_waitcnt lgkmcnt(1)
	v_mfma_f32_32x32x16_bf16 v[82:97], v[240:243], v[252:255], v[82:97]
	ds_read_b128 v[220:223], v210 offset:0
	s_add_u32 m0, s81, 0x5000
	s_nop 0
	global_load_lds_dwordx4 v202, s[70:71]
	v_mfma_f32_32x32x16_bf16 v[66:81], v[236:239], v[252:255], v[66:81]
	ds_read_b128 v[232:235], v214 offset:0
	s_add_u32 m0, s82, 0x0
	s_nop 0
	global_load_lds_dwordx4 v207, s[72:73]
	v_mfma_f32_32x32x16_bf16 v[50:65], v[240:243], v[248:251], v[50:65]
	ds_read_b128 v[216:219], v210 offset:4096
	s_add_u32 m0, s82, 0x1000
	s_nop 0
	global_load_lds_dwordx4 v206, s[72:73]
	v_mfma_f32_32x32x16_bf16 v[34:49], v[236:239], v[248:251], v[34:49]
	ds_read_b128 v[228:231], v214 offset:4096
	s_add_u32 m0, s82, 0x2000
	s_nop 0
	global_load_lds_dwordx4 v205, s[72:73]
	s_waitcnt lgkmcnt(4)
	v_mfma_f32_32x32x16_bf16 v[18:33], v[240:243], v[244:247], v[18:33]
	ds_read_b128 v[224:227], v214 offset:8192
	v_mfma_f32_32x32x16_bf16 v[2:17], v[236:239], v[244:247], v[2:17]
	s_add_u32 m0, s82, 0x3000
	s_nop 0
	global_load_lds_dwordx4 v204, s[72:73]
	s_waitcnt lgkmcnt(1)
	v_mfma_f32_32x32x16_bf16 v[82:97], v[220:223], v[232:235], v[82:97]
	ds_read_b128 v[240:243], v209 offset:0
	v_mfma_f32_32x32x16_bf16 v[66:81], v[216:219], v[232:235], v[66:81]
	ds_read_b128 v[252:255], v213 offset:0
	v_mfma_f32_32x32x16_bf16 v[50:65], v[220:223], v[228:231], v[50:65]
	ds_read_b128 v[236:239], v209 offset:4096
	v_mfma_f32_32x32x16_bf16 v[34:49], v[216:219], v[228:231], v[34:49]
	ds_read_b128 v[248:251], v213 offset:4096
	s_waitcnt lgkmcnt(4)
	v_mfma_f32_32x32x16_bf16 v[18:33], v[220:223], v[224:227], v[18:33]
	ds_read_b128 v[244:247], v213 offset:8192
	v_mfma_f32_32x32x16_bf16 v[2:17], v[216:219], v[224:227], v[2:17]
	s_waitcnt lgkmcnt(1)
	v_mfma_f32_32x32x16_bf16 v[82:97], v[240:243], v[252:255], v[82:97]
	ds_read_b128 v[220:223], v208 offset:0
	v_mfma_f32_32x32x16_bf16 v[66:81], v[236:239], v[252:255], v[66:81]
	ds_read_b128 v[232:235], v212 offset:0
	v_mfma_f32_32x32x16_bf16 v[50:65], v[240:243], v[248:251], v[50:65]
	ds_read_b128 v[216:219], v208 offset:4096
	v_mfma_f32_32x32x16_bf16 v[34:49], v[236:239], v[248:251], v[34:49]
	ds_read_b128 v[228:231], v212 offset:4096
	s_waitcnt lgkmcnt(4)
	v_mfma_f32_32x32x16_bf16 v[18:33], v[240:243], v[244:247], v[18:33]
	ds_read_b128 v[224:227], v212 offset:8192
	v_mfma_f32_32x32x16_bf16 v[2:17], v[236:239], v[244:247], v[2:17]
	s_waitcnt vmcnt(0) lgkmcnt(0)
	s_barrier
	v_mfma_f32_32x32x16_bf16 v[82:97], v[220:223], v[232:235], v[82:97]
	ds_read_b128 v[240:243], v211 offset:16384
	v_mfma_f32_32x32x16_bf16 v[66:81], v[216:219], v[232:235], v[66:81]
	ds_read_b128 v[252:255], v215 offset:24576
	v_mfma_f32_32x32x16_bf16 v[50:65], v[220:223], v[228:231], v[50:65]
	ds_read_b128 v[236:239], v211 offset:20480
	v_mfma_f32_32x32x16_bf16 v[34:49], v[216:219], v[228:231], v[34:49]
	ds_read_b128 v[248:251], v215 offset:28672
	v_mfma_f32_32x32x16_bf16 v[18:33], v[220:223], v[224:227], v[18:33]
	ds_read_b128 v[244:247], v215 offset:32768
	v_mfma_f32_32x32x16_bf16 v[2:17], v[216:219], v[224:227], v[2:17]
	s_waitcnt lgkmcnt(1)
	v_mfma_f32_32x32x16_bf16 v[82:97], v[240:243], v[252:255], v[82:97]
	ds_read_b128 v[220:223], v210 offset:16384
	v_mfma_f32_32x32x16_bf16 v[66:81], v[236:239], v[252:255], v[66:81]
	ds_read_b128 v[232:235], v214 offset:24576
	v_mfma_f32_32x32x16_bf16 v[50:65], v[240:243], v[248:251], v[50:65]
	ds_read_b128 v[216:219], v210 offset:20480
	v_mfma_f32_32x32x16_bf16 v[34:49], v[236:239], v[248:251], v[34:49]
	ds_read_b128 v[228:231], v214 offset:28672
	s_waitcnt lgkmcnt(4)
	v_mfma_f32_32x32x16_bf16 v[18:33], v[240:243], v[244:247], v[18:33]
	ds_read_b128 v[224:227], v214 offset:32768
	v_mfma_f32_32x32x16_bf16 v[2:17], v[236:239], v[244:247], v[2:17]
	s_waitcnt lgkmcnt(1)
	v_mfma_f32_32x32x16_bf16 v[82:97], v[220:223], v[232:235], v[82:97]
	ds_read_b128 v[240:243], v209 offset:16384
	v_mfma_f32_32x32x16_bf16 v[66:81], v[216:219], v[232:235], v[66:81]
	ds_read_b128 v[252:255], v213 offset:24576
	v_mfma_f32_32x32x16_bf16 v[50:65], v[220:223], v[228:231], v[50:65]
	ds_read_b128 v[236:239], v209 offset:20480
	v_mfma_f32_32x32x16_bf16 v[34:49], v[216:219], v[228:231], v[34:49]
	ds_read_b128 v[248:251], v213 offset:28672
	s_waitcnt lgkmcnt(4)
	v_mfma_f32_32x32x16_bf16 v[18:33], v[220:223], v[224:227], v[18:33]
	ds_read_b128 v[244:247], v213 offset:32768
	v_mfma_f32_32x32x16_bf16 v[2:17], v[216:219], v[224:227], v[2:17]
	s_waitcnt lgkmcnt(1)
	v_mfma_f32_32x32x16_bf16 v[82:97], v[240:243], v[252:255], v[82:97]
	ds_read_b128 v[220:223], v208 offset:16384
	v_mfma_f32_32x32x16_bf16 v[66:81], v[236:239], v[252:255], v[66:81]
	ds_read_b128 v[232:235], v212 offset:24576
	v_mfma_f32_32x32x16_bf16 v[50:65], v[240:243], v[248:251], v[50:65]
	ds_read_b128 v[216:219], v208 offset:20480
	v_mfma_f32_32x32x16_bf16 v[34:49], v[236:239], v[248:251], v[34:49]
	ds_read_b128 v[228:231], v212 offset:28672
	s_waitcnt lgkmcnt(4)
	v_mfma_f32_32x32x16_bf16 v[18:33], v[240:243], v[244:247], v[18:33]
	ds_read_b128 v[224:227], v212 offset:32768
	v_mfma_f32_32x32x16_bf16 v[2:17], v[236:239], v[244:247], v[2:17]
	s_waitcnt vmcnt(0) lgkmcnt(0)
	s_barrier
	v_mfma_f32_32x32x16_bf16 v[82:97], v[220:223], v[232:235], v[82:97]
	v_mfma_f32_32x32x16_bf16 v[66:81], v[216:219], v[232:235], v[66:81]
	v_mfma_f32_32x32x16_bf16 v[50:65], v[220:223], v[228:231], v[50:65]
	v_mfma_f32_32x32x16_bf16 v[34:49], v[216:219], v[228:231], v[34:49]
	v_mfma_f32_32x32x16_bf16 v[18:33], v[220:223], v[224:227], v[18:33]
	v_mfma_f32_32x32x16_bf16 v[2:17], v[216:219], v[224:227], v[2:17]
	s_nop 7
	s_nop 7
	s_setprio 0
	s_and_b32 s5, s5, 0x1fffff8
	s_nop 4
	s_cmp_eq_u32 s5, 16
	s_nop 4
	s_cselect_b64 s[50:51], -1, 0
	s_nop 4
	s_cmpk_gt_u32 s4, 0x7ff
	s_nop 4
	s_cselect_b64 s[48:49], -1, 0
	s_nop 4
	s_cmpk_gt_u32 s4, 0xbff
	s_nop 4
	s_cselect_b64 s[46:47], -1, 0
	s_nop 4
	s_mov_b64 s[52:53], -1
	s_nop 4
	s_and_b64 vcc, exec, s[50:51]
	s_nop 4
	v_add_u32_e32 v109, s6, v119
	s_nop 4
	v_or_b32_e32 v100, s4, v127
	s_waitcnt lgkmcnt(0)
	s_nop 11
	ds_write_b128 v140, v[82:85]
	ds_write_b128 v140, v[86:89] offset:32
	ds_write_b128 v140, v[90:93] offset:64
	ds_write_b128 v140, v[94:97] offset:96
	s_nop 11
	ds_write_b128 v140, v[66:69] offset:128
	ds_write_b128 v140, v[70:73] offset:160
	ds_write_b128 v140, v[74:77] offset:192
	ds_write_b128 v140, v[78:81] offset:224
	s_waitcnt lgkmcnt(0)
	v_add_u32_e32 v112, v128, v100
	v_or_b32_e32 v100, v100, v131
	v_cmp_lt_i32_e64 s[6:7], s3, v100
	s_cbranch_vccz .LBB0_1278
	v_mov_b32_e32 v80, 0x880
	v_cmp_gt_i32_e64 s[52:53], s57, v109
	v_mov_b32_e32 v81, 0x990
	v_mov_b32_e32 v79, 0xaa0
	v_mov_b32_e32 v78, 0xbb0
	ds_read2_b32 v[70:71], v129 offset1:68
	ds_read2_b32 v[72:73], v129 offset0:136 offset1:204
	v_cndmask_b32_e64 v82, v141, v80, s[52:53]
	v_cndmask_b32_e64 v83, v142, v81, s[52:53]
	v_cndmask_b32_e64 v84, v143, v79, s[52:53]
	v_cndmask_b32_e64 v85, v144, v78, s[52:53]
	v_add_u32_e32 v66, 0xfffff000, v109
	v_ashrrev_i32_e32 v68, 8, v109
	v_add_u32_e32 v82, v129, v82
	v_add_u32_e32 v83, v129, v83
	v_add_u32_e32 v84, v129, v84
	v_add_u32_e32 v85, v129, v85
	v_lshrrev_b32_e32 v66, 11, v66
	v_and_b32_e32 v67, 0x7e0, v109
	v_ashrrev_i32_e32 v69, 31, v68
	ds_read_b32 v82, v82
	ds_read_b32 v83, v83
	ds_read_b32 v84, v84
	ds_read_b32 v85, v85
	v_add_u32_e32 v76, 0x100, v67
	v_mad_u64_u32 v[66:67], s[4:5], v66, s59, v[110:111]
	v_lshlrev_b64 v[68:69], 18, v[68:69]
	v_and_b32_e32 v77, 0xe0, v109
	v_cndmask_b32_e64 v75, v67, v69, s[52:53]
	v_cndmask_b32_e64 v74, v66, v68, s[52:53]
	v_cndmask_b32_e64 v86, v145, v147, s[52:53]
	v_cndmask_b32_e64 v87, v76, v77, s[52:53]
	s_waitcnt lgkmcnt(0)
	v_cvt_pk_bf16_f32 v70, v70, v71
	v_cvt_pk_bf16_f32 v71, v72, v73
	v_cvt_pk_bf16_f32 v72, v82, v83
	v_lshl_add_u64 v[74:75], v[74:75], 1, s[24:25]
	v_mad_u64_u32 v[82:83], s[4:5], v86, v112, 0
	v_lshl_add_u64 v[74:75], v[82:83], 1, v[74:75]
	v_lshlrev_b32_e32 v82, 1, v87
	v_mov_b32_e32 v83, v101
	v_cvt_pk_bf16_f32 v73, v84, v85
	v_lshl_add_u64 v[74:75], v[74:75], 0, v[82:83]
	global_store_dwordx4 v[74:75], v[70:73], off
	v_mov_b32_e32 v84, 0x1540
	v_mov_b32_e32 v83, 0x1650
	v_mov_b64_e32 v[70:71], 0x900
	v_mov_b64_e32 v[72:73], 0x900
	v_mov_b32_e32 v82, 0x1760
	v_mov_b32_e32 v71, 0x1870
	v_mov_b64_e32 v[74:75], v[66:67]
	v_mov_b32_e32 v73, v76
	s_and_saveexec_b64 s[4:5], s[52:53]
	s_cbranch_execz .LBB0_1275
	v_mov_b64_e32 v[72:73], 0x100
	v_mov_b32_e32 v78, 0x770
	v_mov_b32_e32 v79, 0x660
	v_mov_b32_e32 v81, 0x550
	v_mov_b32_e32 v80, 0x440
	v_mov_b32_e32 v84, 0x1980
	v_mov_b32_e32 v83, 0x1a90
	v_mov_b32_e32 v82, 0x1ba0
	v_mov_b32_e32 v71, 0x1cb0
	v_mov_b64_e32 v[74:75], v[68:69]
	v_mov_b32_e32 v73, v77

.Lgm_ph15_noprio:
	s_waitcnt vmcnt(0)
	s_barrier
	s_load_dwordx2 s[66:67], s[0:1], 0x178
	s_load_dwordx2 s[68:69], s[0:1], 0x100
	v_and_b32_e32 v201, 0x3ff, v0
	v_readfirstlane_b32 s80, v0
	v_and_b32_e32 v200, 31, v201
	v_bfe_u32 v214, v201, 1, 3
	v_bfe_u32 v213, v201, 5, 1
	v_xor_b32_e32 v214, v214, v213
	v_lshlrev_b32_e32 v214, 4, v214
	s_and_b32 s80, s80, 0x3ff
	s_lshr_b32 s83, s80, 6
	s_lshl_b32 s80, s80, 4
	s_lshr_b32 s84, s83, 1
	s_and_b32 s83, s83, 1
	s_mul_i32 s84, s84, 0x3000
	s_lshl_b32 s83, s83, 13
	s_add_u32 s83, s83, 0xc000
	v_lshlrev_b32_e32 v200, 7, v200
	v_or_b32_e32 v200, v200, v214
	v_add_u32_e32 v215, s84, v200
	v_add_u32_e32 v211, s83, v200
	v_xor_b32_e32 v214, 0x20, v215
	v_xor_b32_e32 v210, 0x20, v211
	v_xor_b32_e32 v213, 0x40, v215
	v_xor_b32_e32 v209, 0x40, v211
	v_xor_b32_e32 v212, 0x60, v215
	v_xor_b32_e32 v208, 0x60, v211
	v_bfe_u32 v200, v201, 4, 3
	v_and_b32_e32 v206, 7, v201
	v_xor_b32_e32 v200, v200, v206
	v_lshlrev_b32_e32 v200, 4, v200
	v_lshrrev_b32_e32 v206, 3, v201
	v_lshl_or_b32 v207, v206, 11, v200
	v_add_u32_e32 v206, 0x10000, v207
	v_add_u32_e32 v205, 0x20000, v207
	v_add_u32_e32 v204, 0x30000, v207
	v_add_u32_e32 v203, 0x40000, v207
	v_add_u32_e32 v202, 0x50000, v207
	s_lshr_b32 s83, s28, 6
	s_and_b32 s84, s28, 63
	s_mov_b32 s79, 0
	s_mul_i32 s84, s84, 0x60000
	s_lshl_b32 s83, s83, 18
	s_waitcnt lgkmcnt(0)
	s_add_u32 s66, s66, s84
	s_addc_u32 s67, s67, 0
	s_add_u32 s68, s68, s83
	s_addc_u32 s69, s69, 0
	s_add_u32 s83, s79, 0
	s_and_b32 s83, s83, 15
	s_lshl_b32 s83, s83, 7
	s_add_u32 s70, s66, s83
	s_addc_u32 s71, s67, 0
	s_add_u32 s72, s68, s83
	s_addc_u32 s73, s69, 0
	s_add_u32 s81, s80, 0x0
	s_add_u32 s82, s80, 0xc000
	s_add_u32 m0, s81, 0x0
	s_nop 0
	global_load_lds_dwordx4 v207, s[70:71]
	s_add_u32 m0, s81, 0x1000
	s_nop 0
	global_load_lds_dwordx4 v206, s[70:71]
	s_add_u32 m0, s81, 0x2000
	s_nop 0
	global_load_lds_dwordx4 v205, s[70:71]
	s_add_u32 m0, s81, 0x3000
	s_nop 0
	global_load_lds_dwordx4 v204, s[70:71]
	s_add_u32 m0, s81, 0x4000
	s_nop 0
	global_load_lds_dwordx4 v203, s[70:71]
	s_add_u32 m0, s81, 0x5000
	s_nop 0
	global_load_lds_dwordx4 v202, s[70:71]
	s_add_u32 m0, s82, 0x0
	s_nop 0
	global_load_lds_dwordx4 v207, s[72:73]
	s_add_u32 m0, s82, 0x1000
	s_nop 0
	global_load_lds_dwordx4 v206, s[72:73]
	s_add_u32 m0, s82, 0x2000
	s_nop 0
	global_load_lds_dwordx4 v205, s[72:73]
	s_add_u32 m0, s82, 0x3000
	s_nop 0
	global_load_lds_dwordx4 v204, s[72:73]
	s_add_u32 s83, s79, 1
	s_and_b32 s83, s83, 15
	s_lshl_b32 s83, s83, 7
	s_add_u32 s70, s66, s83
	s_addc_u32 s71, s67, 0
	s_add_u32 s72, s68, s83
	s_addc_u32 s73, s69, 0
	s_add_u32 s81, s80, 0x6000
	s_add_u32 s82, s80, 0x10000
	s_add_u32 m0, s81, 0x0
	s_nop 0
	global_load_lds_dwordx4 v207, s[70:71]
	s_add_u32 m0, s81, 0x1000
	s_nop 0
	global_load_lds_dwordx4 v206, s[70:71]
	s_add_u32 m0, s81, 0x2000
	s_nop 0
	global_load_lds_dwordx4 v205, s[70:71]
	s_add_u32 m0, s81, 0x3000
	s_nop 0
	global_load_lds_dwordx4 v204, s[70:71]
	s_add_u32 m0, s81, 0x4000
	s_nop 0
	global_load_lds_dwordx4 v203, s[70:71]
	v_mov_b32_e32 v2, 0
	v_mov_b32_e32 v3, 0
	v_mov_b32_e32 v4, 0
	v_mov_b32_e32 v5, 0
	v_mov_b32_e32 v6, 0
	v_mov_b32_e32 v7, 0
	v_mov_b32_e32 v8, 0
	v_mov_b32_e32 v9, 0
	v_mov_b32_e32 v10, 0
	v_mov_b32_e32 v11, 0
	v_mov_b32_e32 v12, 0
	v_mov_b32_e32 v13, 0
	v_mov_b32_e32 v14, 0
	v_mov_b32_e32 v15, 0
	v_mov_b32_e32 v16, 0
	v_mov_b32_e32 v17, 0
	v_mov_b32_e32 v18, 0
	v_mov_b32_e32 v19, 0
	v_mov_b32_e32 v20, 0
	v_mov_b32_e32 v21, 0
	v_mov_b32_e32 v22, 0
	v_mov_b32_e32 v23, 0
	v_mov_b32_e32 v24, 0
	v_mov_b32_e32 v25, 0
	v_mov_b32_e32 v26, 0
	v_mov_b32_e32 v27, 0
	v_mov_b32_e32 v28, 0
	v_mov_b32_e32 v29, 0
	v_mov_b32_e32 v30, 0
	v_mov_b32_e32 v31, 0
	v_mov_b32_e32 v32, 0
	v_mov_b32_e32 v33, 0
	v_mov_b32_e32 v34, 0
	v_mov_b32_e32 v35, 0
	v_mov_b32_e32 v36, 0
	v_mov_b32_e32 v37, 0
	v_mov_b32_e32 v38, 0
	v_mov_b32_e32 v39, 0
	v_mov_b32_e32 v40, 0
	v_mov_b32_e32 v41, 0
	v_mov_b32_e32 v42, 0
	v_mov_b32_e32 v43, 0
	v_mov_b32_e32 v44, 0
	v_mov_b32_e32 v45, 0
	v_mov_b32_e32 v46, 0
	v_mov_b32_e32 v47, 0
	v_mov_b32_e32 v48, 0
	v_mov_b32_e32 v49, 0
	v_mov_b32_e32 v50, 0
	v_mov_b32_e32 v51, 0
	v_mov_b32_e32 v52, 0
	v_mov_b32_e32 v53, 0
	v_mov_b32_e32 v54, 0
	v_mov_b32_e32 v55, 0
	v_mov_b32_e32 v56, 0
	v_mov_b32_e32 v57, 0
	v_mov_b32_e32 v58, 0
	v_mov_b32_e32 v59, 0
	v_mov_b32_e32 v60, 0
	v_mov_b32_e32 v61, 0
	v_mov_b32_e32 v62, 0
	v_mov_b32_e32 v63, 0
	v_mov_b32_e32 v64, 0
	v_mov_b32_e32 v65, 0
	v_mov_b32_e32 v66, 0
	v_mov_b32_e32 v67, 0
	v_mov_b32_e32 v68, 0
	v_mov_b32_e32 v69, 0
	v_mov_b32_e32 v70, 0
	v_mov_b32_e32 v71, 0
	v_mov_b32_e32 v72, 0
	v_mov_b32_e32 v73, 0
	v_mov_b32_e32 v74, 0
	v_mov_b32_e32 v75, 0
	v_mov_b32_e32 v76, 0
	v_mov_b32_e32 v77, 0
	v_mov_b32_e32 v78, 0
	v_mov_b32_e32 v79, 0
	v_mov_b32_e32 v80, 0
	v_mov_b32_e32 v81, 0
	v_mov_b32_e32 v82, 0
	v_mov_b32_e32 v83, 0
	v_mov_b32_e32 v84, 0
	v_mov_b32_e32 v85, 0
	v_mov_b32_e32 v86, 0
	v_mov_b32_e32 v87, 0
	v_mov_b32_e32 v88, 0
	v_mov_b32_e32 v89, 0
	v_mov_b32_e32 v90, 0
	v_mov_b32_e32 v91, 0
	v_mov_b32_e32 v92, 0
	v_mov_b32_e32 v93, 0
	v_mov_b32_e32 v94, 0
	v_mov_b32_e32 v95, 0
	v_mov_b32_e32 v96, 0
	v_mov_b32_e32 v97, 0
	s_waitcnt vmcnt(5)
	s_barrier
	ds_read_b128 v[240:243], v211 offset:0
	ds_read_b128 v[252:255], v215 offset:0
	ds_read_b128 v[236:239], v211 offset:4096
	ds_read_b128 v[248:251], v215 offset:4096
	ds_read_b128 v[244:247], v215 offset:8192
	s_mov_b32 s78, 0

.LBB0_1992:
	s_ashr_i32 s4, s35, 31
	s_lshr_b32 s4, s4, 26
	s_add_i32 s4, s35, s4
	s_ashr_i32 s6, s4, 6
	s_and_b32 s4, s4, 0x3ffffc0
	s_sub_i32 s4, s35, s4
	s_mulk_i32 s4, 0xc0
	v_add_u32_e32 v2, s4, v112
	s_lshr_b32 s7, s4, 6
	s_lshl_b32 s5, s6, 7
	v_ashrrev_i32_e32 v3, 31, v2
	s_add_i32 s7, s7, s6
	v_lshlrev_b64 v[2:3], 11, v[2:3]
	v_or_b32_e32 v4, s5, v112
	s_lshl_b32 s6, s7, 6
	s_lshl_b32 s7, s7, 7
	v_ashrrev_i32_e32 v5, 31, v4
	v_lshl_add_u64 v[104:105], v[100:101], 0, v[2:3]
	s_and_b32 s14, s7, 0x780
	v_readfirstlane_b32 s7, v113
	v_lshlrev_b64 v[4:5], 11, v[4:5]
	v_lshl_add_u64 v[2:3], v[104:105], 0, s[14:15]
	s_mov_b32 m0, s7
	v_readfirstlane_b32 s7, v125
	v_lshl_add_u64 v[106:107], v[102:103], 0, v[4:5]
	s_getreg_b32 s83, hwreg(HW_REG_HW_ID, 0, 4)
	s_bitcmp1_b32 s83, 0
	s_cbranch_scc0 .Lgm_ph17_noprio
	s_setprio 1
.Lgm_ph17_noprio:
	s_waitcnt vmcnt(0)
	s_barrier
	s_load_dwordx2 s[66:67], s[0:1], 0x90
	s_load_dwordx2 s[68:69], s[0:1], 0xc0
	v_and_b32_e32 v201, 0x3ff, v0
	v_readfirstlane_b32 s80, v0
	v_and_b32_e32 v200, 31, v201
	v_bfe_u32 v214, v201, 1, 3
	v_bfe_u32 v213, v201, 5, 1
	v_xor_b32_e32 v214, v214, v213
	v_lshlrev_b32_e32 v214, 4, v214
	s_and_b32 s80, s80, 0x3ff
	s_lshr_b32 s83, s80, 6
	s_lshl_b32 s80, s80, 4
	s_lshr_b32 s84, s83, 1
	s_and_b32 s83, s83, 1
	s_mul_i32 s84, s84, 0x3000
	s_lshl_b32 s83, s83, 13
	s_add_u32 s83, s83, 0xc000
	v_lshlrev_b32_e32 v200, 7, v200
	v_or_b32_e32 v200, v200, v214
	v_add_u32_e32 v215, s84, v200
	v_add_u32_e32 v211, s83, v200
	v_xor_b32_e32 v214, 0x20, v215
	v_xor_b32_e32 v210, 0x20, v211
	v_xor_b32_e32 v213, 0x40, v215
	v_xor_b32_e32 v209, 0x40, v211
	v_xor_b32_e32 v212, 0x60, v215
	v_xor_b32_e32 v208, 0x60, v211
	v_bfe_u32 v200, v201, 4, 3
	v_and_b32_e32 v206, 7, v201
	v_xor_b32_e32 v200, v200, v206
	v_lshlrev_b32_e32 v200, 4, v200
	v_lshrrev_b32_e32 v206, 3, v201
	v_lshl_or_b32 v207, v206, 11, v200
	v_add_u32_e32 v206, 0x10000, v207
	v_add_u32_e32 v205, 0x20000, v207
	v_add_u32_e32 v204, 0x30000, v207
	v_add_u32_e32 v203, 0x40000, v207
	v_add_u32_e32 v202, 0x50000, v207
	s_lshr_b32 s83, s35, 6
	s_and_b32 s84, s35, 63
	s_mov_b32 s79, 0
	s_mul_i32 s84, s84, 0x60000
	s_lshl_b32 s83, s83, 18
	s_add_u32 s83, s83, 0x400000
	s_waitcnt lgkmcnt(0)
	s_add_u32 s66, s66, s84
	s_addc_u32 s67, s67, 0
	s_add_u32 s68, s68, s83
	s_addc_u32 s69, s69, 0
	s_add_u32 s83, s79, 0
	s_and_b32 s83, s83, 15
	s_lshl_b32 s83, s83, 7
	s_add_u32 s70, s66, s83
	s_addc_u32 s71, s67, 0
	s_add_u32 s72, s68, s83
	s_addc_u32 s73, s69, 0
	s_add_u32 s81, s80, 0x0
	s_add_u32 s82, s80, 0xc000
	s_add_u32 m0, s81, 0x0
	s_nop 0
	global_load_lds_dwordx4 v207, s[70:71]
	s_add_u32 m0, s81, 0x1000
	s_nop 0
	global_load_lds_dwordx4 v206, s[70:71]
	s_add_u32 m0, s81, 0x2000
	s_nop 0
	global_load_lds_dwordx4 v205, s[70:71]
	s_add_u32 m0, s81, 0x3000
	s_nop 0
	global_load_lds_dwordx4 v204, s[70:71]
	s_add_u32 m0, s81, 0x4000
	s_nop 0
	global_load_lds_dwordx4 v203, s[70:71]
	s_add_u32 m0, s81, 0x5000
	s_nop 0
	global_load_lds_dwordx4 v202, s[70:71]
	s_add_u32 m0, s82, 0x0
	s_nop 0
	global_load_lds_dwordx4 v207, s[72:73]
	s_add_u32 m0, s82, 0x1000
	s_nop 0
	global_load_lds_dwordx4 v206, s[72:73]
	s_add_u32 m0, s82, 0x2000
	s_nop 0
	global_load_lds_dwordx4 v205, s[72:73]
	s_add_u32 m0, s82, 0x3000
	s_nop 0
	global_load_lds_dwordx4 v204, s[72:73]
	s_add_u32 s83, s79, 1
	s_and_b32 s83, s83, 15
	s_lshl_b32 s83, s83, 7
	s_add_u32 s70, s66, s83
	s_addc_u32 s71, s67, 0
	s_add_u32 s72, s68, s83
	s_addc_u32 s73, s69, 0
	s_add_u32 s81, s80, 0x6000
	s_add_u32 s82, s80, 0x10000
	s_add_u32 m0, s81, 0x0
	s_nop 0
	global_load_lds_dwordx4 v207, s[70:71]
	s_add_u32 m0, s81, 0x1000
	s_nop 0
	global_load_lds_dwordx4 v206, s[70:71]
	s_add_u32 m0, s81, 0x2000
	s_nop 0
	global_load_lds_dwordx4 v205, s[70:71]
	s_add_u32 m0, s81, 0x3000
	s_nop 0
	global_load_lds_dwordx4 v204, s[70:71]
	s_add_u32 m0, s81, 0x4000
	s_nop 0
	global_load_lds_dwordx4 v203, s[70:71]
	v_mov_b32_e32 v2, 0
	v_mov_b32_e32 v3, 0
	v_mov_b32_e32 v4, 0
	v_mov_b32_e32 v5, 0
	v_mov_b32_e32 v6, 0
	v_mov_b32_e32 v7, 0
	v_mov_b32_e32 v8, 0
	v_mov_b32_e32 v9, 0
	v_mov_b32_e32 v10, 0
	v_mov_b32_e32 v11, 0
	v_mov_b32_e32 v12, 0
	v_mov_b32_e32 v13, 0
	v_mov_b32_e32 v14, 0
	v_mov_b32_e32 v15, 0
	v_mov_b32_e32 v16, 0
	v_mov_b32_e32 v17, 0
	v_mov_b32_e32 v18, 0
	v_mov_b32_e32 v19, 0
	v_mov_b32_e32 v20, 0
	v_mov_b32_e32 v21, 0
	v_mov_b32_e32 v22, 0
	v_mov_b32_e32 v23, 0
	v_mov_b32_e32 v24, 0
	v_mov_b32_e32 v25, 0
	v_mov_b32_e32 v26, 0
	v_mov_b32_e32 v27, 0
	v_mov_b32_e32 v28, 0
	v_mov_b32_e32 v29, 0
	v_mov_b32_e32 v30, 0
	v_mov_b32_e32 v31, 0
	v_mov_b32_e32 v32, 0
	v_mov_b32_e32 v33, 0
	v_mov_b32_e32 v34, 0
	v_mov_b32_e32 v35, 0
	v_mov_b32_e32 v36, 0
	v_mov_b32_e32 v37, 0
	v_mov_b32_e32 v38, 0
	v_mov_b32_e32 v39, 0
	v_mov_b32_e32 v40, 0
	v_mov_b32_e32 v41, 0
	v_mov_b32_e32 v42, 0
	v_mov_b32_e32 v43, 0
	v_mov_b32_e32 v44, 0
	v_mov_b32_e32 v45, 0
	v_mov_b32_e32 v46, 0
	v_mov_b32_e32 v47, 0
	v_mov_b32_e32 v48, 0
	v_mov_b32_e32 v49, 0
	v_mov_b32_e32 v50, 0
	v_mov_b32_e32 v51, 0
	v_mov_b32_e32 v52, 0
	v_mov_b32_e32 v53, 0
	v_mov_b32_e32 v54, 0
	v_mov_b32_e32 v55, 0
	v_mov_b32_e32 v56, 0
	v_mov_b32_e32 v57, 0
	v_mov_b32_e32 v58, 0
	v_mov_b32_e32 v59, 0
	v_mov_b32_e32 v60, 0
	v_mov_b32_e32 v61, 0
	v_mov_b32_e32 v62, 0
	v_mov_b32_e32 v63, 0
	v_mov_b32_e32 v64, 0
	v_mov_b32_e32 v65, 0
	v_mov_b32_e32 v66, 0
	v_mov_b32_e32 v67, 0
	v_mov_b32_e32 v68, 0
	v_mov_b32_e32 v69, 0
	v_mov_b32_e32 v70, 0
	v_mov_b32_e32 v71, 0
	v_mov_b32_e32 v72, 0
	v_mov_b32_e32 v73, 0
	v_mov_b32_e32 v74, 0
	v_mov_b32_e32 v75, 0
	v_mov_b32_e32 v76, 0
	v_mov_b32_e32 v77, 0
	v_mov_b32_e32 v78, 0
	v_mov_b32_e32 v79, 0
	v_mov_b32_e32 v80, 0
	v_mov_b32_e32 v81, 0
	v_mov_b32_e32 v82, 0
	v_mov_b32_e32 v83, 0
	v_mov_b32_e32 v84, 0
	v_mov_b32_e32 v85, 0
	v_mov_b32_e32 v86, 0
	v_mov_b32_e32 v87, 0
	v_mov_b32_e32 v88, 0
	v_mov_b32_e32 v89, 0
	v_mov_b32_e32 v90, 0
	v_mov_b32_e32 v91, 0
	v_mov_b32_e32 v92, 0
	v_mov_b32_e32 v93, 0
	v_mov_b32_e32 v94, 0
	v_mov_b32_e32 v95, 0
	v_mov_b32_e32 v96, 0
	v_mov_b32_e32 v97, 0
	s_waitcnt vmcnt(5)
	s_barrier
	ds_read_b128 v[240:243], v211 offset:0
	ds_read_b128 v[252:255], v215 offset:0
	ds_read_b128 v[236:239], v211 offset:4096
	ds_read_b128 v[248:251], v215 offset:4096
	ds_read_b128 v[244:247], v215 offset:8192
	s_mov_b32 s78, 0
.Lgm_ph17_loop:
	s_waitcnt lgkmcnt(1)
	v_mfma_f32_32x32x16_bf16 v[82:97], v[240:243], v[252:255], v[82:97]
	ds_read_b128 v[220:223], v210 offset:0
	s_add_u32 m0, s81, 0x5000
	s_nop 0
	global_load_lds_dwordx4 v202, s[70:71]
	v_mfma_f32_32x32x16_bf16 v[66:81], v[236:239], v[252:255], v[66:81]
	ds_read_b128 v[232:235], v214 offset:0
	s_add_u32 m0, s82, 0x0
	s_nop 0
	global_load_lds_dwordx4 v207, s[72:73]
	v_mfma_f32_32x32x16_bf16 v[50:65], v[240:243], v[248:251], v[50:65]
	ds_read_b128 v[216:219], v210 offset:4096
	s_add_u32 m0, s82, 0x1000
	s_nop 0
	global_load_lds_dwordx4 v206, s[72:73]
	v_mfma_f32_32x32x16_bf16 v[34:49], v[236:239], v[248:251], v[34:49]
	ds_read_b128 v[228:231], v214 offset:4096
	s_add_u32 m0, s82, 0x2000
	s_nop 0
	global_load_lds_dwordx4 v205, s[72:73]
	s_waitcnt lgkmcnt(4)
	v_mfma_f32_32x32x16_bf16 v[18:33], v[240:243], v[244:247], v[18:33]
	ds_read_b128 v[224:227], v214 offset:8192
	v_mfma_f32_32x32x16_bf16 v[2:17], v[236:239], v[244:247], v[2:17]
	s_add_u32 m0, s82, 0x3000
	s_nop 0
	global_load_lds_dwordx4 v204, s[72:73]
	s_waitcnt lgkmcnt(1)
	v_mfma_f32_32x32x16_bf16 v[82:97], v[220:223], v[232:235], v[82:97]
	ds_read_b128 v[240:243], v209 offset:0
	v_mfma_f32_32x32x16_bf16 v[66:81], v[216:219], v[232:235], v[66:81]
	ds_read_b128 v[252:255], v213 offset:0
	v_mfma_f32_32x32x16_bf16 v[50:65], v[220:223], v[228:231], v[50:65]
	ds_read_b128 v[236:239], v209 offset:4096
	v_mfma_f32_32x32x16_bf16 v[34:49], v[216:219], v[228:231], v[34:49]
	ds_read_b128 v[248:251], v213 offset:4096
	s_waitcnt lgkmcnt(4)
	v_mfma_f32_32x32x16_bf16 v[18:33], v[220:223], v[224:227], v[18:33]
	ds_read_b128 v[244:247], v213 offset:8192
	v_mfma_f32_32x32x16_bf16 v[2:17], v[216:219], v[224:227], v[2:17]
	s_waitcnt lgkmcnt(1)
	v_mfma_f32_32x32x16_bf16 v[82:97], v[240:243], v[252:255], v[82:97]
	ds_read_b128 v[220:223], v208 offset:0
	s_add_u32 s83, s79, s78
	s_add_u32 s83, s83, 2
	s_and_b32 s83, s83, 15
	v_mfma_f32_32x32x16_bf16 v[66:81], v[236:239], v[252:255], v[66:81]
	ds_read_b128 v[232:235], v212 offset:0
	s_lshl_b32 s83, s83, 7
	s_add_u32 s70, s66, s83
	v_mfma_f32_32x32x16_bf16 v[50:65], v[240:243], v[248:251], v[50:65]
	ds_read_b128 v[216:219], v208 offset:4096
	s_addc_u32 s71, s67, 0
	s_add_u32 s72, s68, s83
	v_mfma_f32_32x32x16_bf16 v[34:49], v[236:239], v[248:251], v[34:49]
	ds_read_b128 v[228:231], v212 offset:4096
	s_addc_u32 s73, s69, 0
	s_add_u32 s81, s80, 0x0
	s_add_u32 s82, s80, 0xc000
	s_waitcnt lgkmcnt(4)
	v_mfma_f32_32x32x16_bf16 v[18:33], v[240:243], v[244:247], v[18:33]
	ds_read_b128 v[224:227], v212 offset:8192
	v_mfma_f32_32x32x16_bf16 v[2:17], v[236:239], v[244:247], v[2:17]
	s_waitcnt vmcnt(0) lgkmcnt(0)
	s_barrier
	v_mfma_f32_32x32x16_bf16 v[82:97], v[220:223], v[232:235], v[82:97]
	s_add_u32 m0, s81, 0x0
	ds_read_b128 v[240:243], v211 offset:16384
	global_load_lds_dwordx4 v207, s[70:71]
	v_mfma_f32_32x32x16_bf16 v[66:81], v[216:219], v[232:235], v[66:81]
	s_add_u32 m0, s81, 0x1000
	ds_read_b128 v[252:255], v215 offset:24576
	global_load_lds_dwordx4 v206, s[70:71]
	v_mfma_f32_32x32x16_bf16 v[50:65], v[220:223], v[228:231], v[50:65]
	s_add_u32 m0, s81, 0x2000
	ds_read_b128 v[236:239], v211 offset:20480
	global_load_lds_dwordx4 v205, s[70:71]
	v_mfma_f32_32x32x16_bf16 v[34:49], v[216:219], v[228:231], v[34:49]
	s_add_u32 m0, s81, 0x3000
	ds_read_b128 v[248:251], v215 offset:28672
	global_load_lds_dwordx4 v204, s[70:71]
	v_mfma_f32_32x32x16_bf16 v[18:33], v[220:223], v[224:227], v[18:33]
	s_add_u32 m0, s81, 0x4000
	ds_read_b128 v[244:247], v215 offset:32768
	global_load_lds_dwordx4 v203, s[70:71]
	v_mfma_f32_32x32x16_bf16 v[2:17], v[216:219], v[224:227], v[2:17]
	s_waitcnt lgkmcnt(1)
	v_mfma_f32_32x32x16_bf16 v[82:97], v[240:243], v[252:255], v[82:97]
	ds_read_b128 v[220:223], v210 offset:16384
	s_add_u32 m0, s81, 0x5000
	s_nop 0
	global_load_lds_dwordx4 v202, s[70:71]
	v_mfma_f32_32x32x16_bf16 v[66:81], v[236:239], v[252:255], v[66:81]
	ds_read_b128 v[232:235], v214 offset:24576
	s_add_u32 m0, s82, 0x0
	s_nop 0
	global_load_lds_dwordx4 v207, s[72:73]
	v_mfma_f32_32x32x16_bf16 v[50:65], v[240:243], v[248:251], v[50:65]
	ds_read_b128 v[216:219], v210 offset:20480
	s_add_u32 m0, s82, 0x1000
	s_nop 0
	global_load_lds_dwordx4 v206, s[72:73]
	v_mfma_f32_32x32x16_bf16 v[34:49], v[236:239], v[248:251], v[34:49]
	ds_read_b128 v[228:231], v214 offset:28672
	s_add_u32 m0, s82, 0x2000
	s_nop 0
	global_load_lds_dwordx4 v205, s[72:73]
	s_waitcnt lgkmcnt(4)
	v_mfma_f32_32x32x16_bf16 v[18:33], v[240:243], v[244:247], v[18:33]
	ds_read_b128 v[224:227], v214 offset:32768
	v_mfma_f32_32x32x16_bf16 v[2:17], v[236:239], v[244:247], v[2:17]
	s_add_u32 m0, s82, 0x3000
	s_nop 0
	global_load_lds_dwordx4 v204, s[72:73]
	s_waitcnt lgkmcnt(1)
	v_mfma_f32_32x32x16_bf16 v[82:97], v[220:223], v[232:235], v[82:97]
	ds_read_b128 v[240:243], v209 offset:16384
	v_mfma_f32_32x32x16_bf16 v[66:81], v[216:219], v[232:235], v[66:81]
	ds_read_b128 v[252:255], v213 offset:24576
	v_mfma_f32_32x32x16_bf16 v[50:65], v[220:223], v[228:231], v[50:65]
	ds_read_b128 v[236:239], v209 offset:20480
	v_mfma_f32_32x32x16_bf16 v[34:49], v[216:219], v[228:231], v[34:49]
	ds_read_b128 v[248:251], v213 offset:28672
	s_waitcnt lgkmcnt(4)
	v_mfma_f32_32x32x16_bf16 v[18:33], v[220:223], v[224:227], v[18:33]
	ds_read_b128 v[244:247], v213 offset:32768
	v_mfma_f32_32x32x16_bf16 v[2:17], v[216:219], v[224:227], v[2:17]
	s_waitcnt lgkmcnt(1)
	v_mfma_f32_32x32x16_bf16 v[82:97], v[240:243], v[252:255], v[82:97]
	ds_read_b128 v[220:223], v208 offset:16384
	s_add_u32 s83, s79, s78
	s_add_u32 s83, s83, 3
	s_and_b32 s83, s83, 15
	v_mfma_f32_32x32x16_bf16 v[66:81], v[236:239], v[252:255], v[66:81]
	ds_read_b128 v[232:235], v212 offset:24576
	s_lshl_b32 s83, s83, 7
	s_add_u32 s70, s66, s83
	v_mfma_f32_32x32x16_bf16 v[50:65], v[240:243], v[248:251], v[50:65]
	ds_read_b128 v[216:219], v208 offset:20480
	s_addc_u32 s71, s67, 0
	s_add_u32 s72, s68, s83
	v_mfma_f32_32x32x16_bf16 v[34:49], v[236:239], v[248:251], v[34:49]
	ds_read_b128 v[228:231], v212 offset:28672
	s_addc_u32 s73, s69, 0
	s_add_u32 s81, s80, 0x6000
	s_add_u32 s82, s80, 0x10000
	s_waitcnt lgkmcnt(4)
	v_mfma_f32_32x32x16_bf16 v[18:33], v[240:243], v[244:247], v[18:33]
	ds_read_b128 v[224:227], v212 offset:32768
	v_mfma_f32_32x32x16_bf16 v[2:17], v[236:239], v[244:247], v[2:17]
	s_waitcnt vmcnt(0) lgkmcnt(0)
	s_barrier
	v_mfma_f32_32x32x16_bf16 v[82:97], v[220:223], v[232:235], v[82:97]
	s_add_u32 m0, s81, 0x0
	ds_read_b128 v[240:243], v211 offset:0
	global_load_lds_dwordx4 v207, s[70:71]
	v_mfma_f32_32x32x16_bf16 v[66:81], v[216:219], v[232:235], v[66:81]
	s_add_u32 m0, s81, 0x1000
	ds_read_b128 v[252:255], v215 offset:0
	global_load_lds_dwordx4 v206, s[70:71]
	v_mfma_f32_32x32x16_bf16 v[50:65], v[220:223], v[228:231], v[50:65]
	s_add_u32 m0, s81, 0x2000
	ds_read_b128 v[236:239], v211 offset:4096
	global_load_lds_dwordx4 v205, s[70:71]
	v_mfma_f32_32x32x16_bf16 v[34:49], v[216:219], v[228:231], v[34:49]
	s_add_u32 m0, s81, 0x3000
	ds_read_b128 v[248:251], v215 offset:4096
	global_load_lds_dwordx4 v204, s[70:71]
	v_mfma_f32_32x32x16_bf16 v[18:33], v[220:223], v[224:227], v[18:33]
	s_add_u32 m0, s81, 0x4000
	ds_read_b128 v[244:247], v215 offset:8192
	global_load_lds_dwordx4 v203, s[70:71]
	v_mfma_f32_32x32x16_bf16 v[2:17], v[216:219], v[224:227], v[2:17]
	s_add_u32 s78, s78, 2
	s_cmp_lt_u32 s78, 14
	s_cbranch_scc1 .Lgm_ph17_loop
	s_waitcnt lgkmcnt(1)
	v_mfma_f32_32x32x16_bf16 v[82:97], v[240:243], v[252:255], v[82:97]
	ds_read_b128 v[220:223], v210 offset:0
	s_add_u32 m0, s81, 0x5000
	s_nop 0
	global_load_lds_dwordx4 v202, s[70:71]
	v_mfma_f32_32x32x16_bf16 v[66:81], v[236:239], v[252:255], v[66:81]
	ds_read_b128 v[232:235], v214 offset:0
	s_add_u32 m0, s82, 0x0
	s_nop 0
	global_load_lds_dwordx4 v207, s[72:73]
	v_mfma_f32_32x32x16_bf16 v[50:65], v[240:243], v[248:251], v[50:65]
	ds_read_b128 v[216:219], v210 offset:4096
	s_add_u32 m0, s82, 0x1000
	s_nop 0
	global_load_lds_dwordx4 v206, s[72:73]
	v_mfma_f32_32x32x16_bf16 v[34:49], v[236:239], v[248:251], v[34:49]
	ds_read_b128 v[228:231], v214 offset:4096
	s_add_u32 m0, s82, 0x2000
	s_nop 0
	global_load_lds_dwordx4 v205, s[72:73]
	s_waitcnt lgkmcnt(4)
	v_mfma_f32_32x32x16_bf16 v[18:33], v[240:243], v[244:247], v[18:33]
	ds_read_b128 v[224:227], v214 offset:8192
	v_mfma_f32_32x32x16_bf16 v[2:17], v[236:239], v[244:247], v[2:17]
	s_add_u32 m0, s82, 0x3000
	s_nop 0
	global_load_lds_dwordx4 v204, s[72:73]
	s_waitcnt lgkmcnt(1)
	v_mfma_f32_32x32x16_bf16 v[82:97], v[220:223], v[232:235], v[82:97]
	ds_read_b128 v[240:243], v209 offset:0
	v_mfma_f32_32x32x16_bf16 v[66:81], v[216:219], v[232:235], v[66:81]
	ds_read_b128 v[252:255], v213 offset:0
	v_mfma_f32_32x32x16_bf16 v[50:65], v[220:223], v[228:231], v[50:65]
	ds_read_b128 v[236:239], v209 offset:4096
	v_mfma_f32_32x32x16_bf16 v[34:49], v[216:219], v[228:231], v[34:49]
	ds_read_b128 v[248:251], v213 offset:4096
	s_waitcnt lgkmcnt(4)
	v_mfma_f32_32x32x16_bf16 v[18:33], v[220:223], v[224:227], v[18:33]
	ds_read_b128 v[244:247], v213 offset:8192
	v_mfma_f32_32x32x16_bf16 v[2:17], v[216:219], v[224:227], v[2:17]
	s_waitcnt lgkmcnt(1)
	v_mfma_f32_32x32x16_bf16 v[82:97], v[240:243], v[252:255], v[82:97]
	ds_read_b128 v[220:223], v208 offset:0
	v_mfma_f32_32x32x16_bf16 v[66:81], v[236:239], v[252:255], v[66:81]
	ds_read_b128 v[232:235], v212 offset:0
	v_mfma_f32_32x32x16_bf16 v[50:65], v[240:243], v[248:251], v[50:65]
	ds_read_b128 v[216:219], v208 offset:4096
	v_mfma_f32_32x32x16_bf16 v[34:49], v[236:239], v[248:251], v[34:49]
	ds_read_b128 v[228:231], v212 offset:4096
	s_waitcnt lgkmcnt(4)
	v_mfma_f32_32x32x16_bf16 v[18:33], v[240:243], v[244:247], v[18:33]
	ds_read_b128 v[224:227], v212 offset:8192
	v_mfma_f32_32x32x16_bf16 v[2:17], v[236:239], v[244:247], v[2:17]
	s_waitcnt vmcnt(0) lgkmcnt(0)
	s_barrier
	v_mfma_f32_32x32x16_bf16 v[82:97], v[220:223], v[232:235], v[82:97]
	ds_read_b128 v[240:243], v211 offset:16384
	v_mfma_f32_32x32x16_bf16 v[66:81], v[216:219], v[232:235], v[66:81]
	ds_read_b128 v[252:255], v215 offset:24576
	v_mfma_f32_32x32x16_bf16 v[50:65], v[220:223], v[228:231], v[50:65]
	ds_read_b128 v[236:239], v211 offset:20480
	v_mfma_f32_32x32x16_bf16 v[34:49], v[216:219], v[228:231], v[34:49]
	ds_read_b128 v[248:251], v215 offset:28672
	v_mfma_f32_32x32x16_bf16 v[18:33], v[220:223], v[224:227], v[18:33]
	ds_read_b128 v[244:247], v215 offset:32768
	v_mfma_f32_32x32x16_bf16 v[2:17], v[216:219], v[224:227], v[2:17]
	s_waitcnt lgkmcnt(1)
	v_mfma_f32_32x32x16_bf16 v[82:97], v[240:243], v[252:255], v[82:97]
	ds_read_b128 v[220:223], v210 offset:16384
	v_mfma_f32_32x32x16_bf16 v[66:81], v[236:239], v[252:255], v[66:81]
	ds_read_b128 v[232:235], v214 offset:24576
	v_mfma_f32_32x32x16_bf16 v[50:65], v[240:243], v[248:251], v[50:65]
	ds_read_b128 v[216:219], v210 offset:20480
	v_mfma_f32_32x32x16_bf16 v[34:49], v[236:239], v[248:251], v[34:49]
	ds_read_b128 v[228:231], v214 offset:28672
	s_waitcnt lgkmcnt(4)
	v_mfma_f32_32x32x16_bf16 v[18:33], v[240:243], v[244:247], v[18:33]
	ds_read_b128 v[224:227], v214 offset:32768
	v_mfma_f32_32x32x16_bf16 v[2:17], v[236:239], v[244:247], v[2:17]
	s_waitcnt lgkmcnt(1)
	v_mfma_f32_32x32x16_bf16 v[82:97], v[220:223], v[232:235], v[82:97]
	ds_read_b128 v[240:243], v209 offset:16384
	v_mfma_f32_32x32x16_bf16 v[66:81], v[216:219], v[232:235], v[66:81]
	ds_read_b128 v[252:255], v213 offset:24576
	v_mfma_f32_32x32x16_bf16 v[50:65], v[220:223], v[228:231], v[50:65]
	ds_read_b128 v[236:239], v209 offset:20480
	v_mfma_f32_32x32x16_bf16 v[34:49], v[216:219], v[228:231], v[34:49]
	ds_read_b128 v[248:251], v213 offset:28672
	s_waitcnt lgkmcnt(4)
	v_mfma_f32_32x32x16_bf16 v[18:33], v[220:223], v[224:227], v[18:33]
	ds_read_b128 v[244:247], v213 offset:32768
	v_mfma_f32_32x32x16_bf16 v[2:17], v[216:219], v[224:227], v[2:17]
	s_waitcnt lgkmcnt(1)
	v_mfma_f32_32x32x16_bf16 v[82:97], v[240:243], v[252:255], v[82:97]
	ds_read_b128 v[220:223], v208 offset:16384
	v_mfma_f32_32x32x16_bf16 v[66:81], v[236:239], v[252:255], v[66:81]
	ds_read_b128 v[232:235], v212 offset:24576
	v_mfma_f32_32x32x16_bf16 v[50:65], v[240:243], v[248:251], v[50:65]
	ds_read_b128 v[216:219], v208 offset:20480
	v_mfma_f32_32x32x16_bf16 v[34:49], v[236:239], v[248:251], v[34:49]
	ds_read_b128 v[228:231], v212 offset:28672
	s_waitcnt lgkmcnt(4)
	v_mfma_f32_32x32x16_bf16 v[18:33], v[240:243], v[244:247], v[18:33]
	ds_read_b128 v[224:227], v212 offset:32768
	v_mfma_f32_32x32x16_bf16 v[2:17], v[236:239], v[244:247], v[2:17]
	s_waitcnt vmcnt(0) lgkmcnt(0)
	s_barrier
	v_mfma_f32_32x32x16_bf16 v[82:97], v[220:223], v[232:235], v[82:97]
	v_mfma_f32_32x32x16_bf16 v[66:81], v[216:219], v[232:235], v[66:81]
	v_mfma_f32_32x32x16_bf16 v[50:65], v[220:223], v[228:231], v[50:65]
	v_mfma_f32_32x32x16_bf16 v[34:49], v[216:219], v[228:231], v[34:49]
	v_mfma_f32_32x32x16_bf16 v[18:33], v[220:223], v[224:227], v[18:33]
	v_mfma_f32_32x32x16_bf16 v[2:17], v[216:219], v[224:227], v[2:17]
	s_nop 7
	s_nop 7
	s_setprio 0
	v_add_u32_e32 v144, v116, v120
	s_nop 4
	v_add_u32_e32 v145, v116, v121
	s_nop 4
	v_add_u32_e32 v147, v116, v122
	s_nop 4
	v_or_b32_e32 v143, s5, v123
	s_nop 4
	v_cmp_lt_i32_e64 s[6:7], s3, v143
	s_nop 4
	v_add_u32_e32 v98, v118, v122
	s_nop 4
	s_waitcnt lgkmcnt(0)
	v_add_u32_e32 v106, s4, v115
	v_ashrrev_i32_e32 v107, 31, v106
	v_lshlrev_b64 v[110:111], 11, v[106:107]
	v_or_b32_e32 v104, v143, v124
	v_lshl_add_u64 v[108:109], s[10:11], 0, v[110:111]
	s_and_saveexec_b64 s[4:5], s[6:7]
	s_xor_b64 s[4:5], exec, s[4:5]
	s_cbranch_execz .LBB0_1996
	v_mul_f32_e32 v98, 0xbfb8aa3b, v82
	v_exp_f32_e32 v144, v98
	v_mul_f32_e32 v98, 0xbfb8aa3b, v83
	v_exp_f32_e32 v145, v98
	s_nop 0
	v_pk_add_f32 v[144:145], v[144:145], 1.0 op_sel_hi:[1,0]
	s_nop 0
	v_div_scale_f32 v98, s[30:31], v145, v145, v83
	v_rcp_f32_e32 v105, v98
	v_div_scale_f32 v107, vcc, v83, v145, v83
	v_fma_f32 v147, -v98, v105, 1.0
	v_fmac_f32_e32 v105, v147, v105
	v_mul_f32_e32 v147, v107, v105
	v_fma_f32 v149, -v98, v147, v107
	v_fmac_f32_e32 v147, v149, v105
	v_fma_f32 v98, -v98, v147, v107
	v_div_scale_f32 v107, s[30:31], v144, v144, v82
	v_rcp_f32_e32 v149, v107
	v_div_fmas_f32 v98, v98, v105, v147
	v_mul_f32_e32 v147, 0xbfb8aa3b, v84
	v_exp_f32_e32 v152, v147
	v_mul_f32_e32 v147, 0xbfb8aa3b, v85
	v_fma_f32 v105, -v107, v149, 1.0
	v_exp_f32_e32 v153, v147
	v_fmac_f32_e32 v149, v105, v149
	v_div_scale_f32 v105, vcc, v82, v144, v82
	v_div_fixup_f32 v98, v98, v145, v83
	v_mul_f32_e32 v145, v105, v149
	v_fma_f32 v147, -v107, v145, v105
	v_fmac_f32_e32 v145, v147, v149
	v_pk_add_f32 v[152:153], v[152:153], 1.0 op_sel_hi:[1,0]
	v_fma_f32 v105, -v107, v145, v105
	v_div_scale_f32 v107, s[30:31], v153, v153, v85
	v_rcp_f32_e32 v147, v107
	v_div_fmas_f32 v105, v105, v149, v145
	v_div_fixup_f32 v105, v105, v144, v82
	v_cvt_pk_bf16_f32 v144, v105, v98
	v_fma_f32 v98, -v107, v147, 1.0
	v_fmac_f32_e32 v147, v98, v147
	v_div_scale_f32 v98, vcc, v85, v153, v85
	v_mul_f32_e32 v105, v98, v147
	v_fma_f32 v145, -v107, v105, v98
	v_fmac_f32_e32 v105, v145, v147
	v_fma_f32 v98, -v107, v105, v98
	v_div_scale_f32 v107, s[30:31], v152, v152, v84
	v_rcp_f32_e32 v145, v107
	v_div_fmas_f32 v98, v98, v147, v105
	v_div_fixup_f32 v98, v98, v153, v85
	v_fma_f32 v105, -v107, v145, 1.0
	v_fmac_f32_e32 v145, v105, v145
	v_div_scale_f32 v105, vcc, v84, v152, v84
	v_mul_f32_e32 v147, v105, v145
	v_fma_f32 v149, -v107, v147, v105
	v_fmac_f32_e32 v147, v149, v145
	v_fma_f32 v105, -v107, v147, v105
	v_div_fmas_f32 v105, v105, v145, v147
	v_div_fixup_f32 v105, v105, v152, v84
	v_cvt_pk_bf16_f32 v145, v105, v98
	v_mov_b32_e32 v105, v99
	v_lshl_add_u64 v[152:153], v[104:105], 1, v[108:109]
	global_store_dwordx2 v[152:153], v[144:145], off offset:-2048

.LBB0_2331:
	s_ashr_i32 s10, s2, 31
	s_lshr_b32 s10, s10, 26
	s_add_i32 s10, s2, s10
	s_ashr_i32 s30, s10, 6
	s_and_b32 s10, s10, 0x3ffffc0
	s_sub_i32 s28, s2, s10
	s_mulk_i32 s28, 0xc0
	v_add_u32_e32 v2, s28, v108
	s_lshr_b32 s10, s28, 6
	s_lshl_b32 s29, s30, 7
	v_ashrrev_i32_e32 v3, 31, v2
	s_add_i32 s10, s10, s30
	v_lshlrev_b64 v[2:3], 11, v[2:3]
	v_or_b32_e32 v4, s29, v108
	s_lshl_b32 s30, s10, 6
	s_lshl_b32 s10, s10, 7
	v_ashrrev_i32_e32 v5, 31, v4
	v_lshl_add_u64 v[104:105], v[100:101], 0, v[2:3]
	s_and_b32 s10, s10, 0x780
	v_readfirstlane_b32 s31, v109
	v_lshlrev_b64 v[4:5], 11, v[4:5]
	v_lshl_add_u64 v[2:3], v[104:105], 0, s[10:11]
	s_mov_b32 m0, s31
	v_readfirstlane_b32 s31, v127
	v_lshl_add_u64 v[106:107], v[102:103], 0, v[4:5]
	s_getreg_b32 s83, hwreg(HW_REG_HW_ID, 0, 4)
	s_bitcmp1_b32 s83, 0
	s_cbranch_scc0 .Lgm_ph20_noprio
	s_setprio 1
.Lgm_ph20_noprio:
	s_waitcnt vmcnt(0)
	s_barrier
	s_load_dwordx2 s[66:67], s[0:1], 0x118
	s_load_dwordx2 s[68:69], s[0:1], 0xd0
	v_and_b32_e32 v201, 0x3ff, v0
	v_readfirstlane_b32 s80, v0
	v_and_b32_e32 v200, 31, v201
	v_bfe_u32 v214, v201, 1, 3
	v_bfe_u32 v213, v201, 5, 1
	v_xor_b32_e32 v214, v214, v213
	v_lshlrev_b32_e32 v214, 4, v214
	s_and_b32 s80, s80, 0x3ff
	s_lshr_b32 s83, s80, 6
	s_lshl_b32 s80, s80, 4
	s_lshr_b32 s84, s83, 1
	s_and_b32 s83, s83, 1
	s_mul_i32 s84, s84, 0x3000
	s_lshl_b32 s83, s83, 13
	s_add_u32 s83, s83, 0xc000
	v_lshlrev_b32_e32 v200, 7, v200
	v_or_b32_e32 v200, v200, v214
	v_add_u32_e32 v215, s84, v200
	v_add_u32_e32 v211, s83, v200
	v_xor_b32_e32 v214, 0x20, v215
	v_xor_b32_e32 v210, 0x20, v211
	v_xor_b32_e32 v213, 0x40, v215
	v_xor_b32_e32 v209, 0x40, v211
	v_xor_b32_e32 v212, 0x60, v215
	v_xor_b32_e32 v208, 0x60, v211
	v_bfe_u32 v200, v201, 4, 3
	v_and_b32_e32 v206, 7, v201
	v_xor_b32_e32 v200, v200, v206
	v_lshlrev_b32_e32 v200, 4, v200
	v_lshrrev_b32_e32 v206, 3, v201
	v_lshl_or_b32 v207, v206, 11, v200
	v_add_u32_e32 v206, 0x10000, v207
	v_add_u32_e32 v205, 0x20000, v207
	v_add_u32_e32 v204, 0x30000, v207
	v_add_u32_e32 v203, 0x40000, v207
	v_add_u32_e32 v202, 0x50000, v207
	s_lshr_b32 s83, s2, 6
	s_and_b32 s84, s2, 63
	s_mov_b32 s79, 0
	s_mul_i32 s84, s84, 0x60000
	s_lshl_b32 s83, s83, 18
	s_add_u32 s83, s83, 0x200000
	s_waitcnt lgkmcnt(0)
	s_add_u32 s66, s66, s84
	s_addc_u32 s67, s67, 0
	s_add_u32 s68, s68, s83
	s_addc_u32 s69, s69, 0
	s_add_u32 s83, s79, 0
	s_and_b32 s83, s83, 15
	s_lshl_b32 s83, s83, 7
	s_add_u32 s70, s66, s83
	s_addc_u32 s71, s67, 0
	s_add_u32 s72, s68, s83
	s_addc_u32 s73, s69, 0
	s_add_u32 s81, s80, 0x0
	s_add_u32 s82, s80, 0xc000
	s_add_u32 m0, s81, 0x0
	s_nop 0
	global_load_lds_dwordx4 v207, s[70:71]
	s_add_u32 m0, s81, 0x1000
	s_nop 0
	global_load_lds_dwordx4 v206, s[70:71]
	s_add_u32 m0, s81, 0x2000
	s_nop 0
	global_load_lds_dwordx4 v205, s[70:71]
	s_add_u32 m0, s81, 0x3000
	s_nop 0
	global_load_lds_dwordx4 v204, s[70:71]
	s_add_u32 m0, s81, 0x4000
	s_nop 0
	global_load_lds_dwordx4 v203, s[70:71]
	s_add_u32 m0, s81, 0x5000
	s_nop 0
	global_load_lds_dwordx4 v202, s[70:71]
	s_add_u32 m0, s82, 0x0
	s_nop 0
	global_load_lds_dwordx4 v207, s[72:73]
	s_add_u32 m0, s82, 0x1000
	s_nop 0
	global_load_lds_dwordx4 v206, s[72:73]
	s_add_u32 m0, s82, 0x2000
	s_nop 0
	global_load_lds_dwordx4 v205, s[72:73]
	s_add_u32 m0, s82, 0x3000
	s_nop 0
	global_load_lds_dwordx4 v204, s[72:73]
	s_add_u32 s83, s79, 1
	s_and_b32 s83, s83, 15
	s_lshl_b32 s83, s83, 7
	s_add_u32 s70, s66, s83
	s_addc_u32 s71, s67, 0
	s_add_u32 s72, s68, s83
	s_addc_u32 s73, s69, 0
	s_add_u32 s81, s80, 0x6000
	s_add_u32 s82, s80, 0x10000
	s_add_u32 m0, s81, 0x0
	s_nop 0
	global_load_lds_dwordx4 v207, s[70:71]
	s_add_u32 m0, s81, 0x1000
	s_nop 0
	global_load_lds_dwordx4 v206, s[70:71]
	s_add_u32 m0, s81, 0x2000
	s_nop 0
	global_load_lds_dwordx4 v205, s[70:71]
	s_add_u32 m0, s81, 0x3000
	s_nop 0
	global_load_lds_dwordx4 v204, s[70:71]
	s_add_u32 m0, s81, 0x4000
	s_nop 0
	global_load_lds_dwordx4 v203, s[70:71]
	v_mov_b32_e32 v2, 0
	v_mov_b32_e32 v3, 0
	v_mov_b32_e32 v4, 0
	v_mov_b32_e32 v5, 0
	v_mov_b32_e32 v6, 0
	v_mov_b32_e32 v7, 0
	v_mov_b32_e32 v8, 0
	v_mov_b32_e32 v9, 0
	v_mov_b32_e32 v10, 0
	v_mov_b32_e32 v11, 0
	v_mov_b32_e32 v12, 0
	v_mov_b32_e32 v13, 0
	v_mov_b32_e32 v14, 0
	v_mov_b32_e32 v15, 0
	v_mov_b32_e32 v16, 0
	v_mov_b32_e32 v17, 0
	v_mov_b32_e32 v18, 0
	v_mov_b32_e32 v19, 0
	v_mov_b32_e32 v20, 0
	v_mov_b32_e32 v21, 0
	v_mov_b32_e32 v22, 0
	v_mov_b32_e32 v23, 0
	v_mov_b32_e32 v24, 0
	v_mov_b32_e32 v25, 0
	v_mov_b32_e32 v26, 0
	v_mov_b32_e32 v27, 0
	v_mov_b32_e32 v28, 0
	v_mov_b32_e32 v29, 0
	v_mov_b32_e32 v30, 0
	v_mov_b32_e32 v31, 0
	v_mov_b32_e32 v32, 0
	v_mov_b32_e32 v33, 0
	v_mov_b32_e32 v34, 0
	v_mov_b32_e32 v35, 0
	v_mov_b32_e32 v36, 0
	v_mov_b32_e32 v37, 0
	v_mov_b32_e32 v38, 0
	v_mov_b32_e32 v39, 0
	v_mov_b32_e32 v40, 0
	v_mov_b32_e32 v41, 0
	v_mov_b32_e32 v42, 0
	v_mov_b32_e32 v43, 0
	v_mov_b32_e32 v44, 0
	v_mov_b32_e32 v45, 0
	v_mov_b32_e32 v46, 0
	v_mov_b32_e32 v47, 0
	v_mov_b32_e32 v48, 0
	v_mov_b32_e32 v49, 0
	v_mov_b32_e32 v50, 0
	v_mov_b32_e32 v51, 0
	v_mov_b32_e32 v52, 0
	v_mov_b32_e32 v53, 0
	v_mov_b32_e32 v54, 0
	v_mov_b32_e32 v55, 0
	v_mov_b32_e32 v56, 0
	v_mov_b32_e32 v57, 0
	v_mov_b32_e32 v58, 0
	v_mov_b32_e32 v59, 0
	v_mov_b32_e32 v60, 0
	v_mov_b32_e32 v61, 0
	v_mov_b32_e32 v62, 0
	v_mov_b32_e32 v63, 0
	v_mov_b32_e32 v64, 0
	v_mov_b32_e32 v65, 0
	v_mov_b32_e32 v66, 0
	v_mov_b32_e32 v67, 0
	v_mov_b32_e32 v68, 0
	v_mov_b32_e32 v69, 0
	v_mov_b32_e32 v70, 0
	v_mov_b32_e32 v71, 0
	v_mov_b32_e32 v72, 0
	v_mov_b32_e32 v73, 0
	v_mov_b32_e32 v74, 0
	v_mov_b32_e32 v75, 0
	v_mov_b32_e32 v76, 0
	v_mov_b32_e32 v77, 0
	v_mov_b32_e32 v78, 0
	v_mov_b32_e32 v79, 0
	v_mov_b32_e32 v80, 0
	v_mov_b32_e32 v81, 0
	v_mov_b32_e32 v82, 0
	v_mov_b32_e32 v83, 0
	v_mov_b32_e32 v84, 0
	v_mov_b32_e32 v85, 0
	v_mov_b32_e32 v86, 0
	v_mov_b32_e32 v87, 0
	v_mov_b32_e32 v88, 0
	v_mov_b32_e32 v89, 0
	v_mov_b32_e32 v90, 0
	v_mov_b32_e32 v91, 0
	v_mov_b32_e32 v92, 0
	v_mov_b32_e32 v93, 0
	v_mov_b32_e32 v94, 0
	v_mov_b32_e32 v95, 0
	v_mov_b32_e32 v96, 0
	v_mov_b32_e32 v97, 0
	s_waitcnt vmcnt(5)
	s_barrier
	ds_read_b128 v[240:243], v211 offset:0
	ds_read_b128 v[252:255], v215 offset:0
	ds_read_b128 v[236:239], v211 offset:4096
	ds_read_b128 v[248:251], v215 offset:4096
	ds_read_b128 v[244:247], v215 offset:8192
	s_mov_b32 s78, 0
.Lgm_ph20_loop:
	s_waitcnt lgkmcnt(1)
	v_mfma_f32_32x32x16_bf16 v[82:97], v[240:243], v[252:255], v[82:97]
	ds_read_b128 v[220:223], v210 offset:0
	s_add_u32 m0, s81, 0x5000
	s_nop 0
	global_load_lds_dwordx4 v202, s[70:71]
	v_mfma_f32_32x32x16_bf16 v[66:81], v[236:239], v[252:255], v[66:81]
	ds_read_b128 v[232:235], v214 offset:0
	s_add_u32 m0, s82, 0x0
	s_nop 0
	global_load_lds_dwordx4 v207, s[72:73]
	v_mfma_f32_32x32x16_bf16 v[50:65], v[240:243], v[248:251], v[50:65]
	ds_read_b128 v[216:219], v210 offset:4096
	s_add_u32 m0, s82, 0x1000
	s_nop 0
	global_load_lds_dwordx4 v206, s[72:73]
	v_mfma_f32_32x32x16_bf16 v[34:49], v[236:239], v[248:251], v[34:49]
	ds_read_b128 v[228:231], v214 offset:4096
	s_add_u32 m0, s82, 0x2000
	s_nop 0
	global_load_lds_dwordx4 v205, s[72:73]
	s_waitcnt lgkmcnt(4)
	v_mfma_f32_32x32x16_bf16 v[18:33], v[240:243], v[244:247], v[18:33]
	ds_read_b128 v[224:227], v214 offset:8192
	v_mfma_f32_32x32x16_bf16 v[2:17], v[236:239], v[244:247], v[2:17]
	s_add_u32 m0, s82, 0x3000
	s_nop 0
	global_load_lds_dwordx4 v204, s[72:73]
	s_waitcnt lgkmcnt(1)
	v_mfma_f32_32x32x16_bf16 v[82:97], v[220:223], v[232:235], v[82:97]
	ds_read_b128 v[240:243], v209 offset:0
	v_mfma_f32_32x32x16_bf16 v[66:81], v[216:219], v[232:235], v[66:81]
	ds_read_b128 v[252:255], v213 offset:0
	v_mfma_f32_32x32x16_bf16 v[50:65], v[220:223], v[228:231], v[50:65]
	ds_read_b128 v[236:239], v209 offset:4096
	v_mfma_f32_32x32x16_bf16 v[34:49], v[216:219], v[228:231], v[34:49]
	ds_read_b128 v[248:251], v213 offset:4096
	s_waitcnt lgkmcnt(4)
	v_mfma_f32_32x32x16_bf16 v[18:33], v[220:223], v[224:227], v[18:33]
	ds_read_b128 v[244:247], v213 offset:8192
	v_mfma_f32_32x32x16_bf16 v[2:17], v[216:219], v[224:227], v[2:17]
	s_waitcnt lgkmcnt(1)
	v_mfma_f32_32x32x16_bf16 v[82:97], v[240:243], v[252:255], v[82:97]
	ds_read_b128 v[220:223], v208 offset:0
	s_add_u32 s83, s79, s78
	s_add_u32 s83, s83, 2
	s_and_b32 s83, s83, 15
	v_mfma_f32_32x32x16_bf16 v[66:81], v[236:239], v[252:255], v[66:81]
	ds_read_b128 v[232:235], v212 offset:0
	s_lshl_b32 s83, s83, 7
	s_add_u32 s70, s66, s83
	v_mfma_f32_32x32x16_bf16 v[50:65], v[240:243], v[248:251], v[50:65]
	ds_read_b128 v[216:219], v208 offset:4096
	s_addc_u32 s71, s67, 0
	s_add_u32 s72, s68, s83
	v_mfma_f32_32x32x16_bf16 v[34:49], v[236:239], v[248:251], v[34:49]
	ds_read_b128 v[228:231], v212 offset:4096
	s_addc_u32 s73, s69, 0
	s_add_u32 s81, s80, 0x0
	s_add_u32 s82, s80, 0xc000
	s_waitcnt lgkmcnt(4)
	v_mfma_f32_32x32x16_bf16 v[18:33], v[240:243], v[244:247], v[18:33]
	ds_read_b128 v[224:227], v212 offset:8192
	v_mfma_f32_32x32x16_bf16 v[2:17], v[236:239], v[244:247], v[2:17]
	s_waitcnt vmcnt(0) lgkmcnt(0)
	s_barrier
	v_mfma_f32_32x32x16_bf16 v[82:97], v[220:223], v[232:235], v[82:97]
	s_add_u32 m0, s81, 0x0
	ds_read_b128 v[240:243], v211 offset:16384
	global_load_lds_dwordx4 v207, s[70:71]
	v_mfma_f32_32x32x16_bf16 v[66:81], v[216:219], v[232:235], v[66:81]
	s_add_u32 m0, s81, 0x1000
	ds_read_b128 v[252:255], v215 offset:24576
	global_load_lds_dwordx4 v206, s[70:71]
	v_mfma_f32_32x32x16_bf16 v[50:65], v[220:223], v[228:231], v[50:65]
	s_add_u32 m0, s81, 0x2000
	ds_read_b128 v[236:239], v211 offset:20480
	global_load_lds_dwordx4 v205, s[70:71]
	v_mfma_f32_32x32x16_bf16 v[34:49], v[216:219], v[228:231], v[34:49]
	s_add_u32 m0, s81, 0x3000
	ds_read_b128 v[248:251], v215 offset:28672
	global_load_lds_dwordx4 v204, s[70:71]
	v_mfma_f32_32x32x16_bf16 v[18:33], v[220:223], v[224:227], v[18:33]
	s_add_u32 m0, s81, 0x4000
	ds_read_b128 v[244:247], v215 offset:32768
	global_load_lds_dwordx4 v203, s[70:71]
	v_mfma_f32_32x32x16_bf16 v[2:17], v[216:219], v[224:227], v[2:17]
	s_waitcnt lgkmcnt(1)
	v_mfma_f32_32x32x16_bf16 v[82:97], v[240:243], v[252:255], v[82:97]
	ds_read_b128 v[220:223], v210 offset:16384
	s_add_u32 m0, s81, 0x5000
	s_nop 0
	global_load_lds_dwordx4 v202, s[70:71]
	v_mfma_f32_32x32x16_bf16 v[66:81], v[236:239], v[252:255], v[66:81]
	ds_read_b128 v[232:235], v214 offset:24576
	s_add_u32 m0, s82, 0x0
	s_nop 0
	global_load_lds_dwordx4 v207, s[72:73]
	v_mfma_f32_32x32x16_bf16 v[50:65], v[240:243], v[248:251], v[50:65]
	ds_read_b128 v[216:219], v210 offset:20480
	s_add_u32 m0, s82, 0x1000
	s_nop 0
	global_load_lds_dwordx4 v206, s[72:73]
	v_mfma_f32_32x32x16_bf16 v[34:49], v[236:239], v[248:251], v[34:49]
	ds_read_b128 v[228:231], v214 offset:28672
	s_add_u32 m0, s82, 0x2000
	s_nop 0
	global_load_lds_dwordx4 v205, s[72:73]
	s_waitcnt lgkmcnt(4)
	v_mfma_f32_32x32x16_bf16 v[18:33], v[240:243], v[244:247], v[18:33]
	ds_read_b128 v[224:227], v214 offset:32768
	v_mfma_f32_32x32x16_bf16 v[2:17], v[236:239], v[244:247], v[2:17]
	s_add_u32 m0, s82, 0x3000
	s_nop 0
	global_load_lds_dwordx4 v204, s[72:73]
	s_waitcnt lgkmcnt(1)
	v_mfma_f32_32x32x16_bf16 v[82:97], v[220:223], v[232:235], v[82:97]
	ds_read_b128 v[240:243], v209 offset:16384
	v_mfma_f32_32x32x16_bf16 v[66:81], v[216:219], v[232:235], v[66:81]
	ds_read_b128 v[252:255], v213 offset:24576
	v_mfma_f32_32x32x16_bf16 v[50:65], v[220:223], v[228:231], v[50:65]
	ds_read_b128 v[236:239], v209 offset:20480
	v_mfma_f32_32x32x16_bf16 v[34:49], v[216:219], v[228:231], v[34:49]
	ds_read_b128 v[248:251], v213 offset:28672
	s_waitcnt lgkmcnt(4)
	v_mfma_f32_32x32x16_bf16 v[18:33], v[220:223], v[224:227], v[18:33]
	ds_read_b128 v[244:247], v213 offset:32768
	v_mfma_f32_32x32x16_bf16 v[2:17], v[216:219], v[224:227], v[2:17]
	s_waitcnt lgkmcnt(1)
	v_mfma_f32_32x32x16_bf16 v[82:97], v[240:243], v[252:255], v[82:97]
	ds_read_b128 v[220:223], v208 offset:16384
	s_add_u32 s83, s79, s78
	s_add_u32 s83, s83, 3
	s_and_b32 s83, s83, 15
	v_mfma_f32_32x32x16_bf16 v[66:81], v[236:239], v[252:255], v[66:81]
	ds_read_b128 v[232:235], v212 offset:24576
	s_lshl_b32 s83, s83, 7
	s_add_u32 s70, s66, s83
	v_mfma_f32_32x32x16_bf16 v[50:65], v[240:243], v[248:251], v[50:65]
	ds_read_b128 v[216:219], v208 offset:20480
	s_addc_u32 s71, s67, 0
	s_add_u32 s72, s68, s83
	v_mfma_f32_32x32x16_bf16 v[34:49], v[236:239], v[248:251], v[34:49]
	ds_read_b128 v[228:231], v212 offset:28672
	s_addc_u32 s73, s69, 0
	s_add_u32 s81, s80, 0x6000
	s_add_u32 s82, s80, 0x10000
	s_waitcnt lgkmcnt(4)
	v_mfma_f32_32x32x16_bf16 v[18:33], v[240:243], v[244:247], v[18:33]
	ds_read_b128 v[224:227], v212 offset:32768
	v_mfma_f32_32x32x16_bf16 v[2:17], v[236:239], v[244:247], v[2:17]
	s_waitcnt vmcnt(0) lgkmcnt(0)
	s_barrier
	v_mfma_f32_32x32x16_bf16 v[82:97], v[220:223], v[232:235], v[82:97]
	s_add_u32 m0, s81, 0x0
	ds_read_b128 v[240:243], v211 offset:0
	global_load_lds_dwordx4 v207, s[70:71]
	v_mfma_f32_32x32x16_bf16 v[66:81], v[216:219], v[232:235], v[66:81]
	s_add_u32 m0, s81, 0x1000
	ds_read_b128 v[252:255], v215 offset:0
	global_load_lds_dwordx4 v206, s[70:71]
	v_mfma_f32_32x32x16_bf16 v[50:65], v[220:223], v[228:231], v[50:65]
	s_add_u32 m0, s81, 0x2000
	ds_read_b128 v[236:239], v211 offset:4096
	global_load_lds_dwordx4 v205, s[70:71]
	v_mfma_f32_32x32x16_bf16 v[34:49], v[216:219], v[228:231], v[34:49]
	s_add_u32 m0, s81, 0x3000
	ds_read_b128 v[248:251], v215 offset:4096
	global_load_lds_dwordx4 v204, s[70:71]
	v_mfma_f32_32x32x16_bf16 v[18:33], v[220:223], v[224:227], v[18:33]
	s_add_u32 m0, s81, 0x4000
	ds_read_b128 v[244:247], v215 offset:8192
	global_load_lds_dwordx4 v203, s[70:71]
	v_mfma_f32_32x32x16_bf16 v[2:17], v[216:219], v[224:227], v[2:17]
	s_add_u32 s78, s78, 2
	s_cmp_lt_u32 s78, 14
	s_cbranch_scc1 .Lgm_ph20_loop
	s_waitcnt lgkmcnt(1)
	v_mfma_f32_32x32x16_bf16 v[82:97], v[240:243], v[252:255], v[82:97]
	ds_read_b128 v[220:223], v210 offset:0
	s_add_u32 m0, s81, 0x5000
	s_nop 0
	global_load_lds_dwordx4 v202, s[70:71]
	v_mfma_f32_32x32x16_bf16 v[66:81], v[236:239], v[252:255], v[66:81]
	ds_read_b128 v[232:235], v214 offset:0
	s_add_u32 m0, s82, 0x0
	s_nop 0
	global_load_lds_dwordx4 v207, s[72:73]
	v_mfma_f32_32x32x16_bf16 v[50:65], v[240:243], v[248:251], v[50:65]
	ds_read_b128 v[216:219], v210 offset:4096
	s_add_u32 m0, s82, 0x1000
	s_nop 0
	global_load_lds_dwordx4 v206, s[72:73]
	v_mfma_f32_32x32x16_bf16 v[34:49], v[236:239], v[248:251], v[34:49]
	ds_read_b128 v[228:231], v214 offset:4096
	s_add_u32 m0, s82, 0x2000
	s_nop 0
	global_load_lds_dwordx4 v205, s[72:73]
	s_waitcnt lgkmcnt(4)
	v_mfma_f32_32x32x16_bf16 v[18:33], v[240:243], v[244:247], v[18:33]
	ds_read_b128 v[224:227], v214 offset:8192
	v_mfma_f32_32x32x16_bf16 v[2:17], v[236:239], v[244:247], v[2:17]
	s_add_u32 m0, s82, 0x3000
	s_nop 0
	global_load_lds_dwordx4 v204, s[72:73]
	s_waitcnt lgkmcnt(1)
	v_mfma_f32_32x32x16_bf16 v[82:97], v[220:223], v[232:235], v[82:97]
	ds_read_b128 v[240:243], v209 offset:0
	v_mfma_f32_32x32x16_bf16 v[66:81], v[216:219], v[232:235], v[66:81]
	ds_read_b128 v[252:255], v213 offset:0
	v_mfma_f32_32x32x16_bf16 v[50:65], v[220:223], v[228:231], v[50:65]
	ds_read_b128 v[236:239], v209 offset:4096
	v_mfma_f32_32x32x16_bf16 v[34:49], v[216:219], v[228:231], v[34:49]
	ds_read_b128 v[248:251], v213 offset:4096
	s_waitcnt lgkmcnt(4)
	v_mfma_f32_32x32x16_bf16 v[18:33], v[220:223], v[224:227], v[18:33]
	ds_read_b128 v[244:247], v213 offset:8192
	v_mfma_f32_32x32x16_bf16 v[2:17], v[216:219], v[224:227], v[2:17]
	s_waitcnt lgkmcnt(1)
	v_mfma_f32_32x32x16_bf16 v[82:97], v[240:243], v[252:255], v[82:97]
	ds_read_b128 v[220:223], v208 offset:0
	v_mfma_f32_32x32x16_bf16 v[66:81], v[236:239], v[252:255], v[66:81]
	ds_read_b128 v[232:235], v212 offset:0
	v_mfma_f32_32x32x16_bf16 v[50:65], v[240:243], v[248:251], v[50:65]
	ds_read_b128 v[216:219], v208 offset:4096
	v_mfma_f32_32x32x16_bf16 v[34:49], v[236:239], v[248:251], v[34:49]
	ds_read_b128 v[228:231], v212 offset:4096
	s_waitcnt lgkmcnt(4)
	v_mfma_f32_32x32x16_bf16 v[18:33], v[240:243], v[244:247], v[18:33]
	ds_read_b128 v[224:227], v212 offset:8192
	v_mfma_f32_32x32x16_bf16 v[2:17], v[236:239], v[244:247], v[2:17]
	s_waitcnt vmcnt(0) lgkmcnt(0)
	s_barrier
	v_mfma_f32_32x32x16_bf16 v[82:97], v[220:223], v[232:235], v[82:97]
	ds_read_b128 v[240:243], v211 offset:16384
	v_mfma_f32_32x32x16_bf16 v[66:81], v[216:219], v[232:235], v[66:81]
	ds_read_b128 v[252:255], v215 offset:24576
	v_mfma_f32_32x32x16_bf16 v[50:65], v[220:223], v[228:231], v[50:65]
	ds_read_b128 v[236:239], v211 offset:20480
	v_mfma_f32_32x32x16_bf16 v[34:49], v[216:219], v[228:231], v[34:49]
	ds_read_b128 v[248:251], v215 offset:28672
	v_mfma_f32_32x32x16_bf16 v[18:33], v[220:223], v[224:227], v[18:33]
	ds_read_b128 v[244:247], v215 offset:32768
	v_mfma_f32_32x32x16_bf16 v[2:17], v[216:219], v[224:227], v[2:17]
	s_waitcnt lgkmcnt(1)
	v_mfma_f32_32x32x16_bf16 v[82:97], v[240:243], v[252:255], v[82:97]
	ds_read_b128 v[220:223], v210 offset:16384
	v_mfma_f32_32x32x16_bf16 v[66:81], v[236:239], v[252:255], v[66:81]
	ds_read_b128 v[232:235], v214 offset:24576
	v_mfma_f32_32x32x16_bf16 v[50:65], v[240:243], v[248:251], v[50:65]
	ds_read_b128 v[216:219], v210 offset:20480
	v_mfma_f32_32x32x16_bf16 v[34:49], v[236:239], v[248:251], v[34:49]
	ds_read_b128 v[228:231], v214 offset:28672
	s_waitcnt lgkmcnt(4)
	v_mfma_f32_32x32x16_bf16 v[18:33], v[240:243], v[244:247], v[18:33]
	ds_read_b128 v[224:227], v214 offset:32768
	v_mfma_f32_32x32x16_bf16 v[2:17], v[236:239], v[244:247], v[2:17]
	s_waitcnt lgkmcnt(1)
	v_mfma_f32_32x32x16_bf16 v[82:97], v[220:223], v[232:235], v[82:97]
	ds_read_b128 v[240:243], v209 offset:16384
	v_mfma_f32_32x32x16_bf16 v[66:81], v[216:219], v[232:235], v[66:81]
	ds_read_b128 v[252:255], v213 offset:24576
	v_mfma_f32_32x32x16_bf16 v[50:65], v[220:223], v[228:231], v[50:65]
	ds_read_b128 v[236:239], v209 offset:20480
	v_mfma_f32_32x32x16_bf16 v[34:49], v[216:219], v[228:231], v[34:49]
	ds_read_b128 v[248:251], v213 offset:28672
	s_waitcnt lgkmcnt(4)
	v_mfma_f32_32x32x16_bf16 v[18:33], v[220:223], v[224:227], v[18:33]
	ds_read_b128 v[244:247], v213 offset:32768
	v_mfma_f32_32x32x16_bf16 v[2:17], v[216:219], v[224:227], v[2:17]
	s_waitcnt lgkmcnt(1)
	v_mfma_f32_32x32x16_bf16 v[82:97], v[240:243], v[252:255], v[82:97]
	ds_read_b128 v[220:223], v208 offset:16384
	v_mfma_f32_32x32x16_bf16 v[66:81], v[236:239], v[252:255], v[66:81]
	ds_read_b128 v[232:235], v212 offset:24576
	v_mfma_f32_32x32x16_bf16 v[50:65], v[240:243], v[248:251], v[50:65]
	ds_read_b128 v[216:219], v208 offset:20480
	v_mfma_f32_32x32x16_bf16 v[34:49], v[236:239], v[248:251], v[34:49]
	ds_read_b128 v[228:231], v212 offset:28672
	s_waitcnt lgkmcnt(4)
	v_mfma_f32_32x32x16_bf16 v[18:33], v[240:243], v[244:247], v[18:33]
	ds_read_b128 v[224:227], v212 offset:32768
	v_mfma_f32_32x32x16_bf16 v[2:17], v[236:239], v[244:247], v[2:17]
	s_waitcnt vmcnt(0) lgkmcnt(0)
	s_barrier
	v_mfma_f32_32x32x16_bf16 v[82:97], v[220:223], v[232:235], v[82:97]
	v_mfma_f32_32x32x16_bf16 v[66:81], v[216:219], v[232:235], v[66:81]
	v_mfma_f32_32x32x16_bf16 v[50:65], v[220:223], v[228:231], v[50:65]
	v_mfma_f32_32x32x16_bf16 v[34:49], v[216:219], v[228:231], v[34:49]
	v_mfma_f32_32x32x16_bf16 v[18:33], v[220:223], v[224:227], v[18:33]
	v_mfma_f32_32x32x16_bf16 v[2:17], v[216:219], v[224:227], v[2:17]
	s_nop 7
	s_nop 7
	s_setprio 0
	s_waitcnt lgkmcnt(0)
	s_nop 10
	ds_write_b128 v145, v[82:85]
	ds_write_b128 v145, v[86:89] offset:32
	ds_write_b128 v145, v[90:93] offset:64
	ds_write_b128 v145, v[94:97] offset:96
	ds_write_b128 v145, v[66:69] offset:128
	ds_write_b128 v145, v[70:73] offset:160
	ds_write_b128 v145, v[74:77] offset:192
	ds_write_b128 v145, v[78:81] offset:224
	s_waitcnt lgkmcnt(0)
	v_add_u32_e32 v104, s28, v111
	v_or_b32_e32 v244, s29, v119
	v_lshlrev_b32_e32 v242, 2, v244
	v_add_u32_e32 v242, s3, v242
	v_lshlrev_b32_e32 v243, 1, v244
	v_mov_b32_e32 v240, v104
	v_add_u32_e32 v241, 0xfffff000, v240
	v_lshrrev_b32_e32 v241, 11, v241
	v_mad_u32_u24 v241, v241, s26, s26
	v_lshlrev_b32_e32 v241, 2, v241
	v_or_b32_e32 v232, v240, v1
	v_or_b32_e32 v233, v240, v120
	v_or_b32_e32 v234, v240, v121
	v_or_b32_e32 v235, v240, v122
	v_or_b32_e32 v236, v240, v123
	v_or_b32_e32 v237, v240, v124
	v_or_b32_e32 v238, v240, v125
	v_or_b32_e32 v239, v240, v126
	v_cmp_lt_i32_e64 s[82:83], s27, v232
	v_cmp_lt_i32_e64 s[84:85], s27, v233
	v_cmp_lt_i32_e64 s[86:87], s27, v234
	v_cmp_lt_i32_e64 s[88:89], s27, v235
	v_cmp_lt_i32_e64 s[90:91], s27, v236
	v_cmp_lt_i32_e64 s[92:93], s27, v237
	v_cmp_lt_i32_e64 s[94:95], s27, v238
	v_cmp_lt_i32_e64 s[96:97], s27, v239
	s_waitcnt lgkmcnt(0)
	v_cndmask_b32_e64 v200, 0, v241, s[82:83]
	v_cndmask_b32_e64 v204, 0, v241, s[84:85]
	v_cndmask_b32_e64 v208, 0, v241, s[86:87]
	v_cndmask_b32_e64 v212, 0, v241, s[88:89]
	v_cndmask_b32_e64 v216, 0, v241, s[90:91]
	v_cndmask_b32_e64 v220, 0, v241, s[92:93]
	v_cndmask_b32_e64 v224, 0, v241, s[94:95]
	v_cndmask_b32_e64 v228, 0, v241, s[96:97]
	v_add_u32_e32 v200, v200, v242
	v_add_u32_e32 v204, v204, v242
	v_add_u32_e32 v208, v208, v242
	v_add_u32_e32 v212, v212, v242
	v_add_u32_e32 v216, v216, v242
	v_add_u32_e32 v220, v220, v242
	v_add_u32_e32 v224, v224, v242
	v_add_u32_e32 v228, v228, v242
	ds_read_b128 v[82:85], v147
	global_load_dwordx4 v[200:203], v200, s[6:7]
	ds_read_b128 v[86:89], v147 offset:1088
	global_load_dwordx4 v[204:207], v204, s[6:7]
	ds_read_b128 v[90:93], v147 offset:2176
	global_load_dwordx4 v[208:211], v208, s[6:7]
	ds_read_b128 v[94:97], v147 offset:3264
	global_load_dwordx4 v[212:215], v212, s[6:7]
	ds_read_b128 v[66:69], v147 offset:4352
	global_load_dwordx4 v[216:219], v216, s[6:7]
	ds_read_b128 v[70:73], v147 offset:5440
	global_load_dwordx4 v[220:223], v220, s[6:7]
	ds_read_b128 v[74:77], v147 offset:6528
	global_load_dwordx4 v[224:227], v224, s[6:7]
	ds_read_b128 v[78:81], v147 offset:7616
	global_load_dwordx4 v[228:231], v228, s[6:7]
	v_lshl_add_u32 v232, v232, 11, v243
	v_lshl_add_u32 v233, v233, 11, v243
	v_lshl_add_u32 v234, v234, 11, v243
	v_lshl_add_u32 v235, v235, 11, v243
	v_lshl_add_u32 v236, v236, 11, v243
	v_lshl_add_u32 v237, v237, 11, v243
	v_lshl_add_u32 v238, v238, 11, v243
	v_lshl_add_u32 v239, v239, 11, v243
	s_waitcnt vmcnt(7) lgkmcnt(7)
	v_mul_f32_e32 v82, v82, v200
	v_mul_f32_e32 v83, v83, v201
	v_mul_f32_e32 v84, v84, v202
	v_mul_f32_e32 v85, v85, v203
	v_cvt_pk_bf16_f32 v82, v82, v83
	v_cvt_pk_bf16_f32 v83, v84, v85
	global_store_dwordx2 v232, v[82:83], s[4:5] sc1
	s_waitcnt vmcnt(7) lgkmcnt(6)
	v_mul_f32_e32 v86, v86, v204
	v_mul_f32_e32 v87, v87, v205
	v_mul_f32_e32 v88, v88, v206
	v_mul_f32_e32 v89, v89, v207
	v_cvt_pk_bf16_f32 v86, v86, v87
	v_cvt_pk_bf16_f32 v87, v88, v89
	global_store_dwordx2 v233, v[86:87], s[4:5] sc1
	s_waitcnt vmcnt(7) lgkmcnt(5)
	v_mul_f32_e32 v90, v90, v208
	v_mul_f32_e32 v91, v91, v209
	v_mul_f32_e32 v92, v92, v210
	v_mul_f32_e32 v93, v93, v211
	v_cvt_pk_bf16_f32 v90, v90, v91
	v_cvt_pk_bf16_f32 v91, v92, v93
	global_store_dwordx2 v234, v[90:91], s[4:5] sc1
	s_waitcnt vmcnt(7) lgkmcnt(4)
	v_mul_f32_e32 v94, v94, v212
	v_mul_f32_e32 v95, v95, v213
	v_mul_f32_e32 v96, v96, v214
	v_mul_f32_e32 v97, v97, v215
	v_cvt_pk_bf16_f32 v94, v94, v95
	v_cvt_pk_bf16_f32 v95, v96, v97
	global_store_dwordx2 v235, v[94:95], s[4:5] sc1
	s_waitcnt vmcnt(7) lgkmcnt(3)
	v_mul_f32_e32 v66, v66, v216
	v_mul_f32_e32 v67, v67, v217
	v_mul_f32_e32 v68, v68, v218
	v_mul_f32_e32 v69, v69, v219
	v_cvt_pk_bf16_f32 v66, v66, v67
	v_cvt_pk_bf16_f32 v67, v68, v69
	global_store_dwordx2 v236, v[66:67], s[4:5] sc1
	s_waitcnt vmcnt(7) lgkmcnt(2)
	v_mul_f32_e32 v70, v70, v220
	v_mul_f32_e32 v71, v71, v221
	v_mul_f32_e32 v72, v72, v222
	v_mul_f32_e32 v73, v73, v223
	v_cvt_pk_bf16_f32 v70, v70, v71
	v_cvt_pk_bf16_f32 v71, v72, v73
	global_store_dwordx2 v237, v[70:71], s[4:5] sc1
	s_waitcnt vmcnt(7) lgkmcnt(1)
	v_mul_f32_e32 v74, v74, v224
	v_mul_f32_e32 v75, v75, v225
	v_mul_f32_e32 v76, v76, v226
	v_mul_f32_e32 v77, v77, v227
	v_cvt_pk_bf16_f32 v74, v74, v75
	v_cvt_pk_bf16_f32 v75, v76, v77
	global_store_dwordx2 v238, v[74:75], s[4:5] sc1
	s_waitcnt vmcnt(7) lgkmcnt(0)
	v_mul_f32_e32 v78, v78, v228
	v_mul_f32_e32 v79, v79, v229
	v_mul_f32_e32 v80, v80, v230
	v_mul_f32_e32 v81, v81, v231
	v_cvt_pk_bf16_f32 v78, v78, v79
	v_cvt_pk_bf16_f32 v79, v80, v81
	global_store_dwordx2 v239, v[78:79], s[4:5] sc1
	ds_write_b128 v145, v[50:53]
	ds_write_b128 v145, v[54:57] offset:32
	ds_write_b128 v145, v[58:61] offset:64
	ds_write_b128 v145, v[62:65] offset:96
	ds_write_b128 v145, v[34:37] offset:128
	ds_write_b128 v145, v[38:41] offset:160
	ds_write_b128 v145, v[42:45] offset:192
	ds_write_b128 v145, v[46:49] offset:224
	v_add_u32_e32 v240, 0x20, v104
	v_add_u32_e32 v241, 0xfffff000, v240
	v_lshrrev_b32_e32 v241, 11, v241
	v_mad_u32_u24 v241, v241, s26, s26
	v_lshlrev_b32_e32 v241, 2, v241
	v_or_b32_e32 v232, v240, v1
	v_or_b32_e32 v233, v240, v120
	v_or_b32_e32 v234, v240, v121
	v_or_b32_e32 v235, v240, v122
	v_or_b32_e32 v236, v240, v123
	v_or_b32_e32 v237, v240, v124
	v_or_b32_e32 v238, v240, v125
	v_or_b32_e32 v239, v240, v126
	v_cmp_lt_i32_e64 s[82:83], s27, v232
	v_cmp_lt_i32_e64 s[84:85], s27, v233
	v_cmp_lt_i32_e64 s[86:87], s27, v234
	v_cmp_lt_i32_e64 s[88:89], s27, v235
	v_cmp_lt_i32_e64 s[90:91], s27, v236
	v_cmp_lt_i32_e64 s[92:93], s27, v237
	v_cmp_lt_i32_e64 s[94:95], s27, v238
	v_cmp_lt_i32_e64 s[96:97], s27, v239
	s_waitcnt lgkmcnt(0)
	v_cndmask_b32_e64 v200, 0, v241, s[82:83]
	v_cndmask_b32_e64 v204, 0, v241, s[84:85]
	v_cndmask_b32_e64 v208, 0, v241, s[86:87]
	v_cndmask_b32_e64 v212, 0, v241, s[88:89]
	v_cndmask_b32_e64 v216, 0, v241, s[90:91]
	v_cndmask_b32_e64 v220, 0, v241, s[92:93]
	v_cndmask_b32_e64 v224, 0, v241, s[94:95]
	v_cndmask_b32_e64 v228, 0, v241, s[96:97]
	v_add_u32_e32 v200, v200, v242
	v_add_u32_e32 v204, v204, v242
	v_add_u32_e32 v208, v208, v242
	v_add_u32_e32 v212, v212, v242
	v_add_u32_e32 v216, v216, v242
	v_add_u32_e32 v220, v220, v242
	v_add_u32_e32 v224, v224, v242
	v_add_u32_e32 v228, v228, v242
	ds_read_b128 v[50:53], v147
	global_load_dwordx4 v[200:203], v200, s[6:7]
	ds_read_b128 v[54:57], v147 offset:1088
	global_load_dwordx4 v[204:207], v204, s[6:7]
	ds_read_b128 v[58:61], v147 offset:2176
	global_load_dwordx4 v[208:211], v208, s[6:7]
	ds_read_b128 v[62:65], v147 offset:3264
	global_load_dwordx4 v[212:215], v212, s[6:7]
	ds_read_b128 v[34:37], v147 offset:4352
	global_load_dwordx4 v[216:219], v216, s[6:7]
	ds_read_b128 v[38:41], v147 offset:5440
	global_load_dwordx4 v[220:223], v220, s[6:7]
	ds_read_b128 v[42:45], v147 offset:6528
	global_load_dwordx4 v[224:227], v224, s[6:7]
	ds_read_b128 v[46:49], v147 offset:7616
	global_load_dwordx4 v[228:231], v228, s[6:7]
	v_lshl_add_u32 v232, v232, 11, v243
	v_lshl_add_u32 v233, v233, 11, v243
	v_lshl_add_u32 v234, v234, 11, v243
	v_lshl_add_u32 v235, v235, 11, v243
	v_lshl_add_u32 v236, v236, 11, v243
	v_lshl_add_u32 v237, v237, 11, v243
	v_lshl_add_u32 v238, v238, 11, v243
	v_lshl_add_u32 v239, v239, 11, v243
	s_waitcnt vmcnt(7) lgkmcnt(7)
	v_mul_f32_e32 v50, v50, v200
	v_mul_f32_e32 v51, v51, v201
	v_mul_f32_e32 v52, v52, v202
	v_mul_f32_e32 v53, v53, v203
	v_cvt_pk_bf16_f32 v50, v50, v51
	v_cvt_pk_bf16_f32 v51, v52, v53
	global_store_dwordx2 v232, v[50:51], s[4:5] sc1
	s_waitcnt vmcnt(7) lgkmcnt(6)
	v_mul_f32_e32 v54, v54, v204
	v_mul_f32_e32 v55, v55, v205
	v_mul_f32_e32 v56, v56, v206
	v_mul_f32_e32 v57, v57, v207
	v_cvt_pk_bf16_f32 v54, v54, v55
	v_cvt_pk_bf16_f32 v55, v56, v57
	global_store_dwordx2 v233, v[54:55], s[4:5] sc1
	s_waitcnt vmcnt(7) lgkmcnt(5)
	v_mul_f32_e32 v58, v58, v208
	v_mul_f32_e32 v59, v59, v209
	v_mul_f32_e32 v60, v60, v210
	v_mul_f32_e32 v61, v61, v211
	v_cvt_pk_bf16_f32 v58, v58, v59
	v_cvt_pk_bf16_f32 v59, v60, v61
	global_store_dwordx2 v234, v[58:59], s[4:5] sc1
	s_waitcnt vmcnt(7) lgkmcnt(4)
	v_mul_f32_e32 v62, v62, v212
	v_mul_f32_e32 v63, v63, v213
	v_mul_f32_e32 v64, v64, v214
	v_mul_f32_e32 v65, v65, v215
	v_cvt_pk_bf16_f32 v62, v62, v63
	v_cvt_pk_bf16_f32 v63, v64, v65
	global_store_dwordx2 v235, v[62:63], s[4:5] sc1
	s_waitcnt vmcnt(7) lgkmcnt(3)
	v_mul_f32_e32 v34, v34, v216
	v_mul_f32_e32 v35, v35, v217
	v_mul_f32_e32 v36, v36, v218
	v_mul_f32_e32 v37, v37, v219
	v_cvt_pk_bf16_f32 v34, v34, v35
	v_cvt_pk_bf16_f32 v35, v36, v37
	global_store_dwordx2 v236, v[34:35], s[4:5] sc1
	s_waitcnt vmcnt(7) lgkmcnt(2)
	v_mul_f32_e32 v38, v38, v220
	v_mul_f32_e32 v39, v39, v221
	v_mul_f32_e32 v40, v40, v222
	v_mul_f32_e32 v41, v41, v223
	v_cvt_pk_bf16_f32 v38, v38, v39
	v_cvt_pk_bf16_f32 v39, v40, v41
	global_store_dwordx2 v237, v[38:39], s[4:5] sc1
	s_waitcnt vmcnt(7) lgkmcnt(1)
	v_mul_f32_e32 v42, v42, v224
	v_mul_f32_e32 v43, v43, v225
	v_mul_f32_e32 v44, v44, v226
	v_mul_f32_e32 v45, v45, v227
	v_cvt_pk_bf16_f32 v42, v42, v43
	v_cvt_pk_bf16_f32 v43, v44, v45
	global_store_dwordx2 v238, v[42:43], s[4:5] sc1
	s_waitcnt vmcnt(7) lgkmcnt(0)
	v_mul_f32_e32 v46, v46, v228
	v_mul_f32_e32 v47, v47, v229
	v_mul_f32_e32 v48, v48, v230
	v_mul_f32_e32 v49, v49, v231
	v_cvt_pk_bf16_f32 v46, v46, v47
	v_cvt_pk_bf16_f32 v47, v48, v49
	global_store_dwordx2 v239, v[46:47], s[4:5] sc1
	ds_write_b128 v145, v[18:21]
	ds_write_b128 v145, v[22:25] offset:32
	ds_write_b128 v145, v[26:29] offset:64
	ds_write_b128 v145, v[30:33] offset:96
	ds_write_b128 v145, v[2:5] offset:128
	ds_write_b128 v145, v[6:9] offset:160
	ds_write_b128 v145, v[10:13] offset:192
	ds_write_b128 v145, v[14:17] offset:224
	v_add_u32_e32 v240, 0x40, v104
	v_add_u32_e32 v241, 0xfffff000, v240
	v_lshrrev_b32_e32 v241, 11, v241
	v_mad_u32_u24 v241, v241, s26, s26
	v_lshlrev_b32_e32 v241, 2, v241
	v_or_b32_e32 v232, v240, v1
	v_or_b32_e32 v233, v240, v120
	v_or_b32_e32 v234, v240, v121
	v_or_b32_e32 v235, v240, v122
	v_or_b32_e32 v236, v240, v123
	v_or_b32_e32 v237, v240, v124
	v_or_b32_e32 v238, v240, v125
	v_or_b32_e32 v239, v240, v126
	v_cmp_lt_i32_e64 s[82:83], s27, v232
	v_cmp_lt_i32_e64 s[84:85], s27, v233
	v_cmp_lt_i32_e64 s[86:87], s27, v234
	v_cmp_lt_i32_e64 s[88:89], s27, v235
	v_cmp_lt_i32_e64 s[90:91], s27, v236
	v_cmp_lt_i32_e64 s[92:93], s27, v237
	v_cmp_lt_i32_e64 s[94:95], s27, v238
	v_cmp_lt_i32_e64 s[96:97], s27, v239
	s_waitcnt lgkmcnt(0)
	v_cndmask_b32_e64 v200, 0, v241, s[82:83]
	v_cndmask_b32_e64 v204, 0, v241, s[84:85]
	v_cndmask_b32_e64 v208, 0, v241, s[86:87]
	v_cndmask_b32_e64 v212, 0, v241, s[88:89]
	v_cndmask_b32_e64 v216, 0, v241, s[90:91]
	v_cndmask_b32_e64 v220, 0, v241, s[92:93]
	v_cndmask_b32_e64 v224, 0, v241, s[94:95]
	v_cndmask_b32_e64 v228, 0, v241, s[96:97]
	v_add_u32_e32 v200, v200, v242
	v_add_u32_e32 v204, v204, v242
	v_add_u32_e32 v208, v208, v242
	v_add_u32_e32 v212, v212, v242
	v_add_u32_e32 v216, v216, v242
	v_add_u32_e32 v220, v220, v242
	v_add_u32_e32 v224, v224, v242
	v_add_u32_e32 v228, v228, v242
	ds_read_b128 v[18:21], v147
	global_load_dwordx4 v[200:203], v200, s[6:7]
	ds_read_b128 v[22:25], v147 offset:1088
	global_load_dwordx4 v[204:207], v204, s[6:7]
	ds_read_b128 v[26:29], v147 offset:2176
	global_load_dwordx4 v[208:211], v208, s[6:7]
	ds_read_b128 v[30:33], v147 offset:3264
	global_load_dwordx4 v[212:215], v212, s[6:7]
	ds_read_b128 v[2:5], v147 offset:4352
	global_load_dwordx4 v[216:219], v216, s[6:7]
	ds_read_b128 v[6:9], v147 offset:5440
	global_load_dwordx4 v[220:223], v220, s[6:7]
	ds_read_b128 v[10:13], v147 offset:6528
	global_load_dwordx4 v[224:227], v224, s[6:7]
	ds_read_b128 v[14:17], v147 offset:7616
	global_load_dwordx4 v[228:231], v228, s[6:7]
	v_lshl_add_u32 v232, v232, 11, v243
	v_lshl_add_u32 v233, v233, 11, v243
	v_lshl_add_u32 v234, v234, 11, v243
	v_lshl_add_u32 v235, v235, 11, v243
	v_lshl_add_u32 v236, v236, 11, v243
	v_lshl_add_u32 v237, v237, 11, v243
	v_lshl_add_u32 v238, v238, 11, v243
	v_lshl_add_u32 v239, v239, 11, v243
	s_waitcnt vmcnt(7) lgkmcnt(7)
	v_mul_f32_e32 v18, v18, v200
	v_mul_f32_e32 v19, v19, v201
	v_mul_f32_e32 v20, v20, v202
	v_mul_f32_e32 v21, v21, v203
	v_cvt_pk_bf16_f32 v18, v18, v19
	v_cvt_pk_bf16_f32 v19, v20, v21
	global_store_dwordx2 v232, v[18:19], s[4:5] sc1
	s_waitcnt vmcnt(7) lgkmcnt(6)
	v_mul_f32_e32 v22, v22, v204
	v_mul_f32_e32 v23, v23, v205
	v_mul_f32_e32 v24, v24, v206
	v_mul_f32_e32 v25, v25, v207
	v_cvt_pk_bf16_f32 v22, v22, v23
	v_cvt_pk_bf16_f32 v23, v24, v25
	global_store_dwordx2 v233, v[22:23], s[4:5] sc1
	s_waitcnt vmcnt(7) lgkmcnt(5)
	v_mul_f32_e32 v26, v26, v208
	v_mul_f32_e32 v27, v27, v209
	v_mul_f32_e32 v28, v28, v210
	v_mul_f32_e32 v29, v29, v211
	v_cvt_pk_bf16_f32 v26, v26, v27
	v_cvt_pk_bf16_f32 v27, v28, v29
	global_store_dwordx2 v234, v[26:27], s[4:5] sc1
	s_waitcnt vmcnt(7) lgkmcnt(4)
	v_mul_f32_e32 v30, v30, v212
	v_mul_f32_e32 v31, v31, v213
	v_mul_f32_e32 v32, v32, v214
	v_mul_f32_e32 v33, v33, v215
	v_cvt_pk_bf16_f32 v30, v30, v31
	v_cvt_pk_bf16_f32 v31, v32, v33
	global_store_dwordx2 v235, v[30:31], s[4:5] sc1
	s_waitcnt vmcnt(7) lgkmcnt(3)
	v_mul_f32_e32 v2, v2, v216
	v_mul_f32_e32 v3, v3, v217
	v_mul_f32_e32 v4, v4, v218
	v_mul_f32_e32 v5, v5, v219
	v_cvt_pk_bf16_f32 v2, v2, v3
	v_cvt_pk_bf16_f32 v3, v4, v5
	global_store_dwordx2 v236, v[2:3], s[4:5] sc1
	s_waitcnt vmcnt(7) lgkmcnt(2)
	v_mul_f32_e32 v6, v6, v220
	v_mul_f32_e32 v7, v7, v221
	v_mul_f32_e32 v8, v8, v222
	v_mul_f32_e32 v9, v9, v223
	v_cvt_pk_bf16_f32 v6, v6, v7
	v_cvt_pk_bf16_f32 v7, v8, v9
	global_store_dwordx2 v237, v[6:7], s[4:5] sc1
	s_waitcnt vmcnt(7) lgkmcnt(1)
	v_mul_f32_e32 v10, v10, v224
	v_mul_f32_e32 v11, v11, v225
	v_mul_f32_e32 v12, v12, v226
	v_mul_f32_e32 v13, v13, v227
	v_cvt_pk_bf16_f32 v10, v10, v11
	v_cvt_pk_bf16_f32 v11, v12, v13
	global_store_dwordx2 v238, v[10:11], s[4:5] sc1
	s_waitcnt vmcnt(7) lgkmcnt(0)
	v_mul_f32_e32 v14, v14, v228
	v_mul_f32_e32 v15, v15, v229
	v_mul_f32_e32 v16, v16, v230
	v_mul_f32_e32 v17, v17, v231
	v_cvt_pk_bf16_f32 v14, v14, v15
	v_cvt_pk_bf16_f32 v15, v16, v17
	global_store_dwordx2 v239, v[14:15], s[4:5] sc1
	s_waitcnt lgkmcnt(0)
	s_load_dword s10, s[8:9], 0x0
	s_waitcnt lgkmcnt(0)
	s_add_i32 s2, s10, s2
	s_cmpk_lt_i32 s2, 0x200
	s_cbranch_scc1 .LBB0_2331
